# remove s_setprio toggles around MFMA blocks in all GEMM loops
# baseline (speedup 1.0000x reference)
.LBB0_174:
	s_ashr_i32 s31, s30, 31
	s_lshl_b64 s[34:35], s[30:31], 19
	s_add_u32 s34, s48, s34
	s_addc_u32 s35, s49, s35
	s_ashr_i32 s29, s28, 31
	s_lshl_b64 s[36:37], s[28:29], 19
	s_add_u32 s36, s51, s36
	s_mov_b32 s44, 0
	s_addc_u32 s37, s52, s37
	s_ashr_i32 s45, s44, 31
	s_lshl_b64 s[76:77], s[44:45], 7
	s_add_u32 s78, s76, 0x100
	s_addc_u32 s79, s77, 0
	s_add_u32 s44, s42, s78
	ds_read_b128 v[0:3], v141
	ds_read_b128 v[4:7], v141 offset:1024
	ds_read_b128 v[8:11], v141 offset:2048
	ds_read_b128 v[12:15], v141 offset:3072
	ds_read_b128 v[16:19], v142
	ds_read_b128 v[20:23], v142 offset:1024
	ds_read_b128 v[24:27], v142 offset:2048
	ds_read_b128 v[28:31], v142 offset:3072
	s_addc_u32 s45, s43, s79
	s_and_b64 s[74:75], s[4:5], exec
	s_cselect_b32 s31, s37, s41
	s_cselect_b32 s74, s36, s40
	s_add_u32 s78, s40, s78
	s_addc_u32 s79, s41, s79
	s_add_u32 s76, s42, s76
	s_mov_b32 s29, 0
	s_addc_u32 s77, s43, s77
	v_lshl_add_u64 v[64:65], s[76:77], 0, v[130:131]
	s_mov_b32 m0, s66
	v_lshl_add_u64 v[66:67], v[64:65], 0, s[22:23]
	ds_read_b128 v[32:35], v143
	ds_read_b128 v[36:39], v143 offset:1024
	ds_read_b128 v[40:43], v143 offset:2048
	ds_read_b128 v[44:47], v143 offset:3072
	ds_read_b128 v[48:51], v143 offset:4096
	ds_read_b128 v[52:55], v143 offset:5120
	ds_read_b128 v[56:59], v143 offset:6144
	ds_read_b128 v[60:63], v143 offset:7168
	global_load_lds_dwordx4 v[66:67], off
	v_lshl_add_u64 v[64:65], v[64:65], 0, s[24:25]
	s_mov_b32 m0, s67
	s_and_b64 s[76:77], s[4:5], exec
	global_load_lds_dwordx4 v[64:65], off
	s_waitcnt vmcnt(16)
	s_waitcnt lgkmcnt(0)
	s_cselect_b32 s75, s35, s43
	s_cselect_b32 s76, s34, s42
	s_barrier
	s_waitcnt lgkmcnt(0)
	v_mfma_f32_16x16x32_bf16 v[64:67], v[0:3], v[32:35], 0
	v_mfma_f32_16x16x32_bf16 v[68:71], v[8:11], v[32:35], 0
	v_mfma_f32_16x16x32_bf16 v[72:75], v[0:3], v[40:43], 0
	v_mfma_f32_16x16x32_bf16 v[76:79], v[8:11], v[40:43], 0
	v_mfma_f32_16x16x32_bf16 v[80:83], v[0:3], v[48:51], 0
	v_mfma_f32_16x16x32_bf16 v[84:87], v[8:11], v[48:51], 0
	v_mfma_f32_16x16x32_bf16 v[88:91], v[0:3], v[56:59], 0
	v_mfma_f32_16x16x32_bf16 v[92:95], v[8:11], v[56:59], 0
	v_mfma_f32_16x16x32_bf16 v[64:67], v[4:7], v[36:39], v[64:67]
	v_mfma_f32_16x16x32_bf16 v[68:71], v[12:15], v[36:39], v[68:71]
	v_mfma_f32_16x16x32_bf16 v[72:75], v[4:7], v[44:47], v[72:75]
	v_mfma_f32_16x16x32_bf16 v[76:79], v[12:15], v[44:47], v[76:79]
	v_mfma_f32_16x16x32_bf16 v[80:83], v[4:7], v[52:55], v[80:83]
	v_mfma_f32_16x16x32_bf16 v[84:87], v[12:15], v[52:55], v[84:87]
	v_mfma_f32_16x16x32_bf16 v[88:91], v[4:7], v[60:63], v[88:91]
	v_mfma_f32_16x16x32_bf16 v[100:103], v[12:15], v[60:63], v[92:95]
	v_mfma_f32_16x16x32_bf16 v[92:95], v[16:19], v[32:35], 0
	v_mfma_f32_16x16x32_bf16 v[32:35], v[24:27], v[32:35], 0
	v_mfma_f32_16x16x32_bf16 v[104:107], v[20:23], v[36:39], v[92:95]
	v_mfma_f32_16x16x32_bf16 v[32:35], v[28:31], v[36:39], v[32:35]
	v_mfma_f32_16x16x32_bf16 v[36:39], v[16:19], v[40:43], 0
	v_mfma_f32_16x16x32_bf16 v[40:43], v[24:27], v[40:43], 0
	v_mfma_f32_16x16x32_bf16 v[36:39], v[20:23], v[44:47], v[36:39]
	v_mfma_f32_16x16x32_bf16 v[40:43], v[28:31], v[44:47], v[40:43]
	v_mfma_f32_16x16x32_bf16 v[44:47], v[16:19], v[48:51], 0
	v_mfma_f32_16x16x32_bf16 v[48:51], v[24:27], v[48:51], 0
	v_mfma_f32_16x16x32_bf16 v[44:47], v[20:23], v[52:55], v[44:47]
	v_mfma_f32_16x16x32_bf16 v[48:51], v[28:31], v[52:55], v[48:51]
	v_mfma_f32_16x16x32_bf16 v[52:55], v[16:19], v[56:59], 0
	v_mfma_f32_16x16x32_bf16 v[56:59], v[24:27], v[56:59], 0
	v_mfma_f32_16x16x32_bf16 v[52:55], v[20:23], v[60:63], v[52:55]
	v_mfma_f32_16x16x32_bf16 v[56:59], v[28:31], v[60:63], v[56:59]
	s_barrier
	s_mov_b32 m0, s68
	v_lshl_add_u64 v[244:245], s[78:79], 0, v[128:129]
	ds_read_b128 v[60:63], v143 offset:16384
	ds_read_b128 v[92:95], v143 offset:17408
	ds_read_b128 v[96:99], v143 offset:18432
	ds_read_b128 v[108:111], v143 offset:19456
	ds_read_b128 v[112:115], v143 offset:20480
	ds_read_b128 v[116:119], v143 offset:21504
	ds_read_b128 v[120:123], v143 offset:22528
	ds_read_b128 v[124:127], v143 offset:23552
	global_load_lds_dwordx4 v[244:245], off
	v_lshl_add_u64 v[136:137], v[244:245], 0, s[0:1]
	s_mov_b32 m0, s69
	v_lshl_add_u64 v[246:247], s[44:45], 0, v[130:131]
	global_load_lds_dwordx4 v[136:137], off
	v_lshl_add_u64 v[136:137], v[244:245], 0, s[2:3]
	s_mov_b32 m0, s70
	s_nop 0
	global_load_lds_dwordx4 v[136:137], off
	v_lshl_add_u64 v[136:137], v[244:245], 0, s[8:9]
	s_mov_b32 m0, s71
	s_nop 0
	global_load_lds_dwordx4 v[136:137], off
	s_mov_b32 m0, s39
	v_lshl_add_u64 v[136:137], v[246:247], 0, s[0:1]
	global_load_lds_dwordx4 v[246:247], off
	s_mov_b32 m0, s56
	s_nop 0
	global_load_lds_dwordx4 v[136:137], off
	s_waitcnt vmcnt(16)
	s_waitcnt lgkmcnt(0)
	s_barrier
	s_waitcnt lgkmcnt(0)
	v_mfma_f32_16x16x32_bf16 v[146:149], v[0:3], v[60:63], 0
	v_mfma_f32_16x16x32_bf16 v[154:157], v[0:3], v[96:99], 0
	v_mfma_f32_16x16x32_bf16 v[162:165], v[0:3], v[112:115], 0
	v_mfma_f32_16x16x32_bf16 v[0:3], v[0:3], v[120:123], 0
	v_mfma_f32_16x16x32_bf16 v[146:149], v[4:7], v[92:95], v[146:149]
	v_mfma_f32_16x16x32_bf16 v[154:157], v[4:7], v[108:111], v[154:157]
	v_mfma_f32_16x16x32_bf16 v[162:165], v[4:7], v[116:119], v[162:165]
	v_mfma_f32_16x16x32_bf16 v[0:3], v[4:7], v[124:127], v[0:3]
	v_mfma_f32_16x16x32_bf16 v[4:7], v[8:11], v[120:123], 0
	v_mfma_f32_16x16x32_bf16 v[150:153], v[8:11], v[60:63], 0
	v_mfma_f32_16x16x32_bf16 v[158:161], v[8:11], v[96:99], 0
	v_mfma_f32_16x16x32_bf16 v[166:169], v[8:11], v[112:115], 0
	v_mfma_f32_16x16x32_bf16 v[4:7], v[12:15], v[124:127], v[4:7]
	v_mfma_f32_16x16x32_bf16 v[150:153], v[12:15], v[92:95], v[150:153]
	v_mfma_f32_16x16x32_bf16 v[158:161], v[12:15], v[108:111], v[158:161]
	v_mfma_f32_16x16x32_bf16 v[166:169], v[12:15], v[116:119], v[166:169]
	v_mfma_f32_16x16x32_bf16 v[12:15], v[24:27], v[60:63], 0
	v_mfma_f32_16x16x32_bf16 v[170:173], v[28:31], v[92:95], v[12:15]
	v_mfma_f32_16x16x32_bf16 v[12:15], v[16:19], v[96:99], 0
	v_mfma_f32_16x16x32_bf16 v[174:177], v[20:23], v[108:111], v[12:15]
	v_mfma_f32_16x16x32_bf16 v[12:15], v[24:27], v[96:99], 0
	v_mfma_f32_16x16x32_bf16 v[178:181], v[28:31], v[108:111], v[12:15]
	v_mfma_f32_16x16x32_bf16 v[12:15], v[16:19], v[112:115], 0
	v_mfma_f32_16x16x32_bf16 v[182:185], v[20:23], v[116:119], v[12:15]
	v_mfma_f32_16x16x32_bf16 v[12:15], v[24:27], v[112:115], 0
	v_mfma_f32_16x16x32_bf16 v[8:11], v[16:19], v[60:63], 0
	v_mfma_f32_16x16x32_bf16 v[186:189], v[28:31], v[116:119], v[12:15]
	v_mfma_f32_16x16x32_bf16 v[12:15], v[16:19], v[120:123], 0
	v_mfma_f32_16x16x32_bf16 v[8:11], v[20:23], v[92:95], v[8:11]
	v_mfma_f32_16x16x32_bf16 v[190:193], v[20:23], v[124:127], v[12:15]
	v_mfma_f32_16x16x32_bf16 v[12:15], v[24:27], v[120:123], 0
	v_mfma_f32_16x16x32_bf16 v[194:197], v[28:31], v[124:127], v[12:15]
	s_barrier
	s_add_i32 s79, 0, 0x1c000
	v_add_u32_e32 v136, s79, v140
	s_nop 2
	ds_read_b128 v[12:15], v144
	ds_read_b128 v[20:23], v144 offset:1024
	ds_read_b128 v[24:27], v144 offset:2048
	ds_read_b128 v[198:201], v144 offset:3072
	ds_read_b128 v[202:205], v136
	ds_read_b128 v[206:209], v136 offset:1024
	ds_read_b128 v[212:215], v136 offset:2048
	ds_read_b128 v[216:219], v136 offset:3072
	s_mov_b32 m0, s57
	v_lshl_add_u64 v[92:93], v[246:247], 0, s[2:3]
	ds_read_b128 v[16:19], v143 offset:32768
	ds_read_b128 v[28:31], v143 offset:33792
	ds_read_b128 v[60:63], v143 offset:34816
	ds_read_b128 v[220:223], v143 offset:35840
	ds_read_b128 v[224:227], v143 offset:36864
	ds_read_b128 v[228:231], v143 offset:37888
	ds_read_b128 v[232:235], v143 offset:38912
	ds_read_b128 v[236:239], v143 offset:39936
	global_load_lds_dwordx4 v[92:93], off
	v_lshl_add_u64 v[92:93], v[246:247], 0, s[8:9]
	s_mov_b32 m0, s58
	s_nop 0
	global_load_lds_dwordx4 v[92:93], off
	s_waitcnt vmcnt(8)
	s_waitcnt lgkmcnt(0)
	s_barrier
	s_waitcnt lgkmcnt(0)
	v_mfma_f32_16x16x32_bf16 v[64:67], v[12:15], v[16:19], v[64:67]
	v_mfma_f32_16x16x32_bf16 v[124:127], v[20:23], v[28:31], v[64:67]
	v_mfma_f32_16x16x32_bf16 v[64:67], v[24:27], v[16:19], v[68:71]
	v_mfma_f32_16x16x32_bf16 v[112:115], v[198:201], v[28:31], v[64:67]
	v_mfma_f32_16x16x32_bf16 v[64:67], v[12:15], v[60:63], v[72:75]
	v_mfma_f32_16x16x32_bf16 v[108:111], v[20:23], v[220:223], v[64:67]
	v_mfma_f32_16x16x32_bf16 v[64:67], v[24:27], v[60:63], v[76:79]
	v_mfma_f32_16x16x32_bf16 v[96:99], v[198:201], v[220:223], v[64:67]
	v_mfma_f32_16x16x32_bf16 v[64:67], v[12:15], v[224:227], v[80:83]
	v_mfma_f32_16x16x32_bf16 v[92:95], v[20:23], v[228:231], v[64:67]
	v_mfma_f32_16x16x32_bf16 v[64:67], v[24:27], v[224:227], v[84:87]
	v_mfma_f32_16x16x32_bf16 v[80:83], v[198:201], v[228:231], v[64:67]
	v_mfma_f32_16x16x32_bf16 v[64:67], v[12:15], v[232:235], v[88:91]
	v_mfma_f32_16x16x32_bf16 v[76:79], v[20:23], v[236:239], v[64:67]
	v_mfma_f32_16x16x32_bf16 v[64:67], v[24:27], v[232:235], v[100:103]
	v_mfma_f32_16x16x32_bf16 v[64:67], v[198:201], v[236:239], v[64:67]
	v_mfma_f32_16x16x32_bf16 v[68:71], v[202:205], v[16:19], v[104:107]
	v_mfma_f32_16x16x32_bf16 v[16:19], v[212:215], v[16:19], v[32:35]
	v_mfma_f32_16x16x32_bf16 v[116:119], v[216:219], v[28:31], v[16:19]
	v_mfma_f32_16x16x32_bf16 v[16:19], v[202:205], v[60:63], v[36:39]
	v_mfma_f32_16x16x32_bf16 v[104:107], v[206:209], v[220:223], v[16:19]
	v_mfma_f32_16x16x32_bf16 v[16:19], v[212:215], v[60:63], v[40:43]
	v_mfma_f32_16x16x32_bf16 v[100:103], v[216:219], v[220:223], v[16:19]
	v_mfma_f32_16x16x32_bf16 v[16:19], v[202:205], v[224:227], v[44:47]
	v_mfma_f32_16x16x32_bf16 v[88:91], v[206:209], v[228:231], v[16:19]
	v_mfma_f32_16x16x32_bf16 v[16:19], v[212:215], v[224:227], v[48:51]
	v_mfma_f32_16x16x32_bf16 v[84:87], v[216:219], v[228:231], v[16:19]
	v_mfma_f32_16x16x32_bf16 v[16:19], v[202:205], v[232:235], v[52:55]
	v_mfma_f32_16x16x32_bf16 v[72:75], v[206:209], v[236:239], v[16:19]
	v_mfma_f32_16x16x32_bf16 v[16:19], v[212:215], v[232:235], v[56:59]
	v_mfma_f32_16x16x32_bf16 v[120:123], v[206:209], v[28:31], v[68:71]
	v_mfma_f32_16x16x32_bf16 v[68:71], v[216:219], v[236:239], v[16:19]
	s_barrier
	s_add_i32 s77, s72, s53
	s_nop 2
	v_lshl_add_u64 v[16:17], v[244:245], 0, s[18:19]
	s_mov_b32 m0, s77
	s_add_i32 s78, s77, 0x2000
	ds_read_b128 v[36:39], v143 offset:49152
	ds_read_b128 v[40:43], v143 offset:50176
	ds_read_b128 v[220:223], v143 offset:51200
	ds_read_b128 v[224:227], v143 offset:52224
	ds_read_b128 v[228:231], v143 offset:53248
	ds_read_b128 v[232:235], v143 offset:54272
	ds_read_b128 v[236:239], v143 offset:55296
	ds_read_b128 v[240:243], v143 offset:56320
	global_load_lds_dwordx4 v[16:17], off
	v_lshl_add_u64 v[16:17], v[244:245], 0, s[20:21]
	s_mov_b32 m0, s78
	s_add_i32 s79, s79, s53
	global_load_lds_dwordx4 v[16:17], off
	v_lshl_add_u64 v[16:17], v[244:245], 0, s[22:23]
	s_mov_b32 m0, s79
	s_add_i32 s80, s79, 0x2000
	global_load_lds_dwordx4 v[16:17], off
	v_lshl_add_u64 v[16:17], v[244:245], 0, s[24:25]
	s_mov_b32 m0, s80
	s_nop 0
	global_load_lds_dwordx4 v[16:17], off
	v_lshl_add_u64 v[16:17], v[246:247], 0, s[18:19]
	s_mov_b32 m0, s60
	s_nop 0
	global_load_lds_dwordx4 v[16:17], off
	v_lshl_add_u64 v[16:17], v[246:247], 0, s[20:21]
	s_mov_b32 m0, s61
	s_nop 0
	global_load_lds_dwordx4 v[16:17], off
	s_waitcnt vmcnt(8)
	s_waitcnt lgkmcnt(0)
	s_barrier
	s_waitcnt lgkmcnt(0)
	v_mfma_f32_16x16x32_bf16 v[16:19], v[12:15], v[36:39], v[146:149]
	v_mfma_f32_16x16x32_bf16 v[60:63], v[20:23], v[40:43], v[16:19]
	v_mfma_f32_16x16x32_bf16 v[16:19], v[24:27], v[36:39], v[150:153]
	v_mfma_f32_16x16x32_bf16 v[48:51], v[198:201], v[40:43], v[16:19]
	v_mfma_f32_16x16x32_bf16 v[16:19], v[12:15], v[220:223], v[154:157]
	v_mfma_f32_16x16x32_bf16 v[44:47], v[20:23], v[224:227], v[16:19]
	v_mfma_f32_16x16x32_bf16 v[16:19], v[24:27], v[220:223], v[158:161]
	v_mfma_f32_16x16x32_bf16 v[32:35], v[198:201], v[224:227], v[16:19]
	v_mfma_f32_16x16x32_bf16 v[16:19], v[12:15], v[228:231], v[162:165]
	v_mfma_f32_16x16x32_bf16 v[0:3], v[12:15], v[236:239], v[0:3]
	v_mfma_f32_16x16x32_bf16 v[28:31], v[20:23], v[232:235], v[16:19]
	v_mfma_f32_16x16x32_bf16 v[16:19], v[24:27], v[228:231], v[166:169]
	v_mfma_f32_16x16x32_bf16 v[12:15], v[20:23], v[240:243], v[0:3]
	v_mfma_f32_16x16x32_bf16 v[0:3], v[24:27], v[236:239], v[4:7]
	v_mfma_f32_16x16x32_bf16 v[16:19], v[198:201], v[232:235], v[16:19]
	v_mfma_f32_16x16x32_bf16 v[0:3], v[198:201], v[240:243], v[0:3]
	v_mfma_f32_16x16x32_bf16 v[4:7], v[202:205], v[36:39], v[8:11]
	v_mfma_f32_16x16x32_bf16 v[56:59], v[206:209], v[40:43], v[4:7]
	v_mfma_f32_16x16x32_bf16 v[4:7], v[212:215], v[36:39], v[170:173]
	v_mfma_f32_16x16x32_bf16 v[52:55], v[216:219], v[40:43], v[4:7]
	v_mfma_f32_16x16x32_bf16 v[4:7], v[202:205], v[220:223], v[174:177]
	v_mfma_f32_16x16x32_bf16 v[40:43], v[206:209], v[224:227], v[4:7]
	v_mfma_f32_16x16x32_bf16 v[4:7], v[212:215], v[220:223], v[178:181]
	v_mfma_f32_16x16x32_bf16 v[36:39], v[216:219], v[224:227], v[4:7]
	v_mfma_f32_16x16x32_bf16 v[4:7], v[202:205], v[228:231], v[182:185]
	v_mfma_f32_16x16x32_bf16 v[24:27], v[206:209], v[232:235], v[4:7]
	v_mfma_f32_16x16x32_bf16 v[4:7], v[212:215], v[228:231], v[186:189]
	v_mfma_f32_16x16x32_bf16 v[20:23], v[216:219], v[232:235], v[4:7]
	v_mfma_f32_16x16x32_bf16 v[4:7], v[202:205], v[236:239], v[190:193]
	v_mfma_f32_16x16x32_bf16 v[8:11], v[206:209], v[240:243], v[4:7]
	v_mfma_f32_16x16x32_bf16 v[4:7], v[212:215], v[236:239], v[194:197]
	v_mfma_f32_16x16x32_bf16 v[4:7], v[216:219], v[240:243], v[4:7]
	s_barrier
.LBB0_175:
	s_add_i32 s29, s29, 2
	s_mov_b32 s44, s29
	ds_read_b128 v[146:149], v141
	ds_read_b128 v[150:153], v141 offset:1024
	ds_read_b128 v[154:157], v141 offset:2048
	ds_read_b128 v[158:161], v141 offset:3072
	ds_read_b128 v[162:165], v142
	ds_read_b128 v[166:169], v142 offset:1024
	ds_read_b128 v[170:173], v142 offset:2048
	ds_read_b128 v[174:177], v142 offset:3072
	s_ashr_i32 s45, s44, 31
	s_lshl_b64 s[82:83], s[44:45], 7
	s_add_u32 s45, s82, 0x100
	s_addc_u32 s81, s83, 0
	s_add_u32 s84, s42, s45
	s_addc_u32 s85, s43, s81
	s_add_u32 s86, s40, s45
	s_addc_u32 s81, s41, s81
	s_cmp_eq_u32 s44, 14
	s_cselect_b32 s45, s75, s85
	s_cselect_b32 s44, s76, s84
	s_cselect_b32 s85, s31, s81
	s_cselect_b32 s84, s74, s86
	s_add_u32 s82, s42, s82
	s_addc_u32 s83, s43, s83
	v_lshl_add_u64 v[212:213], s[82:83], 0, v[130:131]
	s_mov_b32 m0, s66
	v_lshl_add_u64 v[214:215], v[212:213], 0, s[22:23]
	ds_read_b128 v[178:181], v143
	ds_read_b128 v[182:185], v143 offset:1024
	ds_read_b128 v[186:189], v143 offset:2048
	ds_read_b128 v[190:193], v143 offset:3072
	ds_read_b128 v[194:197], v143 offset:4096
	ds_read_b128 v[198:201], v143 offset:5120
	ds_read_b128 v[202:205], v143 offset:6144
	ds_read_b128 v[206:209], v143 offset:7168
	global_load_lds_dwordx4 v[214:215], off
	v_lshl_add_u64 v[212:213], v[212:213], 0, s[24:25]
	s_mov_b32 m0, s67
	s_nop 0
	global_load_lds_dwordx4 v[212:213], off
	s_waitcnt vmcnt(8)
	s_waitcnt lgkmcnt(0)
	s_barrier
	s_waitcnt lgkmcnt(0)
	v_mfma_f32_16x16x32_bf16 v[124:127], v[146:149], v[178:181], v[124:127]
	v_mfma_f32_16x16x32_bf16 v[112:115], v[154:157], v[178:181], v[112:115]
	v_mfma_f32_16x16x32_bf16 v[108:111], v[146:149], v[186:189], v[108:111]
	v_mfma_f32_16x16x32_bf16 v[96:99], v[154:157], v[186:189], v[96:99]
	v_mfma_f32_16x16x32_bf16 v[92:95], v[146:149], v[194:197], v[92:95]
	v_mfma_f32_16x16x32_bf16 v[80:83], v[154:157], v[194:197], v[80:83]
	v_mfma_f32_16x16x32_bf16 v[76:79], v[146:149], v[202:205], v[76:79]
	v_mfma_f32_16x16x32_bf16 v[64:67], v[154:157], v[202:205], v[64:67]
	v_mfma_f32_16x16x32_bf16 v[124:127], v[150:153], v[182:185], v[124:127]
	v_mfma_f32_16x16x32_bf16 v[112:115], v[158:161], v[182:185], v[112:115]
	v_mfma_f32_16x16x32_bf16 v[108:111], v[150:153], v[190:193], v[108:111]
	v_mfma_f32_16x16x32_bf16 v[96:99], v[158:161], v[190:193], v[96:99]
	v_mfma_f32_16x16x32_bf16 v[92:95], v[150:153], v[198:201], v[92:95]
	v_mfma_f32_16x16x32_bf16 v[80:83], v[158:161], v[198:201], v[80:83]
	v_mfma_f32_16x16x32_bf16 v[76:79], v[150:153], v[206:209], v[76:79]
	v_mfma_f32_16x16x32_bf16 v[64:67], v[158:161], v[206:209], v[64:67]
	v_mfma_f32_16x16x32_bf16 v[120:123], v[162:165], v[178:181], v[120:123]
	v_mfma_f32_16x16x32_bf16 v[116:119], v[170:173], v[178:181], v[116:119]
	v_mfma_f32_16x16x32_bf16 v[104:107], v[162:165], v[186:189], v[104:107]
	v_mfma_f32_16x16x32_bf16 v[100:103], v[170:173], v[186:189], v[100:103]
	v_mfma_f32_16x16x32_bf16 v[88:91], v[162:165], v[194:197], v[88:91]
	v_mfma_f32_16x16x32_bf16 v[84:87], v[170:173], v[194:197], v[84:87]
	v_mfma_f32_16x16x32_bf16 v[72:75], v[162:165], v[202:205], v[72:75]
	v_mfma_f32_16x16x32_bf16 v[68:71], v[170:173], v[202:205], v[68:71]
	v_mfma_f32_16x16x32_bf16 v[120:123], v[166:169], v[182:185], v[120:123]
	v_mfma_f32_16x16x32_bf16 v[116:119], v[174:177], v[182:185], v[116:119]
	v_mfma_f32_16x16x32_bf16 v[104:107], v[166:169], v[190:193], v[104:107]
	v_mfma_f32_16x16x32_bf16 v[100:103], v[174:177], v[190:193], v[100:103]
	v_mfma_f32_16x16x32_bf16 v[88:91], v[166:169], v[198:201], v[88:91]
	v_mfma_f32_16x16x32_bf16 v[84:87], v[174:177], v[198:201], v[84:87]
	v_mfma_f32_16x16x32_bf16 v[72:75], v[166:169], v[206:209], v[72:75]
	v_mfma_f32_16x16x32_bf16 v[68:71], v[174:177], v[206:209], v[68:71]
	s_barrier
	s_mov_b32 m0, s68
	v_lshl_add_u64 v[212:213], s[84:85], 0, v[128:129]
	ds_read_b128 v[178:181], v143 offset:16384
	ds_read_b128 v[182:185], v143 offset:17408
	ds_read_b128 v[186:189], v143 offset:18432
	ds_read_b128 v[190:193], v143 offset:19456
	ds_read_b128 v[194:197], v143 offset:20480
	ds_read_b128 v[198:201], v143 offset:21504
	ds_read_b128 v[202:205], v143 offset:22528
	ds_read_b128 v[206:209], v143 offset:23552
	global_load_lds_dwordx4 v[212:213], off
	v_lshl_add_u64 v[214:215], v[212:213], 0, s[0:1]
	s_mov_b32 m0, s69
	s_nop 0
	global_load_lds_dwordx4 v[214:215], off
	v_lshl_add_u64 v[214:215], v[212:213], 0, s[2:3]
	s_mov_b32 m0, s70
	s_nop 0
	global_load_lds_dwordx4 v[214:215], off
	v_lshl_add_u64 v[214:215], v[212:213], 0, s[8:9]
	s_mov_b32 m0, s71
	s_nop 0
	global_load_lds_dwordx4 v[214:215], off
	v_lshl_add_u64 v[214:215], s[44:45], 0, v[130:131]
	s_mov_b32 m0, s39
	v_lshl_add_u64 v[216:217], v[214:215], 0, s[0:1]
	global_load_lds_dwordx4 v[214:215], off
	s_mov_b32 m0, s56
	s_nop 0
	global_load_lds_dwordx4 v[216:217], off
	s_waitcnt vmcnt(8)
	s_waitcnt lgkmcnt(0)
	s_barrier
	s_waitcnt lgkmcnt(0)
	v_mfma_f32_16x16x32_bf16 v[60:63], v[146:149], v[178:181], v[60:63]
	v_mfma_f32_16x16x32_bf16 v[48:51], v[154:157], v[178:181], v[48:51]
	v_mfma_f32_16x16x32_bf16 v[44:47], v[146:149], v[186:189], v[44:47]
	v_mfma_f32_16x16x32_bf16 v[32:35], v[154:157], v[186:189], v[32:35]
	v_mfma_f32_16x16x32_bf16 v[28:31], v[146:149], v[194:197], v[28:31]
	v_mfma_f32_16x16x32_bf16 v[16:19], v[154:157], v[194:197], v[16:19]
	v_mfma_f32_16x16x32_bf16 v[12:15], v[146:149], v[202:205], v[12:15]
	v_mfma_f32_16x16x32_bf16 v[0:3], v[154:157], v[202:205], v[0:3]
	v_mfma_f32_16x16x32_bf16 v[60:63], v[150:153], v[182:185], v[60:63]
	v_mfma_f32_16x16x32_bf16 v[48:51], v[158:161], v[182:185], v[48:51]
	v_mfma_f32_16x16x32_bf16 v[44:47], v[150:153], v[190:193], v[44:47]
	v_mfma_f32_16x16x32_bf16 v[32:35], v[158:161], v[190:193], v[32:35]
	v_mfma_f32_16x16x32_bf16 v[28:31], v[150:153], v[198:201], v[28:31]
	v_mfma_f32_16x16x32_bf16 v[16:19], v[158:161], v[198:201], v[16:19]
	v_mfma_f32_16x16x32_bf16 v[12:15], v[150:153], v[206:209], v[12:15]
	v_mfma_f32_16x16x32_bf16 v[0:3], v[158:161], v[206:209], v[0:3]
	v_mfma_f32_16x16x32_bf16 v[56:59], v[162:165], v[178:181], v[56:59]
	v_mfma_f32_16x16x32_bf16 v[52:55], v[170:173], v[178:181], v[52:55]
	v_mfma_f32_16x16x32_bf16 v[40:43], v[162:165], v[186:189], v[40:43]
	v_mfma_f32_16x16x32_bf16 v[36:39], v[170:173], v[186:189], v[36:39]
	v_mfma_f32_16x16x32_bf16 v[24:27], v[162:165], v[194:197], v[24:27]
	v_mfma_f32_16x16x32_bf16 v[20:23], v[170:173], v[194:197], v[20:23]
	v_mfma_f32_16x16x32_bf16 v[8:11], v[162:165], v[202:205], v[8:11]
	v_mfma_f32_16x16x32_bf16 v[4:7], v[170:173], v[202:205], v[4:7]
	v_mfma_f32_16x16x32_bf16 v[56:59], v[166:169], v[182:185], v[56:59]
	v_mfma_f32_16x16x32_bf16 v[52:55], v[174:177], v[182:185], v[52:55]
	v_mfma_f32_16x16x32_bf16 v[40:43], v[166:169], v[190:193], v[40:43]
	v_mfma_f32_16x16x32_bf16 v[36:39], v[174:177], v[190:193], v[36:39]
	v_mfma_f32_16x16x32_bf16 v[24:27], v[166:169], v[198:201], v[24:27]
	v_mfma_f32_16x16x32_bf16 v[20:23], v[174:177], v[198:201], v[20:23]
	v_mfma_f32_16x16x32_bf16 v[8:11], v[166:169], v[206:209], v[8:11]
	v_mfma_f32_16x16x32_bf16 v[4:7], v[174:177], v[206:209], v[4:7]
	s_barrier
	ds_read_b128 v[146:149], v144
	ds_read_b128 v[150:153], v144 offset:1024
	ds_read_b128 v[154:157], v144 offset:2048
	ds_read_b128 v[158:161], v144 offset:3072
	ds_read_b128 v[162:165], v136
	ds_read_b128 v[166:169], v136 offset:1024
	ds_read_b128 v[170:173], v136 offset:2048
	ds_read_b128 v[174:177], v136 offset:3072
	s_mov_b32 m0, s57
	v_lshl_add_u64 v[216:217], v[214:215], 0, s[2:3]
	ds_read_b128 v[178:181], v143 offset:32768
	ds_read_b128 v[182:185], v143 offset:33792
	ds_read_b128 v[186:189], v143 offset:34816
	ds_read_b128 v[190:193], v143 offset:35840
	ds_read_b128 v[194:197], v143 offset:36864
	ds_read_b128 v[198:201], v143 offset:37888
	ds_read_b128 v[202:205], v143 offset:38912
	ds_read_b128 v[206:209], v143 offset:39936
	global_load_lds_dwordx4 v[216:217], off
	v_lshl_add_u64 v[216:217], v[214:215], 0, s[8:9]
	s_mov_b32 m0, s58
	s_nop 0
	global_load_lds_dwordx4 v[216:217], off
	s_waitcnt vmcnt(8)
	s_waitcnt lgkmcnt(0)
	s_barrier
	s_waitcnt lgkmcnt(0)
	v_mfma_f32_16x16x32_bf16 v[124:127], v[146:149], v[178:181], v[124:127]
	v_mfma_f32_16x16x32_bf16 v[112:115], v[154:157], v[178:181], v[112:115]
	v_mfma_f32_16x16x32_bf16 v[108:111], v[146:149], v[186:189], v[108:111]
	v_mfma_f32_16x16x32_bf16 v[96:99], v[154:157], v[186:189], v[96:99]
	v_mfma_f32_16x16x32_bf16 v[92:95], v[146:149], v[194:197], v[92:95]
	v_mfma_f32_16x16x32_bf16 v[80:83], v[154:157], v[194:197], v[80:83]
	v_mfma_f32_16x16x32_bf16 v[76:79], v[146:149], v[202:205], v[76:79]
	v_mfma_f32_16x16x32_bf16 v[64:67], v[154:157], v[202:205], v[64:67]
	v_mfma_f32_16x16x32_bf16 v[124:127], v[150:153], v[182:185], v[124:127]
	v_mfma_f32_16x16x32_bf16 v[112:115], v[158:161], v[182:185], v[112:115]
	v_mfma_f32_16x16x32_bf16 v[108:111], v[150:153], v[190:193], v[108:111]
	v_mfma_f32_16x16x32_bf16 v[96:99], v[158:161], v[190:193], v[96:99]
	v_mfma_f32_16x16x32_bf16 v[92:95], v[150:153], v[198:201], v[92:95]
	v_mfma_f32_16x16x32_bf16 v[80:83], v[158:161], v[198:201], v[80:83]
	v_mfma_f32_16x16x32_bf16 v[76:79], v[150:153], v[206:209], v[76:79]
	v_mfma_f32_16x16x32_bf16 v[64:67], v[158:161], v[206:209], v[64:67]
	v_mfma_f32_16x16x32_bf16 v[120:123], v[162:165], v[178:181], v[120:123]
	v_mfma_f32_16x16x32_bf16 v[116:119], v[170:173], v[178:181], v[116:119]
	v_mfma_f32_16x16x32_bf16 v[104:107], v[162:165], v[186:189], v[104:107]
	v_mfma_f32_16x16x32_bf16 v[100:103], v[170:173], v[186:189], v[100:103]
	v_mfma_f32_16x16x32_bf16 v[88:91], v[162:165], v[194:197], v[88:91]
	v_mfma_f32_16x16x32_bf16 v[84:87], v[170:173], v[194:197], v[84:87]
	v_mfma_f32_16x16x32_bf16 v[72:75], v[162:165], v[202:205], v[72:75]
	v_mfma_f32_16x16x32_bf16 v[68:71], v[170:173], v[202:205], v[68:71]
	v_mfma_f32_16x16x32_bf16 v[120:123], v[166:169], v[182:185], v[120:123]
	v_mfma_f32_16x16x32_bf16 v[116:119], v[174:177], v[182:185], v[116:119]
	v_mfma_f32_16x16x32_bf16 v[104:107], v[166:169], v[190:193], v[104:107]
	v_mfma_f32_16x16x32_bf16 v[100:103], v[174:177], v[190:193], v[100:103]
	v_mfma_f32_16x16x32_bf16 v[88:91], v[166:169], v[198:201], v[88:91]
	v_mfma_f32_16x16x32_bf16 v[84:87], v[174:177], v[198:201], v[84:87]
	v_mfma_f32_16x16x32_bf16 v[72:75], v[166:169], v[206:209], v[72:75]
	v_mfma_f32_16x16x32_bf16 v[68:71], v[174:177], v[206:209], v[68:71]
	s_barrier
	s_mov_b32 m0, s77
	v_lshl_add_u64 v[216:217], v[212:213], 0, s[18:19]
	ds_read_b128 v[178:181], v143 offset:49152
	ds_read_b128 v[182:185], v143 offset:50176
	ds_read_b128 v[186:189], v143 offset:51200
	ds_read_b128 v[190:193], v143 offset:52224
	ds_read_b128 v[194:197], v143 offset:53248
	ds_read_b128 v[198:201], v143 offset:54272
	ds_read_b128 v[202:205], v143 offset:55296
	ds_read_b128 v[206:209], v143 offset:56320
	global_load_lds_dwordx4 v[216:217], off
	v_lshl_add_u64 v[216:217], v[212:213], 0, s[20:21]
	s_mov_b32 m0, s78
	s_nop 0
	global_load_lds_dwordx4 v[216:217], off
	v_lshl_add_u64 v[216:217], v[212:213], 0, s[22:23]
	s_mov_b32 m0, s79
	v_lshl_add_u64 v[212:213], v[212:213], 0, s[24:25]
	global_load_lds_dwordx4 v[216:217], off
	s_mov_b32 m0, s80
	s_nop 0
	global_load_lds_dwordx4 v[212:213], off
	v_lshl_add_u64 v[212:213], v[214:215], 0, s[18:19]
	s_mov_b32 m0, s60
	s_nop 0
	global_load_lds_dwordx4 v[212:213], off
	v_lshl_add_u64 v[212:213], v[214:215], 0, s[20:21]
	s_mov_b32 m0, s61
	s_nop 0
	global_load_lds_dwordx4 v[212:213], off
	s_waitcnt vmcnt(8)
	s_waitcnt lgkmcnt(0)
	s_barrier
	s_waitcnt lgkmcnt(0)
	v_mfma_f32_16x16x32_bf16 v[60:63], v[146:149], v[178:181], v[60:63]
	v_mfma_f32_16x16x32_bf16 v[48:51], v[154:157], v[178:181], v[48:51]
	v_mfma_f32_16x16x32_bf16 v[44:47], v[146:149], v[186:189], v[44:47]
	v_mfma_f32_16x16x32_bf16 v[32:35], v[154:157], v[186:189], v[32:35]
	v_mfma_f32_16x16x32_bf16 v[28:31], v[146:149], v[194:197], v[28:31]
	v_mfma_f32_16x16x32_bf16 v[16:19], v[154:157], v[194:197], v[16:19]
	v_mfma_f32_16x16x32_bf16 v[12:15], v[146:149], v[202:205], v[12:15]
	v_mfma_f32_16x16x32_bf16 v[0:3], v[154:157], v[202:205], v[0:3]
	v_mfma_f32_16x16x32_bf16 v[60:63], v[150:153], v[182:185], v[60:63]
	v_mfma_f32_16x16x32_bf16 v[48:51], v[158:161], v[182:185], v[48:51]
	v_mfma_f32_16x16x32_bf16 v[44:47], v[150:153], v[190:193], v[44:47]
	v_mfma_f32_16x16x32_bf16 v[32:35], v[158:161], v[190:193], v[32:35]
	v_mfma_f32_16x16x32_bf16 v[28:31], v[150:153], v[198:201], v[28:31]
	v_mfma_f32_16x16x32_bf16 v[16:19], v[158:161], v[198:201], v[16:19]
	v_mfma_f32_16x16x32_bf16 v[12:15], v[150:153], v[206:209], v[12:15]
	v_mfma_f32_16x16x32_bf16 v[0:3], v[158:161], v[206:209], v[0:3]
	v_mfma_f32_16x16x32_bf16 v[56:59], v[162:165], v[178:181], v[56:59]
	v_mfma_f32_16x16x32_bf16 v[52:55], v[170:173], v[178:181], v[52:55]
	v_mfma_f32_16x16x32_bf16 v[40:43], v[162:165], v[186:189], v[40:43]
	v_mfma_f32_16x16x32_bf16 v[36:39], v[170:173], v[186:189], v[36:39]
	v_mfma_f32_16x16x32_bf16 v[24:27], v[162:165], v[194:197], v[24:27]
	v_mfma_f32_16x16x32_bf16 v[20:23], v[170:173], v[194:197], v[20:23]
	v_mfma_f32_16x16x32_bf16 v[8:11], v[162:165], v[202:205], v[8:11]
	v_mfma_f32_16x16x32_bf16 v[4:7], v[170:173], v[202:205], v[4:7]
	v_mfma_f32_16x16x32_bf16 v[56:59], v[166:169], v[182:185], v[56:59]
	v_mfma_f32_16x16x32_bf16 v[52:55], v[174:177], v[182:185], v[52:55]
	v_mfma_f32_16x16x32_bf16 v[40:43], v[166:169], v[190:193], v[40:43]
	v_mfma_f32_16x16x32_bf16 v[36:39], v[174:177], v[190:193], v[36:39]
	v_mfma_f32_16x16x32_bf16 v[24:27], v[166:169], v[198:201], v[24:27]
	v_mfma_f32_16x16x32_bf16 v[20:23], v[174:177], v[198:201], v[20:23]
	v_mfma_f32_16x16x32_bf16 v[8:11], v[166:169], v[206:209], v[8:11]
	v_mfma_f32_16x16x32_bf16 v[4:7], v[174:177], v[206:209], v[4:7]
	s_barrier
	s_cmp_gt_u32 s29, 13
	s_cbranch_scc0 .LBB0_175
	s_and_b64 vcc, exec, s[26:27]
	s_cbranch_vccz .LBB0_178
	s_barrier

.LBB0_255:
	s_add_i32 s73, s73, 2
	s_mov_b32 s74, s73
	ds_read_b128 v[144:147], v141
	ds_read_b128 v[148:151], v141 offset:1024
	ds_read_b128 v[152:155], v141 offset:2048
	ds_read_b128 v[156:159], v141 offset:3072
	ds_read_b128 v[160:163], v142
	ds_read_b128 v[164:167], v142 offset:1024
	ds_read_b128 v[168:171], v142 offset:2048
	ds_read_b128 v[172:175], v142 offset:3072
	s_ashr_i32 s75, s74, 31
	s_lshl_b64 s[76:77], s[74:75], 7
	s_add_u32 s75, s76, 0x100
	s_addc_u32 s78, s77, 0
	s_add_u32 s79, s40, s75
	s_addc_u32 s80, s41, s78
	s_add_u32 s81, s38, s75
	s_addc_u32 s78, s39, s78
	s_cmp_eq_u32 s74, 42
	s_cselect_b32 s75, s1, s80
	s_cselect_b32 s74, s0, s79
	s_cselect_b32 s79, s43, s78
	s_cselect_b32 s78, s42, s81
	v_lshl_add_u64 v[208:209], v[136:137], 0, s[76:77]
	v_lshl_add_u64 v[212:213], v[208:209], 0, s[20:21]
	s_add_i32 m0, s53, 0xc000
	ds_read_b128 v[176:179], v143
	ds_read_b128 v[180:183], v143 offset:1024
	ds_read_b128 v[184:187], v143 offset:2048
	ds_read_b128 v[188:191], v143 offset:3072
	ds_read_b128 v[192:195], v143 offset:4096
	ds_read_b128 v[196:199], v143 offset:5120
	ds_read_b128 v[200:203], v143 offset:6144
	ds_read_b128 v[204:207], v143 offset:7168
	global_load_lds_dwordx4 v[212:213], off
	v_lshl_add_u64 v[208:209], v[208:209], 0, s[22:23]
	s_add_i32 m0, s53, 0xe000
	s_nop 0
	global_load_lds_dwordx4 v[208:209], off
	s_waitcnt vmcnt(8)
	s_waitcnt lgkmcnt(0)
	s_barrier
	s_waitcnt lgkmcnt(0)
	v_mfma_f32_16x16x32_bf16 v[124:127], v[144:147], v[176:179], v[124:127]
	v_mfma_f32_16x16x32_bf16 v[120:123], v[152:155], v[176:179], v[120:123]
	v_mfma_f32_16x16x32_bf16 v[116:119], v[144:147], v[184:187], v[116:119]
	v_mfma_f32_16x16x32_bf16 v[112:115], v[152:155], v[184:187], v[112:115]
	v_mfma_f32_16x16x32_bf16 v[100:103], v[144:147], v[192:195], v[100:103]
	v_mfma_f32_16x16x32_bf16 v[96:99], v[152:155], v[192:195], v[96:99]
	v_mfma_f32_16x16x32_bf16 v[84:87], v[144:147], v[200:203], v[84:87]
	v_mfma_f32_16x16x32_bf16 v[80:83], v[152:155], v[200:203], v[80:83]
	v_mfma_f32_16x16x32_bf16 v[124:127], v[148:151], v[180:183], v[124:127]
	v_mfma_f32_16x16x32_bf16 v[120:123], v[156:159], v[180:183], v[120:123]
	v_mfma_f32_16x16x32_bf16 v[116:119], v[148:151], v[188:191], v[116:119]
	v_mfma_f32_16x16x32_bf16 v[112:115], v[156:159], v[188:191], v[112:115]
	v_mfma_f32_16x16x32_bf16 v[100:103], v[148:151], v[196:199], v[100:103]
	v_mfma_f32_16x16x32_bf16 v[96:99], v[156:159], v[196:199], v[96:99]
	v_mfma_f32_16x16x32_bf16 v[84:87], v[148:151], v[204:207], v[84:87]
	v_mfma_f32_16x16x32_bf16 v[80:83], v[156:159], v[204:207], v[80:83]
	v_mfma_f32_16x16x32_bf16 v[108:111], v[160:163], v[176:179], v[108:111]
	v_mfma_f32_16x16x32_bf16 v[104:107], v[168:171], v[176:179], v[104:107]
	v_mfma_f32_16x16x32_bf16 v[92:95], v[160:163], v[184:187], v[92:95]
	v_mfma_f32_16x16x32_bf16 v[88:91], v[168:171], v[184:187], v[88:91]
	v_mfma_f32_16x16x32_bf16 v[76:79], v[160:163], v[192:195], v[76:79]
	v_mfma_f32_16x16x32_bf16 v[72:75], v[168:171], v[192:195], v[72:75]
	v_mfma_f32_16x16x32_bf16 v[68:71], v[160:163], v[200:203], v[68:71]
	v_mfma_f32_16x16x32_bf16 v[64:67], v[168:171], v[200:203], v[64:67]
	v_mfma_f32_16x16x32_bf16 v[108:111], v[164:167], v[180:183], v[108:111]
	v_mfma_f32_16x16x32_bf16 v[104:107], v[172:175], v[180:183], v[104:107]
	v_mfma_f32_16x16x32_bf16 v[92:95], v[164:167], v[188:191], v[92:95]
	v_mfma_f32_16x16x32_bf16 v[88:91], v[172:175], v[188:191], v[88:91]
	v_mfma_f32_16x16x32_bf16 v[76:79], v[164:167], v[196:199], v[76:79]
	v_mfma_f32_16x16x32_bf16 v[72:75], v[172:175], v[196:199], v[72:75]
	v_mfma_f32_16x16x32_bf16 v[68:71], v[164:167], v[204:207], v[68:71]
	v_mfma_f32_16x16x32_bf16 v[64:67], v[172:175], v[204:207], v[64:67]
	s_barrier
	s_add_i32 s76, s63, s52
	v_lshl_add_u64 v[208:209], s[78:79], 0, v[130:131]
	s_mov_b32 m0, s76
	ds_read_b128 v[176:179], v143 offset:16384
	ds_read_b128 v[180:183], v143 offset:17408
	ds_read_b128 v[184:187], v143 offset:18432
	ds_read_b128 v[188:191], v143 offset:19456
	ds_read_b128 v[192:195], v143 offset:20480
	ds_read_b128 v[196:199], v143 offset:21504
	ds_read_b128 v[200:203], v143 offset:22528
	ds_read_b128 v[204:207], v143 offset:23552
	global_load_lds_dwordx4 v[208:209], off
	v_lshl_add_u64 v[212:213], v[208:209], 0, s[2:3]
	s_add_i32 m0, s76, 0x2000
	s_add_i32 s76, s64, s52
	global_load_lds_dwordx4 v[212:213], off
	v_lshl_add_u64 v[212:213], v[208:209], 0, s[8:9]
	s_mov_b32 m0, s76
	s_nop 0
	global_load_lds_dwordx4 v[212:213], off
	v_lshl_add_u64 v[212:213], v[208:209], 0, s[14:15]
	s_add_i32 m0, s76, 0x2000
	s_nop 0
	global_load_lds_dwordx4 v[212:213], off
	v_lshl_add_u64 v[212:213], s[74:75], 0, v[128:129]
	s_mov_b32 m0, s53
	v_lshl_add_u64 v[214:215], v[212:213], 0, s[2:3]
	global_load_lds_dwordx4 v[212:213], off
	s_mov_b32 m0, s54
	s_nop 0
	global_load_lds_dwordx4 v[214:215], off
	s_waitcnt vmcnt(8)
	s_waitcnt lgkmcnt(0)
	s_barrier
	s_waitcnt lgkmcnt(0)
	v_mfma_f32_16x16x32_bf16 v[60:63], v[144:147], v[176:179], v[60:63]
	v_mfma_f32_16x16x32_bf16 v[56:59], v[152:155], v[176:179], v[56:59]
	v_mfma_f32_16x16x32_bf16 v[52:55], v[144:147], v[184:187], v[52:55]
	v_mfma_f32_16x16x32_bf16 v[48:51], v[152:155], v[184:187], v[48:51]
	v_mfma_f32_16x16x32_bf16 v[36:39], v[144:147], v[192:195], v[36:39]
	v_mfma_f32_16x16x32_bf16 v[32:35], v[152:155], v[192:195], v[32:35]
	v_mfma_f32_16x16x32_bf16 v[20:23], v[144:147], v[200:203], v[20:23]
	v_mfma_f32_16x16x32_bf16 v[16:19], v[152:155], v[200:203], v[16:19]
	v_mfma_f32_16x16x32_bf16 v[60:63], v[148:151], v[180:183], v[60:63]
	v_mfma_f32_16x16x32_bf16 v[56:59], v[156:159], v[180:183], v[56:59]
	v_mfma_f32_16x16x32_bf16 v[52:55], v[148:151], v[188:191], v[52:55]
	v_mfma_f32_16x16x32_bf16 v[48:51], v[156:159], v[188:191], v[48:51]
	v_mfma_f32_16x16x32_bf16 v[36:39], v[148:151], v[196:199], v[36:39]
	v_mfma_f32_16x16x32_bf16 v[32:35], v[156:159], v[196:199], v[32:35]
	v_mfma_f32_16x16x32_bf16 v[20:23], v[148:151], v[204:207], v[20:23]
	v_mfma_f32_16x16x32_bf16 v[16:19], v[156:159], v[204:207], v[16:19]
	v_mfma_f32_16x16x32_bf16 v[44:47], v[160:163], v[176:179], v[44:47]
	v_mfma_f32_16x16x32_bf16 v[40:43], v[168:171], v[176:179], v[40:43]
	v_mfma_f32_16x16x32_bf16 v[28:31], v[160:163], v[184:187], v[28:31]
	v_mfma_f32_16x16x32_bf16 v[24:27], v[168:171], v[184:187], v[24:27]
	v_mfma_f32_16x16x32_bf16 v[12:15], v[160:163], v[192:195], v[12:15]
	v_mfma_f32_16x16x32_bf16 v[8:11], v[168:171], v[192:195], v[8:11]
	v_mfma_f32_16x16x32_bf16 v[4:7], v[160:163], v[200:203], v[4:7]
	v_mfma_f32_16x16x32_bf16 v[0:3], v[168:171], v[200:203], v[0:3]
	v_mfma_f32_16x16x32_bf16 v[44:47], v[164:167], v[180:183], v[44:47]
	v_mfma_f32_16x16x32_bf16 v[40:43], v[172:175], v[180:183], v[40:43]
	v_mfma_f32_16x16x32_bf16 v[28:31], v[164:167], v[188:191], v[28:31]
	v_mfma_f32_16x16x32_bf16 v[24:27], v[172:175], v[188:191], v[24:27]
	v_mfma_f32_16x16x32_bf16 v[12:15], v[164:167], v[196:199], v[12:15]
	v_mfma_f32_16x16x32_bf16 v[8:11], v[172:175], v[196:199], v[8:11]
	v_mfma_f32_16x16x32_bf16 v[4:7], v[164:167], v[204:207], v[4:7]
	v_mfma_f32_16x16x32_bf16 v[0:3], v[172:175], v[204:207], v[0:3]
	s_barrier
	s_add_i32 s74, 0, 0x18000
	s_add_i32 s75, 0, 0x1c000
	v_add_u32_e32 v156, s74, v140
	v_add_u32_e32 v172, s75, v140
	ds_read_b128 v[144:147], v156
	ds_read_b128 v[148:151], v156 offset:1024
	ds_read_b128 v[152:155], v156 offset:2048
	ds_read_b128 v[156:159], v156 offset:3072
	ds_read_b128 v[160:163], v172
	ds_read_b128 v[164:167], v172 offset:1024
	ds_read_b128 v[168:171], v172 offset:2048
	ds_read_b128 v[172:175], v172 offset:3072
	s_mov_b32 m0, s55
	v_lshl_add_u64 v[214:215], v[212:213], 0, s[8:9]
	ds_read_b128 v[176:179], v143 offset:32768
	ds_read_b128 v[180:183], v143 offset:33792
	ds_read_b128 v[184:187], v143 offset:34816
	ds_read_b128 v[188:191], v143 offset:35840
	ds_read_b128 v[192:195], v143 offset:36864
	ds_read_b128 v[196:199], v143 offset:37888
	ds_read_b128 v[200:203], v143 offset:38912
	ds_read_b128 v[204:207], v143 offset:39936
	global_load_lds_dwordx4 v[214:215], off
	v_lshl_add_u64 v[214:215], v[212:213], 0, s[14:15]
	s_mov_b32 m0, s56
	s_nop 0
	global_load_lds_dwordx4 v[214:215], off
	s_waitcnt vmcnt(8)
	s_waitcnt lgkmcnt(0)
	s_barrier
	s_waitcnt lgkmcnt(0)
	v_mfma_f32_16x16x32_bf16 v[124:127], v[144:147], v[176:179], v[124:127]
	v_mfma_f32_16x16x32_bf16 v[120:123], v[152:155], v[176:179], v[120:123]
	v_mfma_f32_16x16x32_bf16 v[116:119], v[144:147], v[184:187], v[116:119]
	v_mfma_f32_16x16x32_bf16 v[112:115], v[152:155], v[184:187], v[112:115]
	v_mfma_f32_16x16x32_bf16 v[100:103], v[144:147], v[192:195], v[100:103]
	v_mfma_f32_16x16x32_bf16 v[96:99], v[152:155], v[192:195], v[96:99]
	v_mfma_f32_16x16x32_bf16 v[84:87], v[144:147], v[200:203], v[84:87]
	v_mfma_f32_16x16x32_bf16 v[80:83], v[152:155], v[200:203], v[80:83]
	v_mfma_f32_16x16x32_bf16 v[124:127], v[148:151], v[180:183], v[124:127]
	v_mfma_f32_16x16x32_bf16 v[120:123], v[156:159], v[180:183], v[120:123]
	v_mfma_f32_16x16x32_bf16 v[116:119], v[148:151], v[188:191], v[116:119]
	v_mfma_f32_16x16x32_bf16 v[112:115], v[156:159], v[188:191], v[112:115]
	v_mfma_f32_16x16x32_bf16 v[100:103], v[148:151], v[196:199], v[100:103]
	v_mfma_f32_16x16x32_bf16 v[96:99], v[156:159], v[196:199], v[96:99]
	v_mfma_f32_16x16x32_bf16 v[84:87], v[148:151], v[204:207], v[84:87]
	v_mfma_f32_16x16x32_bf16 v[80:83], v[156:159], v[204:207], v[80:83]
	v_mfma_f32_16x16x32_bf16 v[108:111], v[160:163], v[176:179], v[108:111]
	v_mfma_f32_16x16x32_bf16 v[104:107], v[168:171], v[176:179], v[104:107]
	v_mfma_f32_16x16x32_bf16 v[92:95], v[160:163], v[184:187], v[92:95]
	v_mfma_f32_16x16x32_bf16 v[88:91], v[168:171], v[184:187], v[88:91]
	v_mfma_f32_16x16x32_bf16 v[76:79], v[160:163], v[192:195], v[76:79]
	v_mfma_f32_16x16x32_bf16 v[72:75], v[168:171], v[192:195], v[72:75]
	v_mfma_f32_16x16x32_bf16 v[68:71], v[160:163], v[200:203], v[68:71]
	v_mfma_f32_16x16x32_bf16 v[64:67], v[168:171], v[200:203], v[64:67]
	v_mfma_f32_16x16x32_bf16 v[108:111], v[164:167], v[180:183], v[108:111]
	v_mfma_f32_16x16x32_bf16 v[104:107], v[172:175], v[180:183], v[104:107]
	v_mfma_f32_16x16x32_bf16 v[92:95], v[164:167], v[188:191], v[92:95]
	v_mfma_f32_16x16x32_bf16 v[88:91], v[172:175], v[188:191], v[88:91]
	v_mfma_f32_16x16x32_bf16 v[76:79], v[164:167], v[196:199], v[76:79]
	v_mfma_f32_16x16x32_bf16 v[72:75], v[172:175], v[196:199], v[72:75]
	v_mfma_f32_16x16x32_bf16 v[68:71], v[164:167], v[204:207], v[68:71]
	v_mfma_f32_16x16x32_bf16 v[64:67], v[172:175], v[204:207], v[64:67]
	s_barrier
	s_add_i32 s74, s74, s52
	v_lshl_add_u64 v[214:215], v[208:209], 0, s[20:21]
	s_mov_b32 m0, s74
	ds_read_b128 v[176:179], v143 offset:49152
	ds_read_b128 v[180:183], v143 offset:50176
	ds_read_b128 v[184:187], v143 offset:51200
	ds_read_b128 v[188:191], v143 offset:52224
	ds_read_b128 v[192:195], v143 offset:53248
	ds_read_b128 v[196:199], v143 offset:54272
	ds_read_b128 v[200:203], v143 offset:55296
	ds_read_b128 v[204:207], v143 offset:56320
	global_load_lds_dwordx4 v[214:215], off
	v_lshl_add_u64 v[214:215], v[208:209], 0, s[22:23]
	s_add_i32 m0, s74, 0x2000
	s_add_i32 s74, s75, s52
	global_load_lds_dwordx4 v[214:215], off
	v_lshl_add_u64 v[214:215], v[208:209], 0, s[24:25]
	s_mov_b32 m0, s74
	v_lshl_add_u64 v[208:209], v[208:209], 0, s[26:27]
	global_load_lds_dwordx4 v[214:215], off
	s_add_i32 m0, s74, 0x2000
	s_nop 0
	global_load_lds_dwordx4 v[208:209], off
	v_lshl_add_u64 v[208:209], v[212:213], 0, s[20:21]
	s_mov_b32 m0, s58
	s_nop 0
	global_load_lds_dwordx4 v[208:209], off
	v_lshl_add_u64 v[208:209], v[212:213], 0, s[22:23]
	s_mov_b32 m0, s59
	s_nop 0
	global_load_lds_dwordx4 v[208:209], off
	s_waitcnt vmcnt(8)
	s_waitcnt lgkmcnt(0)
	s_barrier
	s_waitcnt lgkmcnt(0)
	v_mfma_f32_16x16x32_bf16 v[60:63], v[144:147], v[176:179], v[60:63]
	v_mfma_f32_16x16x32_bf16 v[56:59], v[152:155], v[176:179], v[56:59]
	v_mfma_f32_16x16x32_bf16 v[52:55], v[144:147], v[184:187], v[52:55]
	v_mfma_f32_16x16x32_bf16 v[48:51], v[152:155], v[184:187], v[48:51]
	v_mfma_f32_16x16x32_bf16 v[36:39], v[144:147], v[192:195], v[36:39]
	v_mfma_f32_16x16x32_bf16 v[32:35], v[152:155], v[192:195], v[32:35]
	v_mfma_f32_16x16x32_bf16 v[20:23], v[144:147], v[200:203], v[20:23]
	v_mfma_f32_16x16x32_bf16 v[16:19], v[152:155], v[200:203], v[16:19]
	v_mfma_f32_16x16x32_bf16 v[60:63], v[148:151], v[180:183], v[60:63]
	v_mfma_f32_16x16x32_bf16 v[56:59], v[156:159], v[180:183], v[56:59]
	v_mfma_f32_16x16x32_bf16 v[52:55], v[148:151], v[188:191], v[52:55]
	v_mfma_f32_16x16x32_bf16 v[48:51], v[156:159], v[188:191], v[48:51]
	v_mfma_f32_16x16x32_bf16 v[36:39], v[148:151], v[196:199], v[36:39]
	v_mfma_f32_16x16x32_bf16 v[32:35], v[156:159], v[196:199], v[32:35]
	v_mfma_f32_16x16x32_bf16 v[20:23], v[148:151], v[204:207], v[20:23]
	v_mfma_f32_16x16x32_bf16 v[16:19], v[156:159], v[204:207], v[16:19]
	v_mfma_f32_16x16x32_bf16 v[44:47], v[160:163], v[176:179], v[44:47]
	v_mfma_f32_16x16x32_bf16 v[40:43], v[168:171], v[176:179], v[40:43]
	v_mfma_f32_16x16x32_bf16 v[28:31], v[160:163], v[184:187], v[28:31]
	v_mfma_f32_16x16x32_bf16 v[24:27], v[168:171], v[184:187], v[24:27]
	v_mfma_f32_16x16x32_bf16 v[12:15], v[160:163], v[192:195], v[12:15]
	v_mfma_f32_16x16x32_bf16 v[8:11], v[168:171], v[192:195], v[8:11]
	v_mfma_f32_16x16x32_bf16 v[4:7], v[160:163], v[200:203], v[4:7]
	v_mfma_f32_16x16x32_bf16 v[0:3], v[168:171], v[200:203], v[0:3]
	v_mfma_f32_16x16x32_bf16 v[44:47], v[164:167], v[180:183], v[44:47]
	v_mfma_f32_16x16x32_bf16 v[40:43], v[172:175], v[180:183], v[40:43]
	v_mfma_f32_16x16x32_bf16 v[28:31], v[164:167], v[188:191], v[28:31]
	v_mfma_f32_16x16x32_bf16 v[24:27], v[172:175], v[188:191], v[24:27]
	v_mfma_f32_16x16x32_bf16 v[12:15], v[164:167], v[196:199], v[12:15]
	v_mfma_f32_16x16x32_bf16 v[8:11], v[172:175], v[196:199], v[8:11]
	v_mfma_f32_16x16x32_bf16 v[4:7], v[164:167], v[204:207], v[4:7]
	v_mfma_f32_16x16x32_bf16 v[0:3], v[172:175], v[204:207], v[0:3]
	s_barrier
	s_cmp_gt_u32 s73, 41
	s_cbranch_scc0 .LBB0_255
	s_and_b64 vcc, exec, s[28:29]
	s_cbranch_vccz .LBB0_258
	s_barrier

.LBB0_386:
	s_add_i32 s70, s70, 2
	s_mov_b32 s42, s70
	s_ashr_i32 s43, s42, 31
	s_lshl_b64 s[72:73], s[42:43], 7
	s_add_u32 s43, s72, 0x100
	s_addc_u32 s71, s73, 0
	s_add_u32 s79, s8, s43
	s_addc_u32 s80, s9, s71
	s_add_u32 s82, s2, s43
	s_addc_u32 s71, s3, s71
	s_add_i32 s83, 0, 0x10000
	s_cmp_eq_u32 s42, 14
	s_cselect_b32 s43, s1, s80
	s_cselect_b32 s42, s57, s79
	s_cselect_b32 s81, s68, s71
	s_cselect_b32 s80, s69, s82
	s_add_i32 s71, 0, 0x14000
	v_add_u32_e32 v140, s83, v220
	v_add_u32_e32 v156, s71, v220
	ds_read_b128 v[128:131], v140
	ds_read_b128 v[132:135], v140 offset:1024
	ds_read_b128 v[136:139], v140 offset:2048
	ds_read_b128 v[140:143], v140 offset:3072
	ds_read_b128 v[144:147], v156
	ds_read_b128 v[148:151], v156 offset:1024
	ds_read_b128 v[152:155], v156 offset:2048
	ds_read_b128 v[156:159], v156 offset:3072
	s_add_u32 s72, s8, s72
	s_addc_u32 s73, s9, s73
	v_lshl_add_u64 v[222:223], s[72:73], 0, v[182:183]
	v_lshl_add_u64 v[224:225], v[222:223], 0, s[14:15]
	s_add_i32 m0, s39, 0xc000
	ds_read_b128 v[160:163], v221
	ds_read_b128 v[164:167], v221 offset:1024
	ds_read_b128 v[186:189], v221 offset:2048
	ds_read_b128 v[190:193], v221 offset:3072
	ds_read_b128 v[194:197], v221 offset:4096
	ds_read_b128 v[198:201], v221 offset:5120
	ds_read_b128 v[202:205], v221 offset:6144
	ds_read_b128 v[206:209], v221 offset:7168
	global_load_lds_dwordx4 v[224:225], off
	v_lshl_add_u64 v[222:223], v[222:223], 0, s[16:17]
	s_add_i32 m0, s39, 0xe000
	s_nop 0
	global_load_lds_dwordx4 v[222:223], off
	s_waitcnt vmcnt(8)
	s_waitcnt lgkmcnt(0)
	s_barrier
	s_waitcnt lgkmcnt(0)
	v_mfma_f32_16x16x32_bf16 v[124:127], v[128:131], v[160:163], v[124:127]
	v_mfma_f32_16x16x32_bf16 v[120:123], v[136:139], v[160:163], v[120:123]
	v_mfma_f32_16x16x32_bf16 v[112:115], v[128:131], v[186:189], v[112:115]
	v_mfma_f32_16x16x32_bf16 v[104:107], v[136:139], v[186:189], v[104:107]
	v_mfma_f32_16x16x32_bf16 v[96:99], v[128:131], v[194:197], v[96:99]
	v_mfma_f32_16x16x32_bf16 v[88:91], v[136:139], v[194:197], v[88:91]
	v_mfma_f32_16x16x32_bf16 v[80:83], v[128:131], v[202:205], v[80:83]
	v_mfma_f32_16x16x32_bf16 v[72:75], v[136:139], v[202:205], v[72:75]
	v_mfma_f32_16x16x32_bf16 v[124:127], v[132:135], v[164:167], v[124:127]
	v_mfma_f32_16x16x32_bf16 v[120:123], v[140:143], v[164:167], v[120:123]
	v_mfma_f32_16x16x32_bf16 v[112:115], v[132:135], v[190:193], v[112:115]
	v_mfma_f32_16x16x32_bf16 v[104:107], v[140:143], v[190:193], v[104:107]
	v_mfma_f32_16x16x32_bf16 v[96:99], v[132:135], v[198:201], v[96:99]
	v_mfma_f32_16x16x32_bf16 v[88:91], v[140:143], v[198:201], v[88:91]
	v_mfma_f32_16x16x32_bf16 v[80:83], v[132:135], v[206:209], v[80:83]
	v_mfma_f32_16x16x32_bf16 v[72:75], v[140:143], v[206:209], v[72:75]
	v_mfma_f32_16x16x32_bf16 v[116:119], v[144:147], v[160:163], v[116:119]
	v_mfma_f32_16x16x32_bf16 v[108:111], v[152:155], v[160:163], v[108:111]
	v_mfma_f32_16x16x32_bf16 v[100:103], v[144:147], v[186:189], v[100:103]
	v_mfma_f32_16x16x32_bf16 v[92:95], v[152:155], v[186:189], v[92:95]
	v_mfma_f32_16x16x32_bf16 v[84:87], v[144:147], v[194:197], v[84:87]
	v_mfma_f32_16x16x32_bf16 v[76:79], v[152:155], v[194:197], v[76:79]
	v_mfma_f32_16x16x32_bf16 v[68:71], v[144:147], v[202:205], v[68:71]
	v_mfma_f32_16x16x32_bf16 v[64:67], v[152:155], v[202:205], v[64:67]
	v_mfma_f32_16x16x32_bf16 v[116:119], v[148:151], v[164:167], v[116:119]
	v_mfma_f32_16x16x32_bf16 v[108:111], v[156:159], v[164:167], v[108:111]
	v_mfma_f32_16x16x32_bf16 v[100:103], v[148:151], v[190:193], v[100:103]
	v_mfma_f32_16x16x32_bf16 v[92:95], v[156:159], v[190:193], v[92:95]
	v_mfma_f32_16x16x32_bf16 v[84:87], v[148:151], v[198:201], v[84:87]
	v_mfma_f32_16x16x32_bf16 v[76:79], v[156:159], v[198:201], v[76:79]
	v_mfma_f32_16x16x32_bf16 v[68:71], v[148:151], v[206:209], v[68:71]
	v_mfma_f32_16x16x32_bf16 v[64:67], v[156:159], v[206:209], v[64:67]
	s_barrier
	s_add_i32 s72, s83, s74
	v_lshl_add_u64 v[222:223], s[80:81], 0, v[184:185]
	s_mov_b32 m0, s72
	ds_read_b128 v[160:163], v221 offset:16384
	ds_read_b128 v[164:167], v221 offset:17408
	ds_read_b128 v[186:189], v221 offset:18432
	ds_read_b128 v[190:193], v221 offset:19456
	ds_read_b128 v[194:197], v221 offset:20480
	ds_read_b128 v[198:201], v221 offset:21504
	ds_read_b128 v[202:205], v221 offset:22528
	ds_read_b128 v[206:209], v221 offset:23552
	global_load_lds_dwordx4 v[222:223], off
	v_lshl_add_u64 v[224:225], v[222:223], 0, s[40:41]
	s_add_i32 m0, s72, 0x2000
	s_add_i32 s71, s71, s74
	global_load_lds_dwordx4 v[224:225], off
	v_lshl_add_u64 v[224:225], v[222:223], 0, s[4:5]
	s_mov_b32 m0, s71
	s_nop 0
	global_load_lds_dwordx4 v[224:225], off
	v_lshl_add_u64 v[224:225], v[222:223], 0, s[6:7]
	s_add_i32 m0, s71, 0x2000
	s_nop 0
	global_load_lds_dwordx4 v[224:225], off
	v_lshl_add_u64 v[224:225], s[42:43], 0, v[182:183]
	s_mov_b32 m0, s39
	v_lshl_add_u64 v[226:227], v[224:225], 0, s[40:41]
	global_load_lds_dwordx4 v[224:225], off
	s_mov_b32 m0, s75
	s_nop 0
	global_load_lds_dwordx4 v[226:227], off
	s_waitcnt vmcnt(8)
	s_waitcnt lgkmcnt(0)
	s_barrier
	s_waitcnt lgkmcnt(0)
	v_mfma_f32_16x16x32_bf16 v[60:63], v[128:131], v[160:163], v[60:63]
	v_mfma_f32_16x16x32_bf16 v[56:59], v[136:139], v[160:163], v[56:59]
	v_mfma_f32_16x16x32_bf16 v[48:51], v[128:131], v[186:189], v[48:51]
	v_mfma_f32_16x16x32_bf16 v[40:43], v[136:139], v[186:189], v[40:43]
	v_mfma_f32_16x16x32_bf16 v[32:35], v[128:131], v[194:197], v[32:35]
	v_mfma_f32_16x16x32_bf16 v[24:27], v[136:139], v[194:197], v[24:27]
	v_mfma_f32_16x16x32_bf16 v[16:19], v[128:131], v[202:205], v[16:19]
	v_mfma_f32_16x16x32_bf16 v[8:11], v[136:139], v[202:205], v[8:11]
	v_mfma_f32_16x16x32_bf16 v[60:63], v[132:135], v[164:167], v[60:63]
	v_mfma_f32_16x16x32_bf16 v[56:59], v[140:143], v[164:167], v[56:59]
	v_mfma_f32_16x16x32_bf16 v[48:51], v[132:135], v[190:193], v[48:51]
	v_mfma_f32_16x16x32_bf16 v[40:43], v[140:143], v[190:193], v[40:43]
	v_mfma_f32_16x16x32_bf16 v[32:35], v[132:135], v[198:201], v[32:35]
	v_mfma_f32_16x16x32_bf16 v[24:27], v[140:143], v[198:201], v[24:27]
	v_mfma_f32_16x16x32_bf16 v[16:19], v[132:135], v[206:209], v[16:19]
	v_mfma_f32_16x16x32_bf16 v[8:11], v[140:143], v[206:209], v[8:11]
	v_mfma_f32_16x16x32_bf16 v[52:55], v[144:147], v[160:163], v[52:55]
	v_mfma_f32_16x16x32_bf16 v[44:47], v[152:155], v[160:163], v[44:47]
	v_mfma_f32_16x16x32_bf16 v[36:39], v[144:147], v[186:189], v[36:39]
	v_mfma_f32_16x16x32_bf16 v[28:31], v[152:155], v[186:189], v[28:31]
	v_mfma_f32_16x16x32_bf16 v[20:23], v[144:147], v[194:197], v[20:23]
	v_mfma_f32_16x16x32_bf16 v[12:15], v[152:155], v[194:197], v[12:15]
	v_mfma_f32_16x16x32_bf16 v[4:7], v[144:147], v[202:205], v[4:7]
	v_mfma_f32_16x16x32_bf16 v[0:3], v[152:155], v[202:205], v[0:3]
	v_mfma_f32_16x16x32_bf16 v[52:55], v[148:151], v[164:167], v[52:55]
	v_mfma_f32_16x16x32_bf16 v[44:47], v[156:159], v[164:167], v[44:47]
	v_mfma_f32_16x16x32_bf16 v[36:39], v[148:151], v[190:193], v[36:39]
	v_mfma_f32_16x16x32_bf16 v[28:31], v[156:159], v[190:193], v[28:31]
	v_mfma_f32_16x16x32_bf16 v[20:23], v[148:151], v[198:201], v[20:23]
	v_mfma_f32_16x16x32_bf16 v[12:15], v[156:159], v[198:201], v[12:15]
	v_mfma_f32_16x16x32_bf16 v[4:7], v[148:151], v[206:209], v[4:7]
	v_mfma_f32_16x16x32_bf16 v[0:3], v[156:159], v[206:209], v[0:3]
	s_barrier
	s_add_i32 s42, 0, 0x18000
	s_add_i32 s43, 0, 0x1c000
	v_add_u32_e32 v140, s42, v220
	v_add_u32_e32 v156, s43, v220
	ds_read_b128 v[128:131], v140
	ds_read_b128 v[132:135], v140 offset:1024
	ds_read_b128 v[136:139], v140 offset:2048
	ds_read_b128 v[140:143], v140 offset:3072
	ds_read_b128 v[144:147], v156
	ds_read_b128 v[148:151], v156 offset:1024
	ds_read_b128 v[152:155], v156 offset:2048
	ds_read_b128 v[156:159], v156 offset:3072
	s_mov_b32 m0, s30
	v_lshl_add_u64 v[226:227], v[224:225], 0, s[4:5]
	ds_read_b128 v[160:163], v221 offset:32768
	ds_read_b128 v[164:167], v221 offset:33792
	ds_read_b128 v[186:189], v221 offset:34816
	ds_read_b128 v[190:193], v221 offset:35840
	ds_read_b128 v[194:197], v221 offset:36864
	ds_read_b128 v[198:201], v221 offset:37888
	ds_read_b128 v[202:205], v221 offset:38912
	ds_read_b128 v[206:209], v221 offset:39936
	global_load_lds_dwordx4 v[226:227], off
	v_lshl_add_u64 v[226:227], v[224:225], 0, s[6:7]
	s_mov_b32 m0, s31
	s_nop 0
	global_load_lds_dwordx4 v[226:227], off
	s_waitcnt vmcnt(8)
	s_waitcnt lgkmcnt(0)
	s_barrier
	s_waitcnt lgkmcnt(0)
	v_mfma_f32_16x16x32_bf16 v[124:127], v[128:131], v[160:163], v[124:127]
	v_mfma_f32_16x16x32_bf16 v[120:123], v[136:139], v[160:163], v[120:123]
	v_mfma_f32_16x16x32_bf16 v[112:115], v[128:131], v[186:189], v[112:115]
	v_mfma_f32_16x16x32_bf16 v[104:107], v[136:139], v[186:189], v[104:107]
	v_mfma_f32_16x16x32_bf16 v[96:99], v[128:131], v[194:197], v[96:99]
	v_mfma_f32_16x16x32_bf16 v[88:91], v[136:139], v[194:197], v[88:91]
	v_mfma_f32_16x16x32_bf16 v[80:83], v[128:131], v[202:205], v[80:83]
	v_mfma_f32_16x16x32_bf16 v[72:75], v[136:139], v[202:205], v[72:75]
	v_mfma_f32_16x16x32_bf16 v[124:127], v[132:135], v[164:167], v[124:127]
	v_mfma_f32_16x16x32_bf16 v[120:123], v[140:143], v[164:167], v[120:123]
	v_mfma_f32_16x16x32_bf16 v[112:115], v[132:135], v[190:193], v[112:115]
	v_mfma_f32_16x16x32_bf16 v[104:107], v[140:143], v[190:193], v[104:107]
	v_mfma_f32_16x16x32_bf16 v[96:99], v[132:135], v[198:201], v[96:99]
	v_mfma_f32_16x16x32_bf16 v[88:91], v[140:143], v[198:201], v[88:91]
	v_mfma_f32_16x16x32_bf16 v[80:83], v[132:135], v[206:209], v[80:83]
	v_mfma_f32_16x16x32_bf16 v[72:75], v[140:143], v[206:209], v[72:75]
	v_mfma_f32_16x16x32_bf16 v[116:119], v[144:147], v[160:163], v[116:119]
	v_mfma_f32_16x16x32_bf16 v[108:111], v[152:155], v[160:163], v[108:111]
	v_mfma_f32_16x16x32_bf16 v[100:103], v[144:147], v[186:189], v[100:103]
	v_mfma_f32_16x16x32_bf16 v[92:95], v[152:155], v[186:189], v[92:95]
	v_mfma_f32_16x16x32_bf16 v[84:87], v[144:147], v[194:197], v[84:87]
	v_mfma_f32_16x16x32_bf16 v[76:79], v[152:155], v[194:197], v[76:79]
	v_mfma_f32_16x16x32_bf16 v[68:71], v[144:147], v[202:205], v[68:71]
	v_mfma_f32_16x16x32_bf16 v[64:67], v[152:155], v[202:205], v[64:67]
	v_mfma_f32_16x16x32_bf16 v[116:119], v[148:151], v[164:167], v[116:119]
	v_mfma_f32_16x16x32_bf16 v[108:111], v[156:159], v[164:167], v[108:111]
	v_mfma_f32_16x16x32_bf16 v[100:103], v[148:151], v[190:193], v[100:103]
	v_mfma_f32_16x16x32_bf16 v[92:95], v[156:159], v[190:193], v[92:95]
	v_mfma_f32_16x16x32_bf16 v[84:87], v[148:151], v[198:201], v[84:87]
	v_mfma_f32_16x16x32_bf16 v[76:79], v[156:159], v[198:201], v[76:79]
	v_mfma_f32_16x16x32_bf16 v[68:71], v[148:151], v[206:209], v[68:71]
	v_mfma_f32_16x16x32_bf16 v[64:67], v[156:159], v[206:209], v[64:67]
	s_barrier
	s_add_i32 s42, s42, s74
	v_lshl_add_u64 v[226:227], v[222:223], 0, s[10:11]
	s_mov_b32 m0, s42
	ds_read_b128 v[160:163], v221 offset:49152
	ds_read_b128 v[164:167], v221 offset:50176
	ds_read_b128 v[186:189], v221 offset:51200
	ds_read_b128 v[190:193], v221 offset:52224
	ds_read_b128 v[194:197], v221 offset:53248
	ds_read_b128 v[198:201], v221 offset:54272
	ds_read_b128 v[202:205], v221 offset:55296
	ds_read_b128 v[206:209], v221 offset:56320
	global_load_lds_dwordx4 v[226:227], off
	v_lshl_add_u64 v[226:227], v[222:223], 0, s[12:13]
	s_add_i32 m0, s42, 0x2000
	s_add_i32 s42, s43, s74
	global_load_lds_dwordx4 v[226:227], off
	v_lshl_add_u64 v[226:227], v[222:223], 0, s[14:15]
	s_mov_b32 m0, s42
	v_lshl_add_u64 v[222:223], v[222:223], 0, s[16:17]
	global_load_lds_dwordx4 v[226:227], off
	s_add_i32 m0, s42, 0x2000
	s_nop 0
	global_load_lds_dwordx4 v[222:223], off
	v_lshl_add_u64 v[222:223], v[224:225], 0, s[10:11]
	s_mov_b32 m0, s26
	s_nop 0
	global_load_lds_dwordx4 v[222:223], off
	v_lshl_add_u64 v[222:223], v[224:225], 0, s[12:13]
	s_mov_b32 m0, s27
	s_nop 0
	global_load_lds_dwordx4 v[222:223], off
	s_waitcnt vmcnt(8)
	s_waitcnt lgkmcnt(0)
	s_barrier
	s_waitcnt lgkmcnt(0)
	v_mfma_f32_16x16x32_bf16 v[60:63], v[128:131], v[160:163], v[60:63]
	v_mfma_f32_16x16x32_bf16 v[56:59], v[136:139], v[160:163], v[56:59]
	v_mfma_f32_16x16x32_bf16 v[48:51], v[128:131], v[186:189], v[48:51]
	v_mfma_f32_16x16x32_bf16 v[40:43], v[136:139], v[186:189], v[40:43]
	v_mfma_f32_16x16x32_bf16 v[32:35], v[128:131], v[194:197], v[32:35]
	v_mfma_f32_16x16x32_bf16 v[24:27], v[136:139], v[194:197], v[24:27]
	v_mfma_f32_16x16x32_bf16 v[16:19], v[128:131], v[202:205], v[16:19]
	v_mfma_f32_16x16x32_bf16 v[8:11], v[136:139], v[202:205], v[8:11]
	v_mfma_f32_16x16x32_bf16 v[60:63], v[132:135], v[164:167], v[60:63]
	v_mfma_f32_16x16x32_bf16 v[56:59], v[140:143], v[164:167], v[56:59]
	v_mfma_f32_16x16x32_bf16 v[48:51], v[132:135], v[190:193], v[48:51]
	v_mfma_f32_16x16x32_bf16 v[40:43], v[140:143], v[190:193], v[40:43]
	v_mfma_f32_16x16x32_bf16 v[32:35], v[132:135], v[198:201], v[32:35]
	v_mfma_f32_16x16x32_bf16 v[24:27], v[140:143], v[198:201], v[24:27]
	v_mfma_f32_16x16x32_bf16 v[16:19], v[132:135], v[206:209], v[16:19]
	v_mfma_f32_16x16x32_bf16 v[8:11], v[140:143], v[206:209], v[8:11]
	v_mfma_f32_16x16x32_bf16 v[52:55], v[144:147], v[160:163], v[52:55]
	v_mfma_f32_16x16x32_bf16 v[44:47], v[152:155], v[160:163], v[44:47]
	v_mfma_f32_16x16x32_bf16 v[36:39], v[144:147], v[186:189], v[36:39]
	v_mfma_f32_16x16x32_bf16 v[28:31], v[152:155], v[186:189], v[28:31]
	v_mfma_f32_16x16x32_bf16 v[20:23], v[144:147], v[194:197], v[20:23]
	v_mfma_f32_16x16x32_bf16 v[12:15], v[152:155], v[194:197], v[12:15]
	v_mfma_f32_16x16x32_bf16 v[4:7], v[144:147], v[202:205], v[4:7]
	v_mfma_f32_16x16x32_bf16 v[0:3], v[152:155], v[202:205], v[0:3]
	v_mfma_f32_16x16x32_bf16 v[52:55], v[148:151], v[164:167], v[52:55]
	v_mfma_f32_16x16x32_bf16 v[44:47], v[156:159], v[164:167], v[44:47]
	v_mfma_f32_16x16x32_bf16 v[36:39], v[148:151], v[190:193], v[36:39]
	v_mfma_f32_16x16x32_bf16 v[28:31], v[156:159], v[190:193], v[28:31]
	v_mfma_f32_16x16x32_bf16 v[20:23], v[148:151], v[198:201], v[20:23]
	v_mfma_f32_16x16x32_bf16 v[12:15], v[156:159], v[198:201], v[12:15]
	v_mfma_f32_16x16x32_bf16 v[4:7], v[148:151], v[206:209], v[4:7]
	v_mfma_f32_16x16x32_bf16 v[0:3], v[156:159], v[206:209], v[0:3]
	s_barrier
	s_cmp_gt_u32 s70, 13
	s_cbranch_scc0 .LBB0_386
	s_and_b64 vcc, exec, s[58:59]
	s_cbranch_vccz .LBB0_389
	s_barrier

.LBB0_760:
	s_add_i32 s78, s78, 2
	s_mov_b32 s50, s78
	s_ashr_i32 s51, s50, 31
	s_lshl_b64 s[80:81], s[50:51], 7
	s_add_u32 s51, s80, 0x100
	s_addc_u32 s79, s81, 0
	s_add_u32 s82, s48, s51
	s_addc_u32 s83, s49, s79
	s_add_u32 s84, s8, s51
	s_addc_u32 s79, s9, s79
	s_add_i32 s85, 0, 0x10000
	s_cmp_eq_u32 s50, 14
	s_cselect_b32 s51, s35, s83
	s_cselect_b32 s50, s76, s82
	v_add_u32_e32 v134, s85, v137
	s_cselect_b32 s83, s31, s79
	s_cselect_b32 s82, s77, s84
	s_add_i32 s79, 0, 0x14000
	ds_read_b128 v[130:133], v134
	ds_read_b128 v[140:143], v134 offset:1024
	ds_read_b128 v[144:147], v134 offset:2048
	ds_read_b128 v[148:151], v134 offset:3072
	v_add_u32_e32 v134, s79, v137
	ds_read_b128 v[152:155], v134
	ds_read_b128 v[156:159], v134 offset:1024
	ds_read_b128 v[160:163], v134 offset:2048
	ds_read_b128 v[164:167], v134 offset:3072
	s_add_u32 s80, s48, s80
	s_addc_u32 s81, s49, s81
	v_lshl_add_u64 v[134:135], s[80:81], 0, v[128:129]
	v_lshl_add_u64 v[224:225], v[134:135], 0, s[14:15]
	s_add_i32 m0, s62, 0xc000
	ds_read_b128 v[182:185], v138
	ds_read_b128 v[186:189], v138 offset:1024
	ds_read_b128 v[190:193], v138 offset:2048
	ds_read_b128 v[194:197], v138 offset:3072
	ds_read_b128 v[198:201], v138 offset:4096
	ds_read_b128 v[202:205], v138 offset:5120
	ds_read_b128 v[206:209], v138 offset:6144
	ds_read_b128 v[220:223], v138 offset:7168
	global_load_lds_dwordx4 v[224:225], off
	v_lshl_add_u64 v[134:135], v[134:135], 0, s[16:17]
	s_add_i32 m0, s62, 0xe000
	s_nop 0
	global_load_lds_dwordx4 v[134:135], off
	s_waitcnt vmcnt(8)
	s_waitcnt lgkmcnt(0)
	s_barrier
	s_waitcnt lgkmcnt(0)
	v_mfma_f32_16x16x32_bf16 v[124:127], v[130:133], v[182:185], v[124:127]
	v_mfma_f32_16x16x32_bf16 v[120:123], v[144:147], v[182:185], v[120:123]
	v_mfma_f32_16x16x32_bf16 v[108:111], v[130:133], v[190:193], v[108:111]
	v_mfma_f32_16x16x32_bf16 v[104:107], v[144:147], v[190:193], v[104:107]
	v_mfma_f32_16x16x32_bf16 v[92:95], v[130:133], v[198:201], v[92:95]
	v_mfma_f32_16x16x32_bf16 v[88:91], v[144:147], v[198:201], v[88:91]
	v_mfma_f32_16x16x32_bf16 v[76:79], v[130:133], v[206:209], v[76:79]
	v_mfma_f32_16x16x32_bf16 v[72:75], v[144:147], v[206:209], v[72:75]
	v_mfma_f32_16x16x32_bf16 v[124:127], v[140:143], v[186:189], v[124:127]
	v_mfma_f32_16x16x32_bf16 v[120:123], v[148:151], v[186:189], v[120:123]
	v_mfma_f32_16x16x32_bf16 v[108:111], v[140:143], v[194:197], v[108:111]
	v_mfma_f32_16x16x32_bf16 v[104:107], v[148:151], v[194:197], v[104:107]
	v_mfma_f32_16x16x32_bf16 v[92:95], v[140:143], v[202:205], v[92:95]
	v_mfma_f32_16x16x32_bf16 v[88:91], v[148:151], v[202:205], v[88:91]
	v_mfma_f32_16x16x32_bf16 v[76:79], v[140:143], v[220:223], v[76:79]
	v_mfma_f32_16x16x32_bf16 v[72:75], v[148:151], v[220:223], v[72:75]
	v_mfma_f32_16x16x32_bf16 v[116:119], v[152:155], v[182:185], v[116:119]
	v_mfma_f32_16x16x32_bf16 v[112:115], v[160:163], v[182:185], v[112:115]
	v_mfma_f32_16x16x32_bf16 v[100:103], v[152:155], v[190:193], v[100:103]
	v_mfma_f32_16x16x32_bf16 v[96:99], v[160:163], v[190:193], v[96:99]
	v_mfma_f32_16x16x32_bf16 v[84:87], v[152:155], v[198:201], v[84:87]
	v_mfma_f32_16x16x32_bf16 v[80:83], v[160:163], v[198:201], v[80:83]
	v_mfma_f32_16x16x32_bf16 v[68:71], v[152:155], v[206:209], v[68:71]
	v_mfma_f32_16x16x32_bf16 v[64:67], v[160:163], v[206:209], v[64:67]
	v_mfma_f32_16x16x32_bf16 v[116:119], v[156:159], v[186:189], v[116:119]
	v_mfma_f32_16x16x32_bf16 v[112:115], v[164:167], v[186:189], v[112:115]
	v_mfma_f32_16x16x32_bf16 v[100:103], v[156:159], v[194:197], v[100:103]
	v_mfma_f32_16x16x32_bf16 v[96:99], v[164:167], v[194:197], v[96:99]
	v_mfma_f32_16x16x32_bf16 v[84:87], v[156:159], v[202:205], v[84:87]
	v_mfma_f32_16x16x32_bf16 v[80:83], v[164:167], v[202:205], v[80:83]
	v_mfma_f32_16x16x32_bf16 v[68:71], v[156:159], v[220:223], v[68:71]
	v_mfma_f32_16x16x32_bf16 v[64:67], v[164:167], v[220:223], v[64:67]
	s_barrier
	s_add_i32 s80, s85, s59
	v_lshl_add_u64 v[134:135], s[82:83], 0, v[172:173]
	s_mov_b32 m0, s80
	ds_read_b128 v[182:185], v138 offset:16384
	ds_read_b128 v[186:189], v138 offset:17408
	ds_read_b128 v[190:193], v138 offset:18432
	ds_read_b128 v[194:197], v138 offset:19456
	ds_read_b128 v[198:201], v138 offset:20480
	ds_read_b128 v[202:205], v138 offset:21504
	ds_read_b128 v[206:209], v138 offset:22528
	ds_read_b128 v[220:223], v138 offset:23552
	global_load_lds_dwordx4 v[134:135], off
	v_lshl_add_u64 v[224:225], v[134:135], 0, s[40:41]
	s_add_i32 m0, s80, 0x2000
	s_add_i32 s79, s79, s59
	global_load_lds_dwordx4 v[224:225], off
	v_lshl_add_u64 v[224:225], v[134:135], 0, s[4:5]
	s_mov_b32 m0, s79
	s_nop 0
	global_load_lds_dwordx4 v[224:225], off
	v_lshl_add_u64 v[224:225], v[134:135], 0, s[6:7]
	s_add_i32 m0, s79, 0x2000
	s_nop 0
	global_load_lds_dwordx4 v[224:225], off
	v_lshl_add_u64 v[224:225], s[50:51], 0, v[128:129]
	s_mov_b32 m0, s62
	v_lshl_add_u64 v[226:227], v[224:225], 0, s[40:41]
	global_load_lds_dwordx4 v[224:225], off
	s_mov_b32 m0, s63
	s_nop 0
	global_load_lds_dwordx4 v[226:227], off
	s_waitcnt vmcnt(8)
	s_waitcnt lgkmcnt(0)
	s_barrier
	s_waitcnt lgkmcnt(0)
	v_mfma_f32_16x16x32_bf16 v[60:63], v[130:133], v[182:185], v[60:63]
	v_mfma_f32_16x16x32_bf16 v[56:59], v[144:147], v[182:185], v[56:59]
	v_mfma_f32_16x16x32_bf16 v[44:47], v[130:133], v[190:193], v[44:47]
	v_mfma_f32_16x16x32_bf16 v[40:43], v[144:147], v[190:193], v[40:43]
	v_mfma_f32_16x16x32_bf16 v[28:31], v[130:133], v[198:201], v[28:31]
	v_mfma_f32_16x16x32_bf16 v[24:27], v[144:147], v[198:201], v[24:27]
	v_mfma_f32_16x16x32_bf16 v[12:15], v[130:133], v[206:209], v[12:15]
	v_mfma_f32_16x16x32_bf16 v[8:11], v[144:147], v[206:209], v[8:11]
	v_mfma_f32_16x16x32_bf16 v[60:63], v[140:143], v[186:189], v[60:63]
	v_mfma_f32_16x16x32_bf16 v[56:59], v[148:151], v[186:189], v[56:59]
	v_mfma_f32_16x16x32_bf16 v[44:47], v[140:143], v[194:197], v[44:47]
	v_mfma_f32_16x16x32_bf16 v[40:43], v[148:151], v[194:197], v[40:43]
	v_mfma_f32_16x16x32_bf16 v[28:31], v[140:143], v[202:205], v[28:31]
	v_mfma_f32_16x16x32_bf16 v[24:27], v[148:151], v[202:205], v[24:27]
	v_mfma_f32_16x16x32_bf16 v[12:15], v[140:143], v[220:223], v[12:15]
	v_mfma_f32_16x16x32_bf16 v[8:11], v[148:151], v[220:223], v[8:11]
	v_mfma_f32_16x16x32_bf16 v[52:55], v[152:155], v[182:185], v[52:55]
	v_mfma_f32_16x16x32_bf16 v[48:51], v[160:163], v[182:185], v[48:51]
	v_mfma_f32_16x16x32_bf16 v[36:39], v[152:155], v[190:193], v[36:39]
	v_mfma_f32_16x16x32_bf16 v[32:35], v[160:163], v[190:193], v[32:35]
	v_mfma_f32_16x16x32_bf16 v[20:23], v[152:155], v[198:201], v[20:23]
	v_mfma_f32_16x16x32_bf16 v[16:19], v[160:163], v[198:201], v[16:19]
	v_mfma_f32_16x16x32_bf16 v[4:7], v[152:155], v[206:209], v[4:7]
	v_mfma_f32_16x16x32_bf16 v[0:3], v[160:163], v[206:209], v[0:3]
	v_mfma_f32_16x16x32_bf16 v[52:55], v[156:159], v[186:189], v[52:55]
	v_mfma_f32_16x16x32_bf16 v[48:51], v[164:167], v[186:189], v[48:51]
	v_mfma_f32_16x16x32_bf16 v[36:39], v[156:159], v[194:197], v[36:39]
	v_mfma_f32_16x16x32_bf16 v[32:35], v[164:167], v[194:197], v[32:35]
	v_mfma_f32_16x16x32_bf16 v[20:23], v[156:159], v[202:205], v[20:23]
	v_mfma_f32_16x16x32_bf16 v[16:19], v[164:167], v[202:205], v[16:19]
	v_mfma_f32_16x16x32_bf16 v[4:7], v[156:159], v[220:223], v[4:7]
	v_mfma_f32_16x16x32_bf16 v[0:3], v[164:167], v[220:223], v[0:3]
	s_barrier
	s_add_i32 s50, 0, 0x18000
	v_add_u32_e32 v139, s50, v137
	s_add_i32 s51, 0, 0x1c000
	ds_read_b128 v[130:133], v139
	ds_read_b128 v[140:143], v139 offset:1024
	ds_read_b128 v[144:147], v139 offset:2048
	ds_read_b128 v[148:151], v139 offset:3072
	v_add_u32_e32 v139, s51, v137
	ds_read_b128 v[152:155], v139
	ds_read_b128 v[156:159], v139 offset:1024
	ds_read_b128 v[160:163], v139 offset:2048
	ds_read_b128 v[164:167], v139 offset:3072
	s_mov_b32 m0, s68
	v_lshl_add_u64 v[226:227], v[224:225], 0, s[4:5]
	ds_read_b128 v[182:185], v138 offset:32768
	ds_read_b128 v[186:189], v138 offset:33792
	ds_read_b128 v[190:193], v138 offset:34816
	ds_read_b128 v[194:197], v138 offset:35840
	ds_read_b128 v[198:201], v138 offset:36864
	ds_read_b128 v[202:205], v138 offset:37888
	ds_read_b128 v[206:209], v138 offset:38912
	ds_read_b128 v[220:223], v138 offset:39936
	global_load_lds_dwordx4 v[226:227], off
	v_lshl_add_u64 v[226:227], v[224:225], 0, s[6:7]
	s_mov_b32 m0, s69
	s_nop 0
	global_load_lds_dwordx4 v[226:227], off
	s_waitcnt vmcnt(8)
	s_waitcnt lgkmcnt(0)
	s_barrier
	s_waitcnt lgkmcnt(0)
	v_mfma_f32_16x16x32_bf16 v[124:127], v[130:133], v[182:185], v[124:127]
	v_mfma_f32_16x16x32_bf16 v[120:123], v[144:147], v[182:185], v[120:123]
	v_mfma_f32_16x16x32_bf16 v[108:111], v[130:133], v[190:193], v[108:111]
	v_mfma_f32_16x16x32_bf16 v[104:107], v[144:147], v[190:193], v[104:107]
	v_mfma_f32_16x16x32_bf16 v[92:95], v[130:133], v[198:201], v[92:95]
	v_mfma_f32_16x16x32_bf16 v[88:91], v[144:147], v[198:201], v[88:91]
	v_mfma_f32_16x16x32_bf16 v[76:79], v[130:133], v[206:209], v[76:79]
	v_mfma_f32_16x16x32_bf16 v[72:75], v[144:147], v[206:209], v[72:75]
	v_mfma_f32_16x16x32_bf16 v[124:127], v[140:143], v[186:189], v[124:127]
	v_mfma_f32_16x16x32_bf16 v[120:123], v[148:151], v[186:189], v[120:123]
	v_mfma_f32_16x16x32_bf16 v[108:111], v[140:143], v[194:197], v[108:111]
	v_mfma_f32_16x16x32_bf16 v[104:107], v[148:151], v[194:197], v[104:107]
	v_mfma_f32_16x16x32_bf16 v[92:95], v[140:143], v[202:205], v[92:95]
	v_mfma_f32_16x16x32_bf16 v[88:91], v[148:151], v[202:205], v[88:91]
	v_mfma_f32_16x16x32_bf16 v[76:79], v[140:143], v[220:223], v[76:79]
	v_mfma_f32_16x16x32_bf16 v[72:75], v[148:151], v[220:223], v[72:75]
	v_mfma_f32_16x16x32_bf16 v[116:119], v[152:155], v[182:185], v[116:119]
	v_mfma_f32_16x16x32_bf16 v[112:115], v[160:163], v[182:185], v[112:115]
	v_mfma_f32_16x16x32_bf16 v[100:103], v[152:155], v[190:193], v[100:103]
	v_mfma_f32_16x16x32_bf16 v[96:99], v[160:163], v[190:193], v[96:99]
	v_mfma_f32_16x16x32_bf16 v[84:87], v[152:155], v[198:201], v[84:87]
	v_mfma_f32_16x16x32_bf16 v[80:83], v[160:163], v[198:201], v[80:83]
	v_mfma_f32_16x16x32_bf16 v[68:71], v[152:155], v[206:209], v[68:71]
	v_mfma_f32_16x16x32_bf16 v[64:67], v[160:163], v[206:209], v[64:67]
	v_mfma_f32_16x16x32_bf16 v[116:119], v[156:159], v[186:189], v[116:119]
	v_mfma_f32_16x16x32_bf16 v[112:115], v[164:167], v[186:189], v[112:115]
	v_mfma_f32_16x16x32_bf16 v[100:103], v[156:159], v[194:197], v[100:103]
	v_mfma_f32_16x16x32_bf16 v[96:99], v[164:167], v[194:197], v[96:99]
	v_mfma_f32_16x16x32_bf16 v[84:87], v[156:159], v[202:205], v[84:87]
	v_mfma_f32_16x16x32_bf16 v[80:83], v[164:167], v[202:205], v[80:83]
	v_mfma_f32_16x16x32_bf16 v[68:71], v[156:159], v[220:223], v[68:71]
	v_mfma_f32_16x16x32_bf16 v[64:67], v[164:167], v[220:223], v[64:67]
	s_barrier
	s_add_i32 s50, s50, s59
	v_lshl_add_u64 v[226:227], v[134:135], 0, s[10:11]
	s_mov_b32 m0, s50
	ds_read_b128 v[182:185], v138 offset:49152
	ds_read_b128 v[186:189], v138 offset:50176
	ds_read_b128 v[190:193], v138 offset:51200
	ds_read_b128 v[194:197], v138 offset:52224
	ds_read_b128 v[198:201], v138 offset:53248
	ds_read_b128 v[202:205], v138 offset:54272
	ds_read_b128 v[206:209], v138 offset:55296
	ds_read_b128 v[220:223], v138 offset:56320
	global_load_lds_dwordx4 v[226:227], off
	v_lshl_add_u64 v[226:227], v[134:135], 0, s[12:13]
	s_add_i32 m0, s50, 0x2000
	s_add_i32 s50, s51, s59
	global_load_lds_dwordx4 v[226:227], off
	v_lshl_add_u64 v[226:227], v[134:135], 0, s[14:15]
	s_mov_b32 m0, s50
	v_lshl_add_u64 v[134:135], v[134:135], 0, s[16:17]
	global_load_lds_dwordx4 v[226:227], off
	s_add_i32 m0, s50, 0x2000
	s_nop 0
	global_load_lds_dwordx4 v[134:135], off
	v_lshl_add_u64 v[134:135], v[224:225], 0, s[10:11]
	s_mov_b32 m0, s72
	s_nop 0
	global_load_lds_dwordx4 v[134:135], off
	v_lshl_add_u64 v[134:135], v[224:225], 0, s[12:13]
	s_mov_b32 m0, s73
	s_nop 0
	global_load_lds_dwordx4 v[134:135], off
	s_waitcnt vmcnt(8)
	s_waitcnt lgkmcnt(0)
	s_barrier
	s_waitcnt lgkmcnt(0)
	v_mfma_f32_16x16x32_bf16 v[60:63], v[130:133], v[182:185], v[60:63]
	v_mfma_f32_16x16x32_bf16 v[56:59], v[144:147], v[182:185], v[56:59]
	v_mfma_f32_16x16x32_bf16 v[44:47], v[130:133], v[190:193], v[44:47]
	v_mfma_f32_16x16x32_bf16 v[40:43], v[144:147], v[190:193], v[40:43]
	v_mfma_f32_16x16x32_bf16 v[28:31], v[130:133], v[198:201], v[28:31]
	v_mfma_f32_16x16x32_bf16 v[24:27], v[144:147], v[198:201], v[24:27]
	v_mfma_f32_16x16x32_bf16 v[12:15], v[130:133], v[206:209], v[12:15]
	v_mfma_f32_16x16x32_bf16 v[8:11], v[144:147], v[206:209], v[8:11]
	v_mfma_f32_16x16x32_bf16 v[60:63], v[140:143], v[186:189], v[60:63]
	v_mfma_f32_16x16x32_bf16 v[56:59], v[148:151], v[186:189], v[56:59]
	v_mfma_f32_16x16x32_bf16 v[44:47], v[140:143], v[194:197], v[44:47]
	v_mfma_f32_16x16x32_bf16 v[40:43], v[148:151], v[194:197], v[40:43]
	v_mfma_f32_16x16x32_bf16 v[28:31], v[140:143], v[202:205], v[28:31]
	v_mfma_f32_16x16x32_bf16 v[24:27], v[148:151], v[202:205], v[24:27]
	v_mfma_f32_16x16x32_bf16 v[12:15], v[140:143], v[220:223], v[12:15]
	v_mfma_f32_16x16x32_bf16 v[8:11], v[148:151], v[220:223], v[8:11]
	v_mfma_f32_16x16x32_bf16 v[52:55], v[152:155], v[182:185], v[52:55]
	v_mfma_f32_16x16x32_bf16 v[48:51], v[160:163], v[182:185], v[48:51]
	v_mfma_f32_16x16x32_bf16 v[36:39], v[152:155], v[190:193], v[36:39]
	v_mfma_f32_16x16x32_bf16 v[32:35], v[160:163], v[190:193], v[32:35]
	v_mfma_f32_16x16x32_bf16 v[20:23], v[152:155], v[198:201], v[20:23]
	v_mfma_f32_16x16x32_bf16 v[16:19], v[160:163], v[198:201], v[16:19]
	v_mfma_f32_16x16x32_bf16 v[4:7], v[152:155], v[206:209], v[4:7]
	v_mfma_f32_16x16x32_bf16 v[0:3], v[160:163], v[206:209], v[0:3]
	v_mfma_f32_16x16x32_bf16 v[52:55], v[156:159], v[186:189], v[52:55]
	v_mfma_f32_16x16x32_bf16 v[48:51], v[164:167], v[186:189], v[48:51]
	v_mfma_f32_16x16x32_bf16 v[36:39], v[156:159], v[194:197], v[36:39]
	v_mfma_f32_16x16x32_bf16 v[32:35], v[164:167], v[194:197], v[32:35]
	v_mfma_f32_16x16x32_bf16 v[20:23], v[156:159], v[202:205], v[20:23]
	v_mfma_f32_16x16x32_bf16 v[16:19], v[164:167], v[202:205], v[16:19]
	v_mfma_f32_16x16x32_bf16 v[4:7], v[156:159], v[220:223], v[4:7]
	v_mfma_f32_16x16x32_bf16 v[0:3], v[164:167], v[220:223], v[0:3]
	s_barrier
	s_cmp_gt_u32 s78, 13
	s_cbranch_scc0 .LBB0_760
	s_and_b64 vcc, exec, s[28:29]
	s_cbranch_vccz .LBB0_763
	s_barrier

.LBB0_784:
	s_add_i32 s80, s80, 2
	s_mov_b32 s48, s80
	s_ashr_i32 s49, s48, 31
	s_lshl_b64 s[82:83], s[48:49], 7
	s_add_u32 s49, s82, 0x100
	s_addc_u32 s81, s83, 0
	s_add_u32 s84, s42, s49
	s_addc_u32 s85, s43, s81
	s_add_u32 s86, s8, s49
	s_addc_u32 s81, s9, s81
	s_add_i32 s87, 0, 0x10000
	s_cmp_eq_u32 s48, 14
	s_cselect_b32 s49, s39, s85
	s_cselect_b32 s48, s72, s84
	v_add_u32_e32 v134, s87, v137
	s_cselect_b32 s85, s35, s81
	s_cselect_b32 s84, s73, s86
	s_add_i32 s81, 0, 0x14000
	ds_read_b128 v[130:133], v134
	ds_read_b128 v[140:143], v134 offset:1024
	ds_read_b128 v[144:147], v134 offset:2048
	ds_read_b128 v[148:151], v134 offset:3072
	v_add_u32_e32 v134, s81, v137
	ds_read_b128 v[152:155], v134
	ds_read_b128 v[156:159], v134 offset:1024
	ds_read_b128 v[160:163], v134 offset:2048
	ds_read_b128 v[164:167], v134 offset:3072
	s_add_u32 s82, s42, s82
	s_addc_u32 s83, s43, s83
	v_lshl_add_u64 v[134:135], s[82:83], 0, v[128:129]
	v_lshl_add_u64 v[224:225], v[134:135], 0, s[14:15]
	s_add_i32 m0, s74, 0xc000
	ds_read_b128 v[182:185], v138
	ds_read_b128 v[186:189], v138 offset:1024
	ds_read_b128 v[190:193], v138 offset:2048
	ds_read_b128 v[194:197], v138 offset:3072
	ds_read_b128 v[198:201], v138 offset:4096
	ds_read_b128 v[202:205], v138 offset:5120
	ds_read_b128 v[206:209], v138 offset:6144
	ds_read_b128 v[220:223], v138 offset:7168
	global_load_lds_dwordx4 v[224:225], off
	v_lshl_add_u64 v[134:135], v[134:135], 0, s[16:17]
	s_add_i32 m0, s74, 0xe000
	s_nop 0
	global_load_lds_dwordx4 v[134:135], off
	s_waitcnt vmcnt(8)
	s_waitcnt lgkmcnt(0)
	s_barrier
	s_waitcnt lgkmcnt(0)
	v_mfma_f32_16x16x32_bf16 v[124:127], v[130:133], v[182:185], v[124:127]
	v_mfma_f32_16x16x32_bf16 v[120:123], v[144:147], v[182:185], v[120:123]
	v_mfma_f32_16x16x32_bf16 v[108:111], v[130:133], v[190:193], v[108:111]
	v_mfma_f32_16x16x32_bf16 v[104:107], v[144:147], v[190:193], v[104:107]
	v_mfma_f32_16x16x32_bf16 v[92:95], v[130:133], v[198:201], v[92:95]
	v_mfma_f32_16x16x32_bf16 v[88:91], v[144:147], v[198:201], v[88:91]
	v_mfma_f32_16x16x32_bf16 v[76:79], v[130:133], v[206:209], v[76:79]
	v_mfma_f32_16x16x32_bf16 v[72:75], v[144:147], v[206:209], v[72:75]
	v_mfma_f32_16x16x32_bf16 v[124:127], v[140:143], v[186:189], v[124:127]
	v_mfma_f32_16x16x32_bf16 v[120:123], v[148:151], v[186:189], v[120:123]
	v_mfma_f32_16x16x32_bf16 v[108:111], v[140:143], v[194:197], v[108:111]
	v_mfma_f32_16x16x32_bf16 v[104:107], v[148:151], v[194:197], v[104:107]
	v_mfma_f32_16x16x32_bf16 v[92:95], v[140:143], v[202:205], v[92:95]
	v_mfma_f32_16x16x32_bf16 v[88:91], v[148:151], v[202:205], v[88:91]
	v_mfma_f32_16x16x32_bf16 v[76:79], v[140:143], v[220:223], v[76:79]
	v_mfma_f32_16x16x32_bf16 v[72:75], v[148:151], v[220:223], v[72:75]
	v_mfma_f32_16x16x32_bf16 v[116:119], v[152:155], v[182:185], v[116:119]
	v_mfma_f32_16x16x32_bf16 v[112:115], v[160:163], v[182:185], v[112:115]
	v_mfma_f32_16x16x32_bf16 v[100:103], v[152:155], v[190:193], v[100:103]
	v_mfma_f32_16x16x32_bf16 v[96:99], v[160:163], v[190:193], v[96:99]
	v_mfma_f32_16x16x32_bf16 v[84:87], v[152:155], v[198:201], v[84:87]
	v_mfma_f32_16x16x32_bf16 v[80:83], v[160:163], v[198:201], v[80:83]
	v_mfma_f32_16x16x32_bf16 v[68:71], v[152:155], v[206:209], v[68:71]
	v_mfma_f32_16x16x32_bf16 v[64:67], v[160:163], v[206:209], v[64:67]
	v_mfma_f32_16x16x32_bf16 v[116:119], v[156:159], v[186:189], v[116:119]
	v_mfma_f32_16x16x32_bf16 v[112:115], v[164:167], v[186:189], v[112:115]
	v_mfma_f32_16x16x32_bf16 v[100:103], v[156:159], v[194:197], v[100:103]
	v_mfma_f32_16x16x32_bf16 v[96:99], v[164:167], v[194:197], v[96:99]
	v_mfma_f32_16x16x32_bf16 v[84:87], v[156:159], v[202:205], v[84:87]
	v_mfma_f32_16x16x32_bf16 v[80:83], v[164:167], v[202:205], v[80:83]
	v_mfma_f32_16x16x32_bf16 v[68:71], v[156:159], v[220:223], v[68:71]
	v_mfma_f32_16x16x32_bf16 v[64:67], v[164:167], v[220:223], v[64:67]
	s_barrier
	s_add_i32 s82, s87, s63
	v_lshl_add_u64 v[134:135], s[84:85], 0, v[172:173]
	s_mov_b32 m0, s82
	ds_read_b128 v[182:185], v138 offset:16384
	ds_read_b128 v[186:189], v138 offset:17408
	ds_read_b128 v[190:193], v138 offset:18432
	ds_read_b128 v[194:197], v138 offset:19456
	ds_read_b128 v[198:201], v138 offset:20480
	ds_read_b128 v[202:205], v138 offset:21504
	ds_read_b128 v[206:209], v138 offset:22528
	ds_read_b128 v[220:223], v138 offset:23552
	global_load_lds_dwordx4 v[134:135], off
	v_lshl_add_u64 v[224:225], v[134:135], 0, s[40:41]
	s_add_i32 m0, s82, 0x2000
	s_add_i32 s81, s81, s63
	global_load_lds_dwordx4 v[224:225], off
	v_lshl_add_u64 v[224:225], v[134:135], 0, s[4:5]
	s_mov_b32 m0, s81
	s_nop 0
	global_load_lds_dwordx4 v[224:225], off
	v_lshl_add_u64 v[224:225], v[134:135], 0, s[6:7]
	s_add_i32 m0, s81, 0x2000
	s_nop 0
	global_load_lds_dwordx4 v[224:225], off
	v_lshl_add_u64 v[224:225], s[48:49], 0, v[128:129]
	s_mov_b32 m0, s74
	v_lshl_add_u64 v[226:227], v[224:225], 0, s[40:41]
	global_load_lds_dwordx4 v[224:225], off
	s_mov_b32 m0, s75
	s_nop 0
	global_load_lds_dwordx4 v[226:227], off
	s_waitcnt vmcnt(8)
	s_waitcnt lgkmcnt(0)
	s_barrier
	s_waitcnt lgkmcnt(0)
	v_mfma_f32_16x16x32_bf16 v[60:63], v[130:133], v[182:185], v[60:63]
	v_mfma_f32_16x16x32_bf16 v[56:59], v[144:147], v[182:185], v[56:59]
	v_mfma_f32_16x16x32_bf16 v[44:47], v[130:133], v[190:193], v[44:47]
	v_mfma_f32_16x16x32_bf16 v[40:43], v[144:147], v[190:193], v[40:43]
	v_mfma_f32_16x16x32_bf16 v[28:31], v[130:133], v[198:201], v[28:31]
	v_mfma_f32_16x16x32_bf16 v[24:27], v[144:147], v[198:201], v[24:27]
	v_mfma_f32_16x16x32_bf16 v[12:15], v[130:133], v[206:209], v[12:15]
	v_mfma_f32_16x16x32_bf16 v[8:11], v[144:147], v[206:209], v[8:11]
	v_mfma_f32_16x16x32_bf16 v[60:63], v[140:143], v[186:189], v[60:63]
	v_mfma_f32_16x16x32_bf16 v[56:59], v[148:151], v[186:189], v[56:59]
	v_mfma_f32_16x16x32_bf16 v[44:47], v[140:143], v[194:197], v[44:47]
	v_mfma_f32_16x16x32_bf16 v[40:43], v[148:151], v[194:197], v[40:43]
	v_mfma_f32_16x16x32_bf16 v[28:31], v[140:143], v[202:205], v[28:31]
	v_mfma_f32_16x16x32_bf16 v[24:27], v[148:151], v[202:205], v[24:27]
	v_mfma_f32_16x16x32_bf16 v[12:15], v[140:143], v[220:223], v[12:15]
	v_mfma_f32_16x16x32_bf16 v[8:11], v[148:151], v[220:223], v[8:11]
	v_mfma_f32_16x16x32_bf16 v[52:55], v[152:155], v[182:185], v[52:55]
	v_mfma_f32_16x16x32_bf16 v[48:51], v[160:163], v[182:185], v[48:51]
	v_mfma_f32_16x16x32_bf16 v[36:39], v[152:155], v[190:193], v[36:39]
	v_mfma_f32_16x16x32_bf16 v[32:35], v[160:163], v[190:193], v[32:35]
	v_mfma_f32_16x16x32_bf16 v[20:23], v[152:155], v[198:201], v[20:23]
	v_mfma_f32_16x16x32_bf16 v[16:19], v[160:163], v[198:201], v[16:19]
	v_mfma_f32_16x16x32_bf16 v[4:7], v[152:155], v[206:209], v[4:7]
	v_mfma_f32_16x16x32_bf16 v[0:3], v[160:163], v[206:209], v[0:3]
	v_mfma_f32_16x16x32_bf16 v[52:55], v[156:159], v[186:189], v[52:55]
	v_mfma_f32_16x16x32_bf16 v[48:51], v[164:167], v[186:189], v[48:51]
	v_mfma_f32_16x16x32_bf16 v[36:39], v[156:159], v[194:197], v[36:39]
	v_mfma_f32_16x16x32_bf16 v[32:35], v[164:167], v[194:197], v[32:35]
	v_mfma_f32_16x16x32_bf16 v[20:23], v[156:159], v[202:205], v[20:23]
	v_mfma_f32_16x16x32_bf16 v[16:19], v[164:167], v[202:205], v[16:19]
	v_mfma_f32_16x16x32_bf16 v[4:7], v[156:159], v[220:223], v[4:7]
	v_mfma_f32_16x16x32_bf16 v[0:3], v[164:167], v[220:223], v[0:3]
	s_barrier
	s_add_i32 s48, 0, 0x18000
	v_add_u32_e32 v139, s48, v137
	s_add_i32 s49, 0, 0x1c000
	ds_read_b128 v[130:133], v139
	ds_read_b128 v[140:143], v139 offset:1024
	ds_read_b128 v[144:147], v139 offset:2048
	ds_read_b128 v[148:151], v139 offset:3072
	v_add_u32_e32 v139, s49, v137
	ds_read_b128 v[152:155], v139
	ds_read_b128 v[156:159], v139 offset:1024
	ds_read_b128 v[160:163], v139 offset:2048
	ds_read_b128 v[164:167], v139 offset:3072
	s_mov_b32 m0, s76
	v_lshl_add_u64 v[226:227], v[224:225], 0, s[4:5]
	ds_read_b128 v[182:185], v138 offset:32768
	ds_read_b128 v[186:189], v138 offset:33792
	ds_read_b128 v[190:193], v138 offset:34816
	ds_read_b128 v[194:197], v138 offset:35840
	ds_read_b128 v[198:201], v138 offset:36864
	ds_read_b128 v[202:205], v138 offset:37888
	ds_read_b128 v[206:209], v138 offset:38912
	ds_read_b128 v[220:223], v138 offset:39936
	global_load_lds_dwordx4 v[226:227], off
	v_lshl_add_u64 v[226:227], v[224:225], 0, s[6:7]
	s_mov_b32 m0, s77
	s_nop 0
	global_load_lds_dwordx4 v[226:227], off
	s_waitcnt vmcnt(8)
	s_waitcnt lgkmcnt(0)
	s_barrier
	s_waitcnt lgkmcnt(0)
	v_mfma_f32_16x16x32_bf16 v[124:127], v[130:133], v[182:185], v[124:127]
	v_mfma_f32_16x16x32_bf16 v[120:123], v[144:147], v[182:185], v[120:123]
	v_mfma_f32_16x16x32_bf16 v[108:111], v[130:133], v[190:193], v[108:111]
	v_mfma_f32_16x16x32_bf16 v[104:107], v[144:147], v[190:193], v[104:107]
	v_mfma_f32_16x16x32_bf16 v[92:95], v[130:133], v[198:201], v[92:95]
	v_mfma_f32_16x16x32_bf16 v[88:91], v[144:147], v[198:201], v[88:91]
	v_mfma_f32_16x16x32_bf16 v[76:79], v[130:133], v[206:209], v[76:79]
	v_mfma_f32_16x16x32_bf16 v[72:75], v[144:147], v[206:209], v[72:75]
	v_mfma_f32_16x16x32_bf16 v[124:127], v[140:143], v[186:189], v[124:127]
	v_mfma_f32_16x16x32_bf16 v[120:123], v[148:151], v[186:189], v[120:123]
	v_mfma_f32_16x16x32_bf16 v[108:111], v[140:143], v[194:197], v[108:111]
	v_mfma_f32_16x16x32_bf16 v[104:107], v[148:151], v[194:197], v[104:107]
	v_mfma_f32_16x16x32_bf16 v[92:95], v[140:143], v[202:205], v[92:95]
	v_mfma_f32_16x16x32_bf16 v[88:91], v[148:151], v[202:205], v[88:91]
	v_mfma_f32_16x16x32_bf16 v[76:79], v[140:143], v[220:223], v[76:79]
	v_mfma_f32_16x16x32_bf16 v[72:75], v[148:151], v[220:223], v[72:75]
	v_mfma_f32_16x16x32_bf16 v[116:119], v[152:155], v[182:185], v[116:119]
	v_mfma_f32_16x16x32_bf16 v[112:115], v[160:163], v[182:185], v[112:115]
	v_mfma_f32_16x16x32_bf16 v[100:103], v[152:155], v[190:193], v[100:103]
	v_mfma_f32_16x16x32_bf16 v[96:99], v[160:163], v[190:193], v[96:99]
	v_mfma_f32_16x16x32_bf16 v[84:87], v[152:155], v[198:201], v[84:87]
	v_mfma_f32_16x16x32_bf16 v[80:83], v[160:163], v[198:201], v[80:83]
	v_mfma_f32_16x16x32_bf16 v[68:71], v[152:155], v[206:209], v[68:71]
	v_mfma_f32_16x16x32_bf16 v[64:67], v[160:163], v[206:209], v[64:67]
	v_mfma_f32_16x16x32_bf16 v[116:119], v[156:159], v[186:189], v[116:119]
	v_mfma_f32_16x16x32_bf16 v[112:115], v[164:167], v[186:189], v[112:115]
	v_mfma_f32_16x16x32_bf16 v[100:103], v[156:159], v[194:197], v[100:103]
	v_mfma_f32_16x16x32_bf16 v[96:99], v[164:167], v[194:197], v[96:99]
	v_mfma_f32_16x16x32_bf16 v[84:87], v[156:159], v[202:205], v[84:87]
	v_mfma_f32_16x16x32_bf16 v[80:83], v[164:167], v[202:205], v[80:83]
	v_mfma_f32_16x16x32_bf16 v[68:71], v[156:159], v[220:223], v[68:71]
	v_mfma_f32_16x16x32_bf16 v[64:67], v[164:167], v[220:223], v[64:67]
	s_barrier
	s_add_i32 s48, s48, s63
	v_lshl_add_u64 v[226:227], v[134:135], 0, s[10:11]
	s_mov_b32 m0, s48
	ds_read_b128 v[182:185], v138 offset:49152
	ds_read_b128 v[186:189], v138 offset:50176
	ds_read_b128 v[190:193], v138 offset:51200
	ds_read_b128 v[194:197], v138 offset:52224
	ds_read_b128 v[198:201], v138 offset:53248
	ds_read_b128 v[202:205], v138 offset:54272
	ds_read_b128 v[206:209], v138 offset:55296
	ds_read_b128 v[220:223], v138 offset:56320
	global_load_lds_dwordx4 v[226:227], off
	v_lshl_add_u64 v[226:227], v[134:135], 0, s[12:13]
	s_add_i32 m0, s48, 0x2000
	s_add_i32 s48, s49, s63
	global_load_lds_dwordx4 v[226:227], off
	v_lshl_add_u64 v[226:227], v[134:135], 0, s[14:15]
	s_mov_b32 m0, s48
	v_lshl_add_u64 v[134:135], v[134:135], 0, s[16:17]
	global_load_lds_dwordx4 v[226:227], off
	s_add_i32 m0, s48, 0x2000
	s_nop 0
	global_load_lds_dwordx4 v[134:135], off
	v_lshl_add_u64 v[134:135], v[224:225], 0, s[10:11]
	s_mov_b32 m0, s68
	s_nop 0
	global_load_lds_dwordx4 v[134:135], off
	v_lshl_add_u64 v[134:135], v[224:225], 0, s[12:13]
	s_mov_b32 m0, s69
	s_nop 0
	global_load_lds_dwordx4 v[134:135], off
	s_waitcnt vmcnt(8)
	s_waitcnt lgkmcnt(0)
	s_barrier
	s_waitcnt lgkmcnt(0)
	v_mfma_f32_16x16x32_bf16 v[60:63], v[130:133], v[182:185], v[60:63]
	v_mfma_f32_16x16x32_bf16 v[56:59], v[144:147], v[182:185], v[56:59]
	v_mfma_f32_16x16x32_bf16 v[44:47], v[130:133], v[190:193], v[44:47]
	v_mfma_f32_16x16x32_bf16 v[40:43], v[144:147], v[190:193], v[40:43]
	v_mfma_f32_16x16x32_bf16 v[28:31], v[130:133], v[198:201], v[28:31]
	v_mfma_f32_16x16x32_bf16 v[24:27], v[144:147], v[198:201], v[24:27]
	v_mfma_f32_16x16x32_bf16 v[12:15], v[130:133], v[206:209], v[12:15]
	v_mfma_f32_16x16x32_bf16 v[8:11], v[144:147], v[206:209], v[8:11]
	v_mfma_f32_16x16x32_bf16 v[60:63], v[140:143], v[186:189], v[60:63]
	v_mfma_f32_16x16x32_bf16 v[56:59], v[148:151], v[186:189], v[56:59]
	v_mfma_f32_16x16x32_bf16 v[44:47], v[140:143], v[194:197], v[44:47]
	v_mfma_f32_16x16x32_bf16 v[40:43], v[148:151], v[194:197], v[40:43]
	v_mfma_f32_16x16x32_bf16 v[28:31], v[140:143], v[202:205], v[28:31]
	v_mfma_f32_16x16x32_bf16 v[24:27], v[148:151], v[202:205], v[24:27]
	v_mfma_f32_16x16x32_bf16 v[12:15], v[140:143], v[220:223], v[12:15]
	v_mfma_f32_16x16x32_bf16 v[8:11], v[148:151], v[220:223], v[8:11]
	v_mfma_f32_16x16x32_bf16 v[52:55], v[152:155], v[182:185], v[52:55]
	v_mfma_f32_16x16x32_bf16 v[48:51], v[160:163], v[182:185], v[48:51]
	v_mfma_f32_16x16x32_bf16 v[36:39], v[152:155], v[190:193], v[36:39]
	v_mfma_f32_16x16x32_bf16 v[32:35], v[160:163], v[190:193], v[32:35]
	v_mfma_f32_16x16x32_bf16 v[20:23], v[152:155], v[198:201], v[20:23]
	v_mfma_f32_16x16x32_bf16 v[16:19], v[160:163], v[198:201], v[16:19]
	v_mfma_f32_16x16x32_bf16 v[4:7], v[152:155], v[206:209], v[4:7]
	v_mfma_f32_16x16x32_bf16 v[0:3], v[160:163], v[206:209], v[0:3]
	v_mfma_f32_16x16x32_bf16 v[52:55], v[156:159], v[186:189], v[52:55]
	v_mfma_f32_16x16x32_bf16 v[48:51], v[164:167], v[186:189], v[48:51]
	v_mfma_f32_16x16x32_bf16 v[36:39], v[156:159], v[194:197], v[36:39]
	v_mfma_f32_16x16x32_bf16 v[32:35], v[164:167], v[194:197], v[32:35]
	v_mfma_f32_16x16x32_bf16 v[20:23], v[156:159], v[202:205], v[20:23]
	v_mfma_f32_16x16x32_bf16 v[16:19], v[164:167], v[202:205], v[16:19]
	v_mfma_f32_16x16x32_bf16 v[4:7], v[156:159], v[220:223], v[4:7]
	v_mfma_f32_16x16x32_bf16 v[0:3], v[164:167], v[220:223], v[0:3]
	s_barrier
	s_cmp_gt_u32 s80, 13
	s_cbranch_scc0 .LBB0_784
	s_and_b64 vcc, exec, s[30:31]
	s_cbranch_vccz .LBB0_787
	s_barrier

.LBB0_856:
	s_add_i32 s78, s78, 2
	s_mov_b32 s50, s78
	s_ashr_i32 s51, s50, 31
	s_lshl_b64 s[80:81], s[50:51], 7
	s_add_u32 s51, s80, 0x100
	s_addc_u32 s79, s81, 0
	s_add_u32 s82, s30, s51
	s_addc_u32 s83, s31, s79
	s_add_u32 s84, s28, s51
	s_addc_u32 s79, s29, s79
	s_add_i32 s85, 0, 0x10000
	s_cmp_eq_u32 s50, 14
	s_cselect_b32 s51, s39, s83
	s_cselect_b32 s50, s76, s82
	v_add_u32_e32 v135, s85, v133
	s_cselect_b32 s83, s35, s79
	s_cselect_b32 s82, s77, s84
	s_add_i32 s79, 0, 0x14000
	ds_read_b128 v[136:139], v135
	ds_read_b128 v[140:143], v135 offset:1024
	ds_read_b128 v[144:147], v135 offset:2048
	ds_read_b128 v[148:151], v135 offset:3072
	v_add_u32_e32 v135, s79, v133
	ds_read_b128 v[152:155], v135
	ds_read_b128 v[156:159], v135 offset:1024
	ds_read_b128 v[160:163], v135 offset:2048
	ds_read_b128 v[164:167], v135 offset:3072
	v_lshl_add_u64 v[224:225], v[130:131], 0, s[80:81]
	v_lshl_add_u64 v[226:227], v[224:225], 0, s[10:11]
	s_add_i32 m0, s62, 0xc000
	ds_read_b128 v[182:185], v134
	ds_read_b128 v[186:189], v134 offset:1024
	ds_read_b128 v[190:193], v134 offset:2048
	ds_read_b128 v[194:197], v134 offset:3072
	ds_read_b128 v[198:201], v134 offset:4096
	ds_read_b128 v[202:205], v134 offset:5120
	ds_read_b128 v[206:209], v134 offset:6144
	ds_read_b128 v[220:223], v134 offset:7168
	global_load_lds_dwordx4 v[226:227], off
	v_lshl_add_u64 v[224:225], v[224:225], 0, s[12:13]
	s_add_i32 m0, s62, 0xe000
	s_nop 0
	global_load_lds_dwordx4 v[224:225], off
	s_waitcnt vmcnt(8)
	s_waitcnt lgkmcnt(0)
	s_barrier
	s_waitcnt lgkmcnt(0)
	v_mfma_f32_16x16x32_bf16 v[124:127], v[136:139], v[182:185], v[124:127]
	v_mfma_f32_16x16x32_bf16 v[120:123], v[144:147], v[182:185], v[120:123]
	v_mfma_f32_16x16x32_bf16 v[116:119], v[136:139], v[190:193], v[116:119]
	v_mfma_f32_16x16x32_bf16 v[112:115], v[144:147], v[190:193], v[112:115]
	v_mfma_f32_16x16x32_bf16 v[100:103], v[136:139], v[198:201], v[100:103]
	v_mfma_f32_16x16x32_bf16 v[96:99], v[144:147], v[198:201], v[96:99]
	v_mfma_f32_16x16x32_bf16 v[84:87], v[136:139], v[206:209], v[84:87]
	v_mfma_f32_16x16x32_bf16 v[80:83], v[144:147], v[206:209], v[80:83]
	v_mfma_f32_16x16x32_bf16 v[124:127], v[140:143], v[186:189], v[124:127]
	v_mfma_f32_16x16x32_bf16 v[120:123], v[148:151], v[186:189], v[120:123]
	v_mfma_f32_16x16x32_bf16 v[116:119], v[140:143], v[194:197], v[116:119]
	v_mfma_f32_16x16x32_bf16 v[112:115], v[148:151], v[194:197], v[112:115]
	v_mfma_f32_16x16x32_bf16 v[100:103], v[140:143], v[202:205], v[100:103]
	v_mfma_f32_16x16x32_bf16 v[96:99], v[148:151], v[202:205], v[96:99]
	v_mfma_f32_16x16x32_bf16 v[84:87], v[140:143], v[220:223], v[84:87]
	v_mfma_f32_16x16x32_bf16 v[80:83], v[148:151], v[220:223], v[80:83]
	v_mfma_f32_16x16x32_bf16 v[108:111], v[152:155], v[182:185], v[108:111]
	v_mfma_f32_16x16x32_bf16 v[104:107], v[160:163], v[182:185], v[104:107]
	v_mfma_f32_16x16x32_bf16 v[92:95], v[152:155], v[190:193], v[92:95]
	v_mfma_f32_16x16x32_bf16 v[88:91], v[160:163], v[190:193], v[88:91]
	v_mfma_f32_16x16x32_bf16 v[76:79], v[152:155], v[198:201], v[76:79]
	v_mfma_f32_16x16x32_bf16 v[72:75], v[160:163], v[198:201], v[72:75]
	v_mfma_f32_16x16x32_bf16 v[68:71], v[152:155], v[206:209], v[68:71]
	v_mfma_f32_16x16x32_bf16 v[64:67], v[160:163], v[206:209], v[64:67]
	v_mfma_f32_16x16x32_bf16 v[108:111], v[156:159], v[186:189], v[108:111]
	v_mfma_f32_16x16x32_bf16 v[104:107], v[164:167], v[186:189], v[104:107]
	v_mfma_f32_16x16x32_bf16 v[92:95], v[156:159], v[194:197], v[92:95]
	v_mfma_f32_16x16x32_bf16 v[88:91], v[164:167], v[194:197], v[88:91]
	v_mfma_f32_16x16x32_bf16 v[76:79], v[156:159], v[202:205], v[76:79]
	v_mfma_f32_16x16x32_bf16 v[72:75], v[164:167], v[202:205], v[72:75]
	v_mfma_f32_16x16x32_bf16 v[68:71], v[156:159], v[220:223], v[68:71]
	v_mfma_f32_16x16x32_bf16 v[64:67], v[164:167], v[220:223], v[64:67]
	s_barrier
	s_add_i32 s80, s85, s59
	v_lshl_add_u64 v[224:225], s[82:83], 0, v[172:173]
	s_mov_b32 m0, s80
	ds_read_b128 v[182:185], v134 offset:16384
	ds_read_b128 v[186:189], v134 offset:17408
	ds_read_b128 v[190:193], v134 offset:18432
	ds_read_b128 v[194:197], v134 offset:19456
	ds_read_b128 v[198:201], v134 offset:20480
	ds_read_b128 v[202:205], v134 offset:21504
	ds_read_b128 v[206:209], v134 offset:22528
	ds_read_b128 v[220:223], v134 offset:23552
	global_load_lds_dwordx4 v[224:225], off
	v_lshl_add_u64 v[226:227], v[224:225], 0, s[40:41]
	s_add_i32 m0, s80, 0x2000
	s_add_i32 s79, s79, s59
	global_load_lds_dwordx4 v[226:227], off
	v_lshl_add_u64 v[226:227], v[224:225], 0, s[4:5]
	s_mov_b32 m0, s79
	s_nop 0
	global_load_lds_dwordx4 v[226:227], off
	v_lshl_add_u64 v[226:227], v[224:225], 0, s[6:7]
	s_add_i32 m0, s79, 0x2000
	s_nop 0
	global_load_lds_dwordx4 v[226:227], off
	v_lshl_add_u64 v[226:227], s[50:51], 0, v[128:129]
	s_mov_b32 m0, s62
	v_lshl_add_u64 v[228:229], v[226:227], 0, s[40:41]
	global_load_lds_dwordx4 v[226:227], off
	s_mov_b32 m0, s63
	s_nop 0
	global_load_lds_dwordx4 v[228:229], off
	s_waitcnt vmcnt(8)
	s_waitcnt lgkmcnt(0)
	s_barrier
	s_waitcnt lgkmcnt(0)
	v_mfma_f32_16x16x32_bf16 v[60:63], v[136:139], v[182:185], v[60:63]
	v_mfma_f32_16x16x32_bf16 v[56:59], v[144:147], v[182:185], v[56:59]
	v_mfma_f32_16x16x32_bf16 v[52:55], v[136:139], v[190:193], v[52:55]
	v_mfma_f32_16x16x32_bf16 v[48:51], v[144:147], v[190:193], v[48:51]
	v_mfma_f32_16x16x32_bf16 v[36:39], v[136:139], v[198:201], v[36:39]
	v_mfma_f32_16x16x32_bf16 v[32:35], v[144:147], v[198:201], v[32:35]
	v_mfma_f32_16x16x32_bf16 v[20:23], v[136:139], v[206:209], v[20:23]
	v_mfma_f32_16x16x32_bf16 v[16:19], v[144:147], v[206:209], v[16:19]
	v_mfma_f32_16x16x32_bf16 v[60:63], v[140:143], v[186:189], v[60:63]
	v_mfma_f32_16x16x32_bf16 v[56:59], v[148:151], v[186:189], v[56:59]
	v_mfma_f32_16x16x32_bf16 v[52:55], v[140:143], v[194:197], v[52:55]
	v_mfma_f32_16x16x32_bf16 v[48:51], v[148:151], v[194:197], v[48:51]
	v_mfma_f32_16x16x32_bf16 v[36:39], v[140:143], v[202:205], v[36:39]
	v_mfma_f32_16x16x32_bf16 v[32:35], v[148:151], v[202:205], v[32:35]
	v_mfma_f32_16x16x32_bf16 v[20:23], v[140:143], v[220:223], v[20:23]
	v_mfma_f32_16x16x32_bf16 v[16:19], v[148:151], v[220:223], v[16:19]
	v_mfma_f32_16x16x32_bf16 v[44:47], v[152:155], v[182:185], v[44:47]
	v_mfma_f32_16x16x32_bf16 v[40:43], v[160:163], v[182:185], v[40:43]
	v_mfma_f32_16x16x32_bf16 v[28:31], v[152:155], v[190:193], v[28:31]
	v_mfma_f32_16x16x32_bf16 v[24:27], v[160:163], v[190:193], v[24:27]
	v_mfma_f32_16x16x32_bf16 v[12:15], v[152:155], v[198:201], v[12:15]
	v_mfma_f32_16x16x32_bf16 v[8:11], v[160:163], v[198:201], v[8:11]
	v_mfma_f32_16x16x32_bf16 v[4:7], v[152:155], v[206:209], v[4:7]
	v_mfma_f32_16x16x32_bf16 v[0:3], v[160:163], v[206:209], v[0:3]
	v_mfma_f32_16x16x32_bf16 v[44:47], v[156:159], v[186:189], v[44:47]
	v_mfma_f32_16x16x32_bf16 v[40:43], v[164:167], v[186:189], v[40:43]
	v_mfma_f32_16x16x32_bf16 v[28:31], v[156:159], v[194:197], v[28:31]
	v_mfma_f32_16x16x32_bf16 v[24:27], v[164:167], v[194:197], v[24:27]
	v_mfma_f32_16x16x32_bf16 v[12:15], v[156:159], v[202:205], v[12:15]
	v_mfma_f32_16x16x32_bf16 v[8:11], v[164:167], v[202:205], v[8:11]
	v_mfma_f32_16x16x32_bf16 v[4:7], v[156:159], v[220:223], v[4:7]
	v_mfma_f32_16x16x32_bf16 v[0:3], v[164:167], v[220:223], v[0:3]
	s_barrier
	s_add_i32 s50, 0, 0x18000
	v_add_u32_e32 v135, s50, v133
	s_add_i32 s51, 0, 0x1c000
	ds_read_b128 v[136:139], v135
	ds_read_b128 v[140:143], v135 offset:1024
	ds_read_b128 v[144:147], v135 offset:2048
	ds_read_b128 v[148:151], v135 offset:3072
	v_add_u32_e32 v135, s51, v133
	ds_read_b128 v[152:155], v135
	ds_read_b128 v[156:159], v135 offset:1024
	ds_read_b128 v[160:163], v135 offset:2048
	ds_read_b128 v[164:167], v135 offset:3072
	s_mov_b32 m0, s68
	v_lshl_add_u64 v[228:229], v[226:227], 0, s[4:5]
	ds_read_b128 v[182:185], v134 offset:32768
	ds_read_b128 v[186:189], v134 offset:33792
	ds_read_b128 v[190:193], v134 offset:34816
	ds_read_b128 v[194:197], v134 offset:35840
	ds_read_b128 v[198:201], v134 offset:36864
	ds_read_b128 v[202:205], v134 offset:37888
	ds_read_b128 v[206:209], v134 offset:38912
	ds_read_b128 v[220:223], v134 offset:39936
	global_load_lds_dwordx4 v[228:229], off
	v_lshl_add_u64 v[228:229], v[226:227], 0, s[6:7]
	s_mov_b32 m0, s69
	s_nop 0
	global_load_lds_dwordx4 v[228:229], off
	s_waitcnt vmcnt(8)
	s_waitcnt lgkmcnt(0)
	s_barrier
	s_waitcnt lgkmcnt(0)
	v_mfma_f32_16x16x32_bf16 v[124:127], v[136:139], v[182:185], v[124:127]
	v_mfma_f32_16x16x32_bf16 v[120:123], v[144:147], v[182:185], v[120:123]
	v_mfma_f32_16x16x32_bf16 v[116:119], v[136:139], v[190:193], v[116:119]
	v_mfma_f32_16x16x32_bf16 v[112:115], v[144:147], v[190:193], v[112:115]
	v_mfma_f32_16x16x32_bf16 v[100:103], v[136:139], v[198:201], v[100:103]
	v_mfma_f32_16x16x32_bf16 v[96:99], v[144:147], v[198:201], v[96:99]
	v_mfma_f32_16x16x32_bf16 v[84:87], v[136:139], v[206:209], v[84:87]
	v_mfma_f32_16x16x32_bf16 v[80:83], v[144:147], v[206:209], v[80:83]
	v_mfma_f32_16x16x32_bf16 v[124:127], v[140:143], v[186:189], v[124:127]
	v_mfma_f32_16x16x32_bf16 v[120:123], v[148:151], v[186:189], v[120:123]
	v_mfma_f32_16x16x32_bf16 v[116:119], v[140:143], v[194:197], v[116:119]
	v_mfma_f32_16x16x32_bf16 v[112:115], v[148:151], v[194:197], v[112:115]
	v_mfma_f32_16x16x32_bf16 v[100:103], v[140:143], v[202:205], v[100:103]
	v_mfma_f32_16x16x32_bf16 v[96:99], v[148:151], v[202:205], v[96:99]
	v_mfma_f32_16x16x32_bf16 v[84:87], v[140:143], v[220:223], v[84:87]
	v_mfma_f32_16x16x32_bf16 v[80:83], v[148:151], v[220:223], v[80:83]
	v_mfma_f32_16x16x32_bf16 v[108:111], v[152:155], v[182:185], v[108:111]
	v_mfma_f32_16x16x32_bf16 v[104:107], v[160:163], v[182:185], v[104:107]
	v_mfma_f32_16x16x32_bf16 v[92:95], v[152:155], v[190:193], v[92:95]
	v_mfma_f32_16x16x32_bf16 v[88:91], v[160:163], v[190:193], v[88:91]
	v_mfma_f32_16x16x32_bf16 v[76:79], v[152:155], v[198:201], v[76:79]
	v_mfma_f32_16x16x32_bf16 v[72:75], v[160:163], v[198:201], v[72:75]
	v_mfma_f32_16x16x32_bf16 v[68:71], v[152:155], v[206:209], v[68:71]
	v_mfma_f32_16x16x32_bf16 v[64:67], v[160:163], v[206:209], v[64:67]
	v_mfma_f32_16x16x32_bf16 v[108:111], v[156:159], v[186:189], v[108:111]
	v_mfma_f32_16x16x32_bf16 v[104:107], v[164:167], v[186:189], v[104:107]
	v_mfma_f32_16x16x32_bf16 v[92:95], v[156:159], v[194:197], v[92:95]
	v_mfma_f32_16x16x32_bf16 v[88:91], v[164:167], v[194:197], v[88:91]
	v_mfma_f32_16x16x32_bf16 v[76:79], v[156:159], v[202:205], v[76:79]
	v_mfma_f32_16x16x32_bf16 v[72:75], v[164:167], v[202:205], v[72:75]
	v_mfma_f32_16x16x32_bf16 v[68:71], v[156:159], v[220:223], v[68:71]
	v_mfma_f32_16x16x32_bf16 v[64:67], v[164:167], v[220:223], v[64:67]
	s_barrier
	s_add_i32 s50, s50, s59
	v_lshl_add_u64 v[228:229], v[224:225], 0, s[10:11]
	s_mov_b32 m0, s50
	ds_read_b128 v[182:185], v134 offset:49152
	ds_read_b128 v[186:189], v134 offset:50176
	ds_read_b128 v[190:193], v134 offset:51200
	ds_read_b128 v[194:197], v134 offset:52224
	ds_read_b128 v[198:201], v134 offset:53248
	ds_read_b128 v[202:205], v134 offset:54272
	ds_read_b128 v[206:209], v134 offset:55296
	ds_read_b128 v[220:223], v134 offset:56320
	global_load_lds_dwordx4 v[228:229], off
	v_lshl_add_u64 v[228:229], v[224:225], 0, s[12:13]
	s_add_i32 m0, s50, 0x2000
	s_add_i32 s50, s51, s59
	global_load_lds_dwordx4 v[228:229], off
	v_lshl_add_u64 v[228:229], v[224:225], 0, s[14:15]
	s_mov_b32 m0, s50
	v_lshl_add_u64 v[224:225], v[224:225], 0, s[16:17]
	global_load_lds_dwordx4 v[228:229], off
	s_add_i32 m0, s50, 0x2000
	s_nop 0
	global_load_lds_dwordx4 v[224:225], off
	v_lshl_add_u64 v[224:225], v[226:227], 0, s[10:11]
	s_mov_b32 m0, s72
	s_nop 0
	global_load_lds_dwordx4 v[224:225], off
	v_lshl_add_u64 v[224:225], v[226:227], 0, s[12:13]
	s_mov_b32 m0, s73
	s_nop 0
	global_load_lds_dwordx4 v[224:225], off
	s_waitcnt vmcnt(8)
	s_waitcnt lgkmcnt(0)
	s_barrier
	s_waitcnt lgkmcnt(0)
	v_mfma_f32_16x16x32_bf16 v[60:63], v[136:139], v[182:185], v[60:63]
	v_mfma_f32_16x16x32_bf16 v[56:59], v[144:147], v[182:185], v[56:59]
	v_mfma_f32_16x16x32_bf16 v[52:55], v[136:139], v[190:193], v[52:55]
	v_mfma_f32_16x16x32_bf16 v[48:51], v[144:147], v[190:193], v[48:51]
	v_mfma_f32_16x16x32_bf16 v[36:39], v[136:139], v[198:201], v[36:39]
	v_mfma_f32_16x16x32_bf16 v[32:35], v[144:147], v[198:201], v[32:35]
	v_mfma_f32_16x16x32_bf16 v[20:23], v[136:139], v[206:209], v[20:23]
	v_mfma_f32_16x16x32_bf16 v[16:19], v[144:147], v[206:209], v[16:19]
	v_mfma_f32_16x16x32_bf16 v[60:63], v[140:143], v[186:189], v[60:63]
	v_mfma_f32_16x16x32_bf16 v[56:59], v[148:151], v[186:189], v[56:59]
	v_mfma_f32_16x16x32_bf16 v[52:55], v[140:143], v[194:197], v[52:55]
	v_mfma_f32_16x16x32_bf16 v[48:51], v[148:151], v[194:197], v[48:51]
	v_mfma_f32_16x16x32_bf16 v[36:39], v[140:143], v[202:205], v[36:39]
	v_mfma_f32_16x16x32_bf16 v[32:35], v[148:151], v[202:205], v[32:35]
	v_mfma_f32_16x16x32_bf16 v[20:23], v[140:143], v[220:223], v[20:23]
	v_mfma_f32_16x16x32_bf16 v[16:19], v[148:151], v[220:223], v[16:19]
	v_mfma_f32_16x16x32_bf16 v[44:47], v[152:155], v[182:185], v[44:47]
	v_mfma_f32_16x16x32_bf16 v[40:43], v[160:163], v[182:185], v[40:43]
	v_mfma_f32_16x16x32_bf16 v[28:31], v[152:155], v[190:193], v[28:31]
	v_mfma_f32_16x16x32_bf16 v[24:27], v[160:163], v[190:193], v[24:27]
	v_mfma_f32_16x16x32_bf16 v[12:15], v[152:155], v[198:201], v[12:15]
	v_mfma_f32_16x16x32_bf16 v[8:11], v[160:163], v[198:201], v[8:11]
	v_mfma_f32_16x16x32_bf16 v[4:7], v[152:155], v[206:209], v[4:7]
	v_mfma_f32_16x16x32_bf16 v[0:3], v[160:163], v[206:209], v[0:3]
	v_mfma_f32_16x16x32_bf16 v[44:47], v[156:159], v[186:189], v[44:47]
	v_mfma_f32_16x16x32_bf16 v[40:43], v[164:167], v[186:189], v[40:43]
	v_mfma_f32_16x16x32_bf16 v[28:31], v[156:159], v[194:197], v[28:31]
	v_mfma_f32_16x16x32_bf16 v[24:27], v[164:167], v[194:197], v[24:27]
	v_mfma_f32_16x16x32_bf16 v[12:15], v[156:159], v[202:205], v[12:15]
	v_mfma_f32_16x16x32_bf16 v[8:11], v[164:167], v[202:205], v[8:11]
	v_mfma_f32_16x16x32_bf16 v[4:7], v[156:159], v[220:223], v[4:7]
	v_mfma_f32_16x16x32_bf16 v[0:3], v[164:167], v[220:223], v[0:3]
	s_barrier
	s_cmp_gt_u32 s78, 13
	s_cbranch_scc0 .LBB0_856
	s_and_b64 vcc, exec, s[8:9]
	s_cbranch_vccz .LBB0_859
	s_barrier

.LBB0_969:
	s_ashr_i32 s23, s22, 31
	s_lshl_b64 s[24:25], s[22:23], 19
	s_add_u32 s24, s41, s24
	s_addc_u32 s25, s42, s25
	s_ashr_i32 s21, s20, 31
	s_lshl_b64 s[26:27], s[20:21], 19
	s_add_u32 s26, s43, s26
	s_mov_b32 s38, 0
	s_addc_u32 s27, s44, s27
	s_ashr_i32 s39, s38, 31
	s_lshl_b64 s[68:69], s[38:39], 7
	s_add_u32 s70, s68, 0x100
	s_addc_u32 s71, s69, 0
	s_add_u32 s38, s34, s70
	ds_read_b128 v[0:3], v140
	ds_read_b128 v[4:7], v140 offset:1024
	ds_read_b128 v[8:11], v140 offset:2048
	ds_read_b128 v[12:15], v140 offset:3072
	ds_read_b128 v[16:19], v141
	ds_read_b128 v[20:23], v141 offset:1024
	ds_read_b128 v[24:27], v141 offset:2048
	ds_read_b128 v[28:31], v141 offset:3072
	s_addc_u32 s39, s35, s71
	s_and_b64 s[66:67], s[36:37], exec
	s_cselect_b32 s23, s27, s31
	s_cselect_b32 s66, s26, s30
	s_add_u32 s70, s30, s70
	s_addc_u32 s71, s31, s71
	s_add_u32 s68, s34, s68
	s_mov_b32 s21, 0
	s_addc_u32 s69, s35, s69
	v_lshl_add_u64 v[64:65], s[68:69], 0, v[130:131]
	s_mov_b32 m0, s59
	v_lshl_add_u64 v[66:67], v[64:65], 0, s[14:15]
	ds_read_b128 v[32:35], v142
	ds_read_b128 v[36:39], v142 offset:1024
	ds_read_b128 v[40:43], v142 offset:2048
	ds_read_b128 v[44:47], v142 offset:3072
	ds_read_b128 v[48:51], v142 offset:4096
	ds_read_b128 v[52:55], v142 offset:5120
	ds_read_b128 v[56:59], v142 offset:6144
	ds_read_b128 v[60:63], v142 offset:7168
	global_load_lds_dwordx4 v[66:67], off
	v_lshl_add_u64 v[64:65], v[64:65], 0, s[16:17]
	s_mov_b32 m0, s60
	s_and_b64 s[68:69], s[36:37], exec
	global_load_lds_dwordx4 v[64:65], off
	s_waitcnt vmcnt(16)
	s_waitcnt lgkmcnt(0)
	s_cselect_b32 s67, s25, s35
	s_cselect_b32 s68, s24, s34
	s_barrier
	s_waitcnt lgkmcnt(0)
	v_mfma_f32_16x16x32_bf16 v[64:67], v[0:3], v[32:35], 0
	v_mfma_f32_16x16x32_bf16 v[68:71], v[8:11], v[32:35], 0
	v_mfma_f32_16x16x32_bf16 v[72:75], v[0:3], v[40:43], 0
	v_mfma_f32_16x16x32_bf16 v[76:79], v[8:11], v[40:43], 0
	v_mfma_f32_16x16x32_bf16 v[80:83], v[0:3], v[48:51], 0
	v_mfma_f32_16x16x32_bf16 v[84:87], v[8:11], v[48:51], 0
	v_mfma_f32_16x16x32_bf16 v[88:91], v[0:3], v[56:59], 0
	v_mfma_f32_16x16x32_bf16 v[92:95], v[8:11], v[56:59], 0
	v_mfma_f32_16x16x32_bf16 v[64:67], v[4:7], v[36:39], v[64:67]
	v_mfma_f32_16x16x32_bf16 v[68:71], v[12:15], v[36:39], v[68:71]
	v_mfma_f32_16x16x32_bf16 v[72:75], v[4:7], v[44:47], v[72:75]
	v_mfma_f32_16x16x32_bf16 v[76:79], v[12:15], v[44:47], v[76:79]
	v_mfma_f32_16x16x32_bf16 v[80:83], v[4:7], v[52:55], v[80:83]
	v_mfma_f32_16x16x32_bf16 v[84:87], v[12:15], v[52:55], v[84:87]
	v_mfma_f32_16x16x32_bf16 v[88:91], v[4:7], v[60:63], v[88:91]
	v_mfma_f32_16x16x32_bf16 v[100:103], v[12:15], v[60:63], v[92:95]
	v_mfma_f32_16x16x32_bf16 v[92:95], v[16:19], v[32:35], 0
	v_mfma_f32_16x16x32_bf16 v[32:35], v[24:27], v[32:35], 0
	v_mfma_f32_16x16x32_bf16 v[104:107], v[20:23], v[36:39], v[92:95]
	v_mfma_f32_16x16x32_bf16 v[32:35], v[28:31], v[36:39], v[32:35]
	v_mfma_f32_16x16x32_bf16 v[36:39], v[16:19], v[40:43], 0
	v_mfma_f32_16x16x32_bf16 v[40:43], v[24:27], v[40:43], 0
	v_mfma_f32_16x16x32_bf16 v[36:39], v[20:23], v[44:47], v[36:39]
	v_mfma_f32_16x16x32_bf16 v[40:43], v[28:31], v[44:47], v[40:43]
	v_mfma_f32_16x16x32_bf16 v[44:47], v[16:19], v[48:51], 0
	v_mfma_f32_16x16x32_bf16 v[48:51], v[24:27], v[48:51], 0
	v_mfma_f32_16x16x32_bf16 v[44:47], v[20:23], v[52:55], v[44:47]
	v_mfma_f32_16x16x32_bf16 v[48:51], v[28:31], v[52:55], v[48:51]
	v_mfma_f32_16x16x32_bf16 v[52:55], v[16:19], v[56:59], 0
	v_mfma_f32_16x16x32_bf16 v[56:59], v[24:27], v[56:59], 0
	v_mfma_f32_16x16x32_bf16 v[52:55], v[20:23], v[60:63], v[52:55]
	v_mfma_f32_16x16x32_bf16 v[56:59], v[28:31], v[60:63], v[56:59]
	s_barrier
	s_mov_b32 m0, s61
	v_lshl_add_u64 v[208:209], s[70:71], 0, v[128:129]
	ds_read_b128 v[60:63], v142 offset:16384
	ds_read_b128 v[92:95], v142 offset:17408
	ds_read_b128 v[96:99], v142 offset:18432
	ds_read_b128 v[108:111], v142 offset:19456
	ds_read_b128 v[112:115], v142 offset:20480
	ds_read_b128 v[116:119], v142 offset:21504
	ds_read_b128 v[120:123], v142 offset:22528
	ds_read_b128 v[124:127], v142 offset:23552
	global_load_lds_dwordx4 v[208:209], off
	v_lshl_add_u64 v[136:137], v[208:209], 0, s[0:1]
	s_mov_b32 m0, s62
	v_lshl_add_u64 v[248:249], s[38:39], 0, v[130:131]
	global_load_lds_dwordx4 v[136:137], off
	v_lshl_add_u64 v[136:137], v[208:209], 0, s[2:3]
	s_mov_b32 m0, s63
	s_nop 0
	global_load_lds_dwordx4 v[136:137], off
	v_lshl_add_u64 v[136:137], v[208:209], 0, s[4:5]
	s_mov_b32 m0, s64
	s_nop 0
	global_load_lds_dwordx4 v[136:137], off
	s_mov_b32 m0, s48
	v_lshl_add_u64 v[136:137], v[248:249], 0, s[0:1]
	global_load_lds_dwordx4 v[248:249], off
	s_mov_b32 m0, s49
	s_nop 0
	global_load_lds_dwordx4 v[136:137], off
	s_waitcnt vmcnt(16)
	s_waitcnt lgkmcnt(0)
	s_barrier
	s_waitcnt lgkmcnt(0)
	v_mfma_f32_16x16x32_bf16 v[144:147], v[0:3], v[60:63], 0
	v_mfma_f32_16x16x32_bf16 v[152:155], v[0:3], v[96:99], 0
	v_mfma_f32_16x16x32_bf16 v[160:163], v[0:3], v[112:115], 0
	v_mfma_f32_16x16x32_bf16 v[0:3], v[0:3], v[120:123], 0
	v_mfma_f32_16x16x32_bf16 v[144:147], v[4:7], v[92:95], v[144:147]
	v_mfma_f32_16x16x32_bf16 v[152:155], v[4:7], v[108:111], v[152:155]
	v_mfma_f32_16x16x32_bf16 v[160:163], v[4:7], v[116:119], v[160:163]
	v_mfma_f32_16x16x32_bf16 v[0:3], v[4:7], v[124:127], v[0:3]
	v_mfma_f32_16x16x32_bf16 v[4:7], v[8:11], v[120:123], 0
	v_mfma_f32_16x16x32_bf16 v[148:151], v[8:11], v[60:63], 0
	v_mfma_f32_16x16x32_bf16 v[156:159], v[8:11], v[96:99], 0
	v_mfma_f32_16x16x32_bf16 v[164:167], v[8:11], v[112:115], 0
	v_mfma_f32_16x16x32_bf16 v[4:7], v[12:15], v[124:127], v[4:7]
	v_mfma_f32_16x16x32_bf16 v[148:151], v[12:15], v[92:95], v[148:151]
	v_mfma_f32_16x16x32_bf16 v[156:159], v[12:15], v[108:111], v[156:159]
	v_mfma_f32_16x16x32_bf16 v[164:167], v[12:15], v[116:119], v[164:167]
	v_mfma_f32_16x16x32_bf16 v[12:15], v[24:27], v[60:63], 0
	v_mfma_f32_16x16x32_bf16 v[172:175], v[28:31], v[92:95], v[12:15]
	v_mfma_f32_16x16x32_bf16 v[12:15], v[16:19], v[96:99], 0
	v_mfma_f32_16x16x32_bf16 v[176:179], v[20:23], v[108:111], v[12:15]
	v_mfma_f32_16x16x32_bf16 v[12:15], v[24:27], v[96:99], 0
	v_mfma_f32_16x16x32_bf16 v[180:183], v[28:31], v[108:111], v[12:15]
	v_mfma_f32_16x16x32_bf16 v[12:15], v[16:19], v[112:115], 0
	v_mfma_f32_16x16x32_bf16 v[184:187], v[20:23], v[116:119], v[12:15]
	v_mfma_f32_16x16x32_bf16 v[12:15], v[24:27], v[112:115], 0
	v_mfma_f32_16x16x32_bf16 v[8:11], v[16:19], v[60:63], 0
	v_mfma_f32_16x16x32_bf16 v[188:191], v[28:31], v[116:119], v[12:15]
	v_mfma_f32_16x16x32_bf16 v[12:15], v[16:19], v[120:123], 0
	v_mfma_f32_16x16x32_bf16 v[8:11], v[20:23], v[92:95], v[8:11]
	v_mfma_f32_16x16x32_bf16 v[192:195], v[20:23], v[124:127], v[12:15]
	v_mfma_f32_16x16x32_bf16 v[12:15], v[24:27], v[120:123], 0
	v_mfma_f32_16x16x32_bf16 v[196:199], v[28:31], v[124:127], v[12:15]
	s_barrier
	s_add_i32 s71, 0, 0x1c000
	v_add_u32_e32 v136, s71, v139
	s_nop 2
	ds_read_b128 v[12:15], v143
	ds_read_b128 v[20:23], v143 offset:1024
	ds_read_b128 v[24:27], v143 offset:2048
	ds_read_b128 v[200:203], v143 offset:3072
	ds_read_b128 v[204:207], v136
	ds_read_b128 v[212:215], v136 offset:1024
	ds_read_b128 v[216:219], v136 offset:2048
	ds_read_b128 v[220:223], v136 offset:3072
	s_mov_b32 m0, s50
	v_lshl_add_u64 v[92:93], v[248:249], 0, s[2:3]
	ds_read_b128 v[16:19], v142 offset:32768
	ds_read_b128 v[28:31], v142 offset:33792
	ds_read_b128 v[60:63], v142 offset:34816
	ds_read_b128 v[224:227], v142 offset:35840
	ds_read_b128 v[228:231], v142 offset:36864
	ds_read_b128 v[232:235], v142 offset:37888
	ds_read_b128 v[236:239], v142 offset:38912
	ds_read_b128 v[240:243], v142 offset:39936
	global_load_lds_dwordx4 v[92:93], off
	v_lshl_add_u64 v[92:93], v[248:249], 0, s[4:5]
	s_mov_b32 m0, s51
	s_nop 0
	global_load_lds_dwordx4 v[92:93], off
	s_waitcnt vmcnt(8)
	s_waitcnt lgkmcnt(0)
	s_barrier
	s_waitcnt lgkmcnt(0)
	v_mfma_f32_16x16x32_bf16 v[64:67], v[12:15], v[16:19], v[64:67]
	v_mfma_f32_16x16x32_bf16 v[124:127], v[20:23], v[28:31], v[64:67]
	v_mfma_f32_16x16x32_bf16 v[64:67], v[24:27], v[16:19], v[68:71]
	v_mfma_f32_16x16x32_bf16 v[112:115], v[200:203], v[28:31], v[64:67]
	v_mfma_f32_16x16x32_bf16 v[64:67], v[12:15], v[60:63], v[72:75]
	v_mfma_f32_16x16x32_bf16 v[108:111], v[20:23], v[224:227], v[64:67]
	v_mfma_f32_16x16x32_bf16 v[64:67], v[24:27], v[60:63], v[76:79]
	v_mfma_f32_16x16x32_bf16 v[96:99], v[200:203], v[224:227], v[64:67]
	v_mfma_f32_16x16x32_bf16 v[64:67], v[12:15], v[228:231], v[80:83]
	v_mfma_f32_16x16x32_bf16 v[92:95], v[20:23], v[232:235], v[64:67]
	v_mfma_f32_16x16x32_bf16 v[64:67], v[24:27], v[228:231], v[84:87]
	v_mfma_f32_16x16x32_bf16 v[80:83], v[200:203], v[232:235], v[64:67]
	v_mfma_f32_16x16x32_bf16 v[64:67], v[12:15], v[236:239], v[88:91]
	v_mfma_f32_16x16x32_bf16 v[76:79], v[20:23], v[240:243], v[64:67]
	v_mfma_f32_16x16x32_bf16 v[64:67], v[24:27], v[236:239], v[100:103]
	v_mfma_f32_16x16x32_bf16 v[64:67], v[200:203], v[240:243], v[64:67]
	v_mfma_f32_16x16x32_bf16 v[68:71], v[204:207], v[16:19], v[104:107]
	v_mfma_f32_16x16x32_bf16 v[16:19], v[216:219], v[16:19], v[32:35]
	v_mfma_f32_16x16x32_bf16 v[116:119], v[220:223], v[28:31], v[16:19]
	v_mfma_f32_16x16x32_bf16 v[16:19], v[204:207], v[60:63], v[36:39]
	v_mfma_f32_16x16x32_bf16 v[104:107], v[212:215], v[224:227], v[16:19]
	v_mfma_f32_16x16x32_bf16 v[16:19], v[216:219], v[60:63], v[40:43]
	v_mfma_f32_16x16x32_bf16 v[100:103], v[220:223], v[224:227], v[16:19]
	v_mfma_f32_16x16x32_bf16 v[16:19], v[204:207], v[228:231], v[44:47]
	v_mfma_f32_16x16x32_bf16 v[88:91], v[212:215], v[232:235], v[16:19]
	v_mfma_f32_16x16x32_bf16 v[16:19], v[216:219], v[228:231], v[48:51]
	v_mfma_f32_16x16x32_bf16 v[84:87], v[220:223], v[232:235], v[16:19]
	v_mfma_f32_16x16x32_bf16 v[16:19], v[204:207], v[236:239], v[52:55]
	v_mfma_f32_16x16x32_bf16 v[72:75], v[212:215], v[240:243], v[16:19]
	v_mfma_f32_16x16x32_bf16 v[16:19], v[216:219], v[236:239], v[56:59]
	v_mfma_f32_16x16x32_bf16 v[120:123], v[212:215], v[28:31], v[68:71]
	v_mfma_f32_16x16x32_bf16 v[68:71], v[220:223], v[240:243], v[16:19]
	s_barrier
	s_add_i32 s69, s65, s45
	s_nop 2
	v_lshl_add_u64 v[16:17], v[208:209], 0, s[10:11]
	s_mov_b32 m0, s69
	s_add_i32 s70, s69, 0x2000
	ds_read_b128 v[36:39], v142 offset:49152
	ds_read_b128 v[40:43], v142 offset:50176
	ds_read_b128 v[224:227], v142 offset:51200
	ds_read_b128 v[228:231], v142 offset:52224
	ds_read_b128 v[232:235], v142 offset:53248
	ds_read_b128 v[236:239], v142 offset:54272
	ds_read_b128 v[240:243], v142 offset:55296
	ds_read_b128 v[244:247], v142 offset:56320
	global_load_lds_dwordx4 v[16:17], off
	v_lshl_add_u64 v[16:17], v[208:209], 0, s[12:13]
	s_mov_b32 m0, s70
	s_add_i32 s71, s71, s45
	global_load_lds_dwordx4 v[16:17], off
	v_lshl_add_u64 v[16:17], v[208:209], 0, s[14:15]
	s_mov_b32 m0, s71
	s_add_i32 s72, s71, 0x2000
	global_load_lds_dwordx4 v[16:17], off
	v_lshl_add_u64 v[16:17], v[208:209], 0, s[16:17]
	s_mov_b32 m0, s72
	s_nop 0
	global_load_lds_dwordx4 v[16:17], off
	v_lshl_add_u64 v[16:17], v[248:249], 0, s[10:11]
	s_mov_b32 m0, s53
	s_nop 0
	global_load_lds_dwordx4 v[16:17], off
	v_lshl_add_u64 v[16:17], v[248:249], 0, s[12:13]
	s_mov_b32 m0, s54
	s_nop 0
	global_load_lds_dwordx4 v[16:17], off
	s_waitcnt vmcnt(8)
	s_waitcnt lgkmcnt(0)
	s_barrier
	s_waitcnt lgkmcnt(0)
	v_mfma_f32_16x16x32_bf16 v[16:19], v[12:15], v[36:39], v[144:147]
	v_mfma_f32_16x16x32_bf16 v[60:63], v[20:23], v[40:43], v[16:19]
	v_mfma_f32_16x16x32_bf16 v[16:19], v[24:27], v[36:39], v[148:151]
	v_mfma_f32_16x16x32_bf16 v[48:51], v[200:203], v[40:43], v[16:19]
	v_mfma_f32_16x16x32_bf16 v[16:19], v[12:15], v[224:227], v[152:155]
	v_mfma_f32_16x16x32_bf16 v[44:47], v[20:23], v[228:231], v[16:19]
	v_mfma_f32_16x16x32_bf16 v[16:19], v[24:27], v[224:227], v[156:159]
	v_mfma_f32_16x16x32_bf16 v[32:35], v[200:203], v[228:231], v[16:19]
	v_mfma_f32_16x16x32_bf16 v[16:19], v[12:15], v[232:235], v[160:163]
	v_mfma_f32_16x16x32_bf16 v[0:3], v[12:15], v[240:243], v[0:3]
	v_mfma_f32_16x16x32_bf16 v[28:31], v[20:23], v[236:239], v[16:19]
	v_mfma_f32_16x16x32_bf16 v[16:19], v[24:27], v[232:235], v[164:167]
	v_mfma_f32_16x16x32_bf16 v[12:15], v[20:23], v[244:247], v[0:3]
	v_mfma_f32_16x16x32_bf16 v[0:3], v[24:27], v[240:243], v[4:7]
	v_mfma_f32_16x16x32_bf16 v[16:19], v[200:203], v[236:239], v[16:19]
	v_mfma_f32_16x16x32_bf16 v[0:3], v[200:203], v[244:247], v[0:3]
	v_mfma_f32_16x16x32_bf16 v[4:7], v[204:207], v[36:39], v[8:11]
	v_mfma_f32_16x16x32_bf16 v[56:59], v[212:215], v[40:43], v[4:7]
	v_mfma_f32_16x16x32_bf16 v[4:7], v[216:219], v[36:39], v[172:175]
	v_mfma_f32_16x16x32_bf16 v[52:55], v[220:223], v[40:43], v[4:7]
	v_mfma_f32_16x16x32_bf16 v[4:7], v[204:207], v[224:227], v[176:179]
	v_mfma_f32_16x16x32_bf16 v[40:43], v[212:215], v[228:231], v[4:7]
	v_mfma_f32_16x16x32_bf16 v[4:7], v[216:219], v[224:227], v[180:183]
	v_mfma_f32_16x16x32_bf16 v[36:39], v[220:223], v[228:231], v[4:7]
	v_mfma_f32_16x16x32_bf16 v[4:7], v[204:207], v[232:235], v[184:187]
	v_mfma_f32_16x16x32_bf16 v[24:27], v[212:215], v[236:239], v[4:7]
	v_mfma_f32_16x16x32_bf16 v[4:7], v[216:219], v[232:235], v[188:191]
	v_mfma_f32_16x16x32_bf16 v[20:23], v[220:223], v[236:239], v[4:7]
	v_mfma_f32_16x16x32_bf16 v[4:7], v[204:207], v[240:243], v[192:195]
	v_mfma_f32_16x16x32_bf16 v[8:11], v[212:215], v[244:247], v[4:7]
	v_mfma_f32_16x16x32_bf16 v[4:7], v[216:219], v[240:243], v[196:199]
	v_mfma_f32_16x16x32_bf16 v[4:7], v[220:223], v[244:247], v[4:7]
	s_barrier
.LBB0_970:
	s_add_i32 s21, s21, 2
	s_mov_b32 s38, s21
	ds_read_b128 v[144:147], v140
	ds_read_b128 v[148:151], v140 offset:1024
	ds_read_b128 v[152:155], v140 offset:2048
	ds_read_b128 v[156:159], v140 offset:3072
	ds_read_b128 v[160:163], v141
	ds_read_b128 v[164:167], v141 offset:1024
	ds_read_b128 v[172:175], v141 offset:2048
	ds_read_b128 v[176:179], v141 offset:3072
	s_ashr_i32 s39, s38, 31
	s_lshl_b64 s[74:75], s[38:39], 7
	s_add_u32 s39, s74, 0x100
	s_addc_u32 s73, s75, 0
	s_add_u32 s76, s34, s39
	s_addc_u32 s77, s35, s73
	s_add_u32 s78, s30, s39
	s_addc_u32 s73, s31, s73
	s_cmp_eq_u32 s38, 14
	s_cselect_b32 s39, s67, s77
	s_cselect_b32 s38, s68, s76
	s_cselect_b32 s77, s23, s73
	s_cselect_b32 s76, s66, s78
	s_add_u32 s74, s34, s74
	s_addc_u32 s75, s35, s75
	v_lshl_add_u64 v[208:209], s[74:75], 0, v[130:131]
	s_mov_b32 m0, s59
	v_lshl_add_u64 v[216:217], v[208:209], 0, s[14:15]
	ds_read_b128 v[180:183], v142
	ds_read_b128 v[184:187], v142 offset:1024
	ds_read_b128 v[188:191], v142 offset:2048
	ds_read_b128 v[192:195], v142 offset:3072
	ds_read_b128 v[196:199], v142 offset:4096
	ds_read_b128 v[200:203], v142 offset:5120
	ds_read_b128 v[204:207], v142 offset:6144
	ds_read_b128 v[212:215], v142 offset:7168
	global_load_lds_dwordx4 v[216:217], off
	v_lshl_add_u64 v[208:209], v[208:209], 0, s[16:17]
	s_mov_b32 m0, s60
	s_nop 0
	global_load_lds_dwordx4 v[208:209], off
	s_waitcnt vmcnt(8)
	s_waitcnt lgkmcnt(0)
	s_barrier
	s_waitcnt lgkmcnt(0)
	v_mfma_f32_16x16x32_bf16 v[124:127], v[144:147], v[180:183], v[124:127]
	v_mfma_f32_16x16x32_bf16 v[112:115], v[152:155], v[180:183], v[112:115]
	v_mfma_f32_16x16x32_bf16 v[108:111], v[144:147], v[188:191], v[108:111]
	v_mfma_f32_16x16x32_bf16 v[96:99], v[152:155], v[188:191], v[96:99]
	v_mfma_f32_16x16x32_bf16 v[92:95], v[144:147], v[196:199], v[92:95]
	v_mfma_f32_16x16x32_bf16 v[80:83], v[152:155], v[196:199], v[80:83]
	v_mfma_f32_16x16x32_bf16 v[76:79], v[144:147], v[204:207], v[76:79]
	v_mfma_f32_16x16x32_bf16 v[64:67], v[152:155], v[204:207], v[64:67]
	v_mfma_f32_16x16x32_bf16 v[124:127], v[148:151], v[184:187], v[124:127]
	v_mfma_f32_16x16x32_bf16 v[112:115], v[156:159], v[184:187], v[112:115]
	v_mfma_f32_16x16x32_bf16 v[108:111], v[148:151], v[192:195], v[108:111]
	v_mfma_f32_16x16x32_bf16 v[96:99], v[156:159], v[192:195], v[96:99]
	v_mfma_f32_16x16x32_bf16 v[92:95], v[148:151], v[200:203], v[92:95]
	v_mfma_f32_16x16x32_bf16 v[80:83], v[156:159], v[200:203], v[80:83]
	v_mfma_f32_16x16x32_bf16 v[76:79], v[148:151], v[212:215], v[76:79]
	v_mfma_f32_16x16x32_bf16 v[64:67], v[156:159], v[212:215], v[64:67]
	v_mfma_f32_16x16x32_bf16 v[120:123], v[160:163], v[180:183], v[120:123]
	v_mfma_f32_16x16x32_bf16 v[116:119], v[172:175], v[180:183], v[116:119]
	v_mfma_f32_16x16x32_bf16 v[104:107], v[160:163], v[188:191], v[104:107]
	v_mfma_f32_16x16x32_bf16 v[100:103], v[172:175], v[188:191], v[100:103]
	v_mfma_f32_16x16x32_bf16 v[88:91], v[160:163], v[196:199], v[88:91]
	v_mfma_f32_16x16x32_bf16 v[84:87], v[172:175], v[196:199], v[84:87]
	v_mfma_f32_16x16x32_bf16 v[72:75], v[160:163], v[204:207], v[72:75]
	v_mfma_f32_16x16x32_bf16 v[68:71], v[172:175], v[204:207], v[68:71]
	v_mfma_f32_16x16x32_bf16 v[120:123], v[164:167], v[184:187], v[120:123]
	v_mfma_f32_16x16x32_bf16 v[116:119], v[176:179], v[184:187], v[116:119]
	v_mfma_f32_16x16x32_bf16 v[104:107], v[164:167], v[192:195], v[104:107]
	v_mfma_f32_16x16x32_bf16 v[100:103], v[176:179], v[192:195], v[100:103]
	v_mfma_f32_16x16x32_bf16 v[88:91], v[164:167], v[200:203], v[88:91]
	v_mfma_f32_16x16x32_bf16 v[84:87], v[176:179], v[200:203], v[84:87]
	v_mfma_f32_16x16x32_bf16 v[72:75], v[164:167], v[212:215], v[72:75]
	v_mfma_f32_16x16x32_bf16 v[68:71], v[176:179], v[212:215], v[68:71]
	s_barrier
	s_mov_b32 m0, s61
	v_lshl_add_u64 v[208:209], s[76:77], 0, v[128:129]
	ds_read_b128 v[180:183], v142 offset:16384
	ds_read_b128 v[184:187], v142 offset:17408
	ds_read_b128 v[188:191], v142 offset:18432
	ds_read_b128 v[192:195], v142 offset:19456
	ds_read_b128 v[196:199], v142 offset:20480
	ds_read_b128 v[200:203], v142 offset:21504
	ds_read_b128 v[204:207], v142 offset:22528
	ds_read_b128 v[212:215], v142 offset:23552
	global_load_lds_dwordx4 v[208:209], off
	v_lshl_add_u64 v[216:217], v[208:209], 0, s[0:1]
	s_mov_b32 m0, s62
	s_nop 0
	global_load_lds_dwordx4 v[216:217], off
	v_lshl_add_u64 v[216:217], v[208:209], 0, s[2:3]
	s_mov_b32 m0, s63
	s_nop 0
	global_load_lds_dwordx4 v[216:217], off
	v_lshl_add_u64 v[216:217], v[208:209], 0, s[4:5]
	s_mov_b32 m0, s64
	s_nop 0
	global_load_lds_dwordx4 v[216:217], off
	v_lshl_add_u64 v[216:217], s[38:39], 0, v[130:131]
	s_mov_b32 m0, s48
	v_lshl_add_u64 v[218:219], v[216:217], 0, s[0:1]
	global_load_lds_dwordx4 v[216:217], off
	s_mov_b32 m0, s49
	s_nop 0
	global_load_lds_dwordx4 v[218:219], off
	s_waitcnt vmcnt(8)
	s_waitcnt lgkmcnt(0)
	s_barrier
	s_waitcnt lgkmcnt(0)
	v_mfma_f32_16x16x32_bf16 v[60:63], v[144:147], v[180:183], v[60:63]
	v_mfma_f32_16x16x32_bf16 v[48:51], v[152:155], v[180:183], v[48:51]
	v_mfma_f32_16x16x32_bf16 v[44:47], v[144:147], v[188:191], v[44:47]
	v_mfma_f32_16x16x32_bf16 v[32:35], v[152:155], v[188:191], v[32:35]
	v_mfma_f32_16x16x32_bf16 v[28:31], v[144:147], v[196:199], v[28:31]
	v_mfma_f32_16x16x32_bf16 v[16:19], v[152:155], v[196:199], v[16:19]
	v_mfma_f32_16x16x32_bf16 v[12:15], v[144:147], v[204:207], v[12:15]
	v_mfma_f32_16x16x32_bf16 v[0:3], v[152:155], v[204:207], v[0:3]
	v_mfma_f32_16x16x32_bf16 v[60:63], v[148:151], v[184:187], v[60:63]
	v_mfma_f32_16x16x32_bf16 v[48:51], v[156:159], v[184:187], v[48:51]
	v_mfma_f32_16x16x32_bf16 v[44:47], v[148:151], v[192:195], v[44:47]
	v_mfma_f32_16x16x32_bf16 v[32:35], v[156:159], v[192:195], v[32:35]
	v_mfma_f32_16x16x32_bf16 v[28:31], v[148:151], v[200:203], v[28:31]
	v_mfma_f32_16x16x32_bf16 v[16:19], v[156:159], v[200:203], v[16:19]
	v_mfma_f32_16x16x32_bf16 v[12:15], v[148:151], v[212:215], v[12:15]
	v_mfma_f32_16x16x32_bf16 v[0:3], v[156:159], v[212:215], v[0:3]
	v_mfma_f32_16x16x32_bf16 v[56:59], v[160:163], v[180:183], v[56:59]
	v_mfma_f32_16x16x32_bf16 v[52:55], v[172:175], v[180:183], v[52:55]
	v_mfma_f32_16x16x32_bf16 v[40:43], v[160:163], v[188:191], v[40:43]
	v_mfma_f32_16x16x32_bf16 v[36:39], v[172:175], v[188:191], v[36:39]
	v_mfma_f32_16x16x32_bf16 v[24:27], v[160:163], v[196:199], v[24:27]
	v_mfma_f32_16x16x32_bf16 v[20:23], v[172:175], v[196:199], v[20:23]
	v_mfma_f32_16x16x32_bf16 v[8:11], v[160:163], v[204:207], v[8:11]
	v_mfma_f32_16x16x32_bf16 v[4:7], v[172:175], v[204:207], v[4:7]
	v_mfma_f32_16x16x32_bf16 v[56:59], v[164:167], v[184:187], v[56:59]
	v_mfma_f32_16x16x32_bf16 v[52:55], v[176:179], v[184:187], v[52:55]
	v_mfma_f32_16x16x32_bf16 v[40:43], v[164:167], v[192:195], v[40:43]
	v_mfma_f32_16x16x32_bf16 v[36:39], v[176:179], v[192:195], v[36:39]
	v_mfma_f32_16x16x32_bf16 v[24:27], v[164:167], v[200:203], v[24:27]
	v_mfma_f32_16x16x32_bf16 v[20:23], v[176:179], v[200:203], v[20:23]
	v_mfma_f32_16x16x32_bf16 v[8:11], v[164:167], v[212:215], v[8:11]
	v_mfma_f32_16x16x32_bf16 v[4:7], v[176:179], v[212:215], v[4:7]
	s_barrier
	ds_read_b128 v[144:147], v143
	ds_read_b128 v[148:151], v143 offset:1024
	ds_read_b128 v[152:155], v143 offset:2048
	ds_read_b128 v[156:159], v143 offset:3072
	ds_read_b128 v[160:163], v136
	ds_read_b128 v[164:167], v136 offset:1024
	ds_read_b128 v[172:175], v136 offset:2048
	ds_read_b128 v[176:179], v136 offset:3072
	s_mov_b32 m0, s50
	v_lshl_add_u64 v[218:219], v[216:217], 0, s[2:3]
	ds_read_b128 v[180:183], v142 offset:32768
	ds_read_b128 v[184:187], v142 offset:33792
	ds_read_b128 v[188:191], v142 offset:34816
	ds_read_b128 v[192:195], v142 offset:35840
	ds_read_b128 v[196:199], v142 offset:36864
	ds_read_b128 v[200:203], v142 offset:37888
	ds_read_b128 v[204:207], v142 offset:38912
	ds_read_b128 v[212:215], v142 offset:39936
	global_load_lds_dwordx4 v[218:219], off
	v_lshl_add_u64 v[218:219], v[216:217], 0, s[4:5]
	s_mov_b32 m0, s51
	s_nop 0
	global_load_lds_dwordx4 v[218:219], off
	s_waitcnt vmcnt(8)
	s_waitcnt lgkmcnt(0)
	s_barrier
	s_waitcnt lgkmcnt(0)
	v_mfma_f32_16x16x32_bf16 v[124:127], v[144:147], v[180:183], v[124:127]
	v_mfma_f32_16x16x32_bf16 v[112:115], v[152:155], v[180:183], v[112:115]
	v_mfma_f32_16x16x32_bf16 v[108:111], v[144:147], v[188:191], v[108:111]
	v_mfma_f32_16x16x32_bf16 v[96:99], v[152:155], v[188:191], v[96:99]
	v_mfma_f32_16x16x32_bf16 v[92:95], v[144:147], v[196:199], v[92:95]
	v_mfma_f32_16x16x32_bf16 v[80:83], v[152:155], v[196:199], v[80:83]
	v_mfma_f32_16x16x32_bf16 v[76:79], v[144:147], v[204:207], v[76:79]
	v_mfma_f32_16x16x32_bf16 v[64:67], v[152:155], v[204:207], v[64:67]
	v_mfma_f32_16x16x32_bf16 v[124:127], v[148:151], v[184:187], v[124:127]
	v_mfma_f32_16x16x32_bf16 v[112:115], v[156:159], v[184:187], v[112:115]
	v_mfma_f32_16x16x32_bf16 v[108:111], v[148:151], v[192:195], v[108:111]
	v_mfma_f32_16x16x32_bf16 v[96:99], v[156:159], v[192:195], v[96:99]
	v_mfma_f32_16x16x32_bf16 v[92:95], v[148:151], v[200:203], v[92:95]
	v_mfma_f32_16x16x32_bf16 v[80:83], v[156:159], v[200:203], v[80:83]
	v_mfma_f32_16x16x32_bf16 v[76:79], v[148:151], v[212:215], v[76:79]
	v_mfma_f32_16x16x32_bf16 v[64:67], v[156:159], v[212:215], v[64:67]
	v_mfma_f32_16x16x32_bf16 v[120:123], v[160:163], v[180:183], v[120:123]
	v_mfma_f32_16x16x32_bf16 v[116:119], v[172:175], v[180:183], v[116:119]
	v_mfma_f32_16x16x32_bf16 v[104:107], v[160:163], v[188:191], v[104:107]
	v_mfma_f32_16x16x32_bf16 v[100:103], v[172:175], v[188:191], v[100:103]
	v_mfma_f32_16x16x32_bf16 v[88:91], v[160:163], v[196:199], v[88:91]
	v_mfma_f32_16x16x32_bf16 v[84:87], v[172:175], v[196:199], v[84:87]
	v_mfma_f32_16x16x32_bf16 v[72:75], v[160:163], v[204:207], v[72:75]
	v_mfma_f32_16x16x32_bf16 v[68:71], v[172:175], v[204:207], v[68:71]
	v_mfma_f32_16x16x32_bf16 v[120:123], v[164:167], v[184:187], v[120:123]
	v_mfma_f32_16x16x32_bf16 v[116:119], v[176:179], v[184:187], v[116:119]
	v_mfma_f32_16x16x32_bf16 v[104:107], v[164:167], v[192:195], v[104:107]
	v_mfma_f32_16x16x32_bf16 v[100:103], v[176:179], v[192:195], v[100:103]
	v_mfma_f32_16x16x32_bf16 v[88:91], v[164:167], v[200:203], v[88:91]
	v_mfma_f32_16x16x32_bf16 v[84:87], v[176:179], v[200:203], v[84:87]
	v_mfma_f32_16x16x32_bf16 v[72:75], v[164:167], v[212:215], v[72:75]
	v_mfma_f32_16x16x32_bf16 v[68:71], v[176:179], v[212:215], v[68:71]
	s_barrier
	s_mov_b32 m0, s69
	v_lshl_add_u64 v[218:219], v[208:209], 0, s[10:11]
	ds_read_b128 v[180:183], v142 offset:49152
	ds_read_b128 v[184:187], v142 offset:50176
	ds_read_b128 v[188:191], v142 offset:51200
	ds_read_b128 v[192:195], v142 offset:52224
	ds_read_b128 v[196:199], v142 offset:53248
	ds_read_b128 v[200:203], v142 offset:54272
	ds_read_b128 v[204:207], v142 offset:55296
	ds_read_b128 v[212:215], v142 offset:56320
	global_load_lds_dwordx4 v[218:219], off
	v_lshl_add_u64 v[218:219], v[208:209], 0, s[12:13]
	s_mov_b32 m0, s70
	s_nop 0
	global_load_lds_dwordx4 v[218:219], off
	v_lshl_add_u64 v[218:219], v[208:209], 0, s[14:15]
	s_mov_b32 m0, s71
	v_lshl_add_u64 v[208:209], v[208:209], 0, s[16:17]
	global_load_lds_dwordx4 v[218:219], off
	s_mov_b32 m0, s72
	s_nop 0
	global_load_lds_dwordx4 v[208:209], off
	v_lshl_add_u64 v[208:209], v[216:217], 0, s[10:11]
	s_mov_b32 m0, s53
	s_nop 0
	global_load_lds_dwordx4 v[208:209], off
	v_lshl_add_u64 v[208:209], v[216:217], 0, s[12:13]
	s_mov_b32 m0, s54
	s_nop 0
	global_load_lds_dwordx4 v[208:209], off
	s_waitcnt vmcnt(8)
	s_waitcnt lgkmcnt(0)
	s_barrier
	s_waitcnt lgkmcnt(0)
	v_mfma_f32_16x16x32_bf16 v[60:63], v[144:147], v[180:183], v[60:63]
	v_mfma_f32_16x16x32_bf16 v[48:51], v[152:155], v[180:183], v[48:51]
	v_mfma_f32_16x16x32_bf16 v[44:47], v[144:147], v[188:191], v[44:47]
	v_mfma_f32_16x16x32_bf16 v[32:35], v[152:155], v[188:191], v[32:35]
	v_mfma_f32_16x16x32_bf16 v[28:31], v[144:147], v[196:199], v[28:31]
	v_mfma_f32_16x16x32_bf16 v[16:19], v[152:155], v[196:199], v[16:19]
	v_mfma_f32_16x16x32_bf16 v[12:15], v[144:147], v[204:207], v[12:15]
	v_mfma_f32_16x16x32_bf16 v[0:3], v[152:155], v[204:207], v[0:3]
	v_mfma_f32_16x16x32_bf16 v[60:63], v[148:151], v[184:187], v[60:63]
	v_mfma_f32_16x16x32_bf16 v[48:51], v[156:159], v[184:187], v[48:51]
	v_mfma_f32_16x16x32_bf16 v[44:47], v[148:151], v[192:195], v[44:47]
	v_mfma_f32_16x16x32_bf16 v[32:35], v[156:159], v[192:195], v[32:35]
	v_mfma_f32_16x16x32_bf16 v[28:31], v[148:151], v[200:203], v[28:31]
	v_mfma_f32_16x16x32_bf16 v[16:19], v[156:159], v[200:203], v[16:19]
	v_mfma_f32_16x16x32_bf16 v[12:15], v[148:151], v[212:215], v[12:15]
	v_mfma_f32_16x16x32_bf16 v[0:3], v[156:159], v[212:215], v[0:3]
	v_mfma_f32_16x16x32_bf16 v[56:59], v[160:163], v[180:183], v[56:59]
	v_mfma_f32_16x16x32_bf16 v[52:55], v[172:175], v[180:183], v[52:55]
	v_mfma_f32_16x16x32_bf16 v[40:43], v[160:163], v[188:191], v[40:43]
	v_mfma_f32_16x16x32_bf16 v[36:39], v[172:175], v[188:191], v[36:39]
	v_mfma_f32_16x16x32_bf16 v[24:27], v[160:163], v[196:199], v[24:27]
	v_mfma_f32_16x16x32_bf16 v[20:23], v[172:175], v[196:199], v[20:23]
	v_mfma_f32_16x16x32_bf16 v[8:11], v[160:163], v[204:207], v[8:11]
	v_mfma_f32_16x16x32_bf16 v[4:7], v[172:175], v[204:207], v[4:7]
	v_mfma_f32_16x16x32_bf16 v[56:59], v[164:167], v[184:187], v[56:59]
	v_mfma_f32_16x16x32_bf16 v[52:55], v[176:179], v[184:187], v[52:55]
	v_mfma_f32_16x16x32_bf16 v[40:43], v[164:167], v[192:195], v[40:43]
	v_mfma_f32_16x16x32_bf16 v[36:39], v[176:179], v[192:195], v[36:39]
	v_mfma_f32_16x16x32_bf16 v[24:27], v[164:167], v[200:203], v[24:27]
	v_mfma_f32_16x16x32_bf16 v[20:23], v[176:179], v[200:203], v[20:23]
	v_mfma_f32_16x16x32_bf16 v[8:11], v[164:167], v[212:215], v[8:11]
	v_mfma_f32_16x16x32_bf16 v[4:7], v[176:179], v[212:215], v[4:7]
	s_barrier
	s_cmp_gt_u32 s21, 13
	s_cbranch_scc0 .LBB0_970
	s_and_b64 vcc, exec, s[18:19]
	s_cbranch_vccz .LBB0_973
	s_barrier

.LBB0_1046:
	s_add_i32 s55, s55, 2
	s_mov_b32 s56, s55
	ds_read_b128 v[144:147], v140
	ds_read_b128 v[148:151], v140 offset:1024
	ds_read_b128 v[152:155], v140 offset:2048
	ds_read_b128 v[156:159], v140 offset:3072
	ds_read_b128 v[160:163], v141
	ds_read_b128 v[164:167], v141 offset:1024
	ds_read_b128 v[172:175], v141 offset:2048
	ds_read_b128 v[176:179], v141 offset:3072
	s_ashr_i32 s57, s56, 31
	s_lshl_b64 s[58:59], s[56:57], 7
	s_add_u32 s57, s58, 0x100
	s_addc_u32 s60, s59, 0
	s_add_u32 s61, s24, s57
	s_addc_u32 s62, s25, s60
	s_add_u32 s63, s22, s57
	s_addc_u32 s60, s23, s60
	s_cmp_eq_u32 s56, 42
	s_cselect_b32 s57, s1, s62
	s_cselect_b32 s56, s0, s61
	s_cselect_b32 s61, s27, s60
	s_cselect_b32 s60, s26, s63
	v_lshl_add_u64 v[208:209], v[136:137], 0, s[58:59]
	v_lshl_add_u64 v[216:217], v[208:209], 0, s[12:13]
	s_add_i32 m0, s39, 0xc000
	ds_read_b128 v[180:183], v142
	ds_read_b128 v[184:187], v142 offset:1024
	ds_read_b128 v[188:191], v142 offset:2048
	ds_read_b128 v[192:195], v142 offset:3072
	ds_read_b128 v[196:199], v142 offset:4096
	ds_read_b128 v[200:203], v142 offset:5120
	ds_read_b128 v[204:207], v142 offset:6144
	ds_read_b128 v[212:215], v142 offset:7168
	global_load_lds_dwordx4 v[216:217], off
	v_lshl_add_u64 v[208:209], v[208:209], 0, s[14:15]
	s_add_i32 m0, s39, 0xe000
	s_nop 0
	global_load_lds_dwordx4 v[208:209], off
	s_waitcnt vmcnt(8)
	s_waitcnt lgkmcnt(0)
	s_barrier
	s_waitcnt lgkmcnt(0)
	v_mfma_f32_16x16x32_bf16 v[124:127], v[144:147], v[180:183], v[124:127]
	v_mfma_f32_16x16x32_bf16 v[120:123], v[152:155], v[180:183], v[120:123]
	v_mfma_f32_16x16x32_bf16 v[116:119], v[144:147], v[188:191], v[116:119]
	v_mfma_f32_16x16x32_bf16 v[112:115], v[152:155], v[188:191], v[112:115]
	v_mfma_f32_16x16x32_bf16 v[100:103], v[144:147], v[196:199], v[100:103]
	v_mfma_f32_16x16x32_bf16 v[96:99], v[152:155], v[196:199], v[96:99]
	v_mfma_f32_16x16x32_bf16 v[84:87], v[144:147], v[204:207], v[84:87]
	v_mfma_f32_16x16x32_bf16 v[80:83], v[152:155], v[204:207], v[80:83]
	v_mfma_f32_16x16x32_bf16 v[124:127], v[148:151], v[184:187], v[124:127]
	v_mfma_f32_16x16x32_bf16 v[120:123], v[156:159], v[184:187], v[120:123]
	v_mfma_f32_16x16x32_bf16 v[116:119], v[148:151], v[192:195], v[116:119]
	v_mfma_f32_16x16x32_bf16 v[112:115], v[156:159], v[192:195], v[112:115]
	v_mfma_f32_16x16x32_bf16 v[100:103], v[148:151], v[200:203], v[100:103]
	v_mfma_f32_16x16x32_bf16 v[96:99], v[156:159], v[200:203], v[96:99]
	v_mfma_f32_16x16x32_bf16 v[84:87], v[148:151], v[212:215], v[84:87]
	v_mfma_f32_16x16x32_bf16 v[80:83], v[156:159], v[212:215], v[80:83]
	v_mfma_f32_16x16x32_bf16 v[108:111], v[160:163], v[180:183], v[108:111]
	v_mfma_f32_16x16x32_bf16 v[104:107], v[172:175], v[180:183], v[104:107]
	v_mfma_f32_16x16x32_bf16 v[92:95], v[160:163], v[188:191], v[92:95]
	v_mfma_f32_16x16x32_bf16 v[88:91], v[172:175], v[188:191], v[88:91]
	v_mfma_f32_16x16x32_bf16 v[76:79], v[160:163], v[196:199], v[76:79]
	v_mfma_f32_16x16x32_bf16 v[72:75], v[172:175], v[196:199], v[72:75]
	v_mfma_f32_16x16x32_bf16 v[68:71], v[160:163], v[204:207], v[68:71]
	v_mfma_f32_16x16x32_bf16 v[64:67], v[172:175], v[204:207], v[64:67]
	v_mfma_f32_16x16x32_bf16 v[108:111], v[164:167], v[184:187], v[108:111]
	v_mfma_f32_16x16x32_bf16 v[104:107], v[176:179], v[184:187], v[104:107]
	v_mfma_f32_16x16x32_bf16 v[92:95], v[164:167], v[192:195], v[92:95]
	v_mfma_f32_16x16x32_bf16 v[88:91], v[176:179], v[192:195], v[88:91]
	v_mfma_f32_16x16x32_bf16 v[76:79], v[164:167], v[200:203], v[76:79]
	v_mfma_f32_16x16x32_bf16 v[72:75], v[176:179], v[200:203], v[72:75]
	v_mfma_f32_16x16x32_bf16 v[68:71], v[164:167], v[212:215], v[68:71]
	v_mfma_f32_16x16x32_bf16 v[64:67], v[176:179], v[212:215], v[64:67]
	s_barrier
	s_add_i32 s58, s49, s38
	v_lshl_add_u64 v[208:209], s[60:61], 0, v[130:131]
	s_mov_b32 m0, s58
	ds_read_b128 v[180:183], v142 offset:16384
	ds_read_b128 v[184:187], v142 offset:17408
	ds_read_b128 v[188:191], v142 offset:18432
	ds_read_b128 v[192:195], v142 offset:19456
	ds_read_b128 v[196:199], v142 offset:20480
	ds_read_b128 v[200:203], v142 offset:21504
	ds_read_b128 v[204:207], v142 offset:22528
	ds_read_b128 v[212:215], v142 offset:23552
	global_load_lds_dwordx4 v[208:209], off
	v_lshl_add_u64 v[216:217], v[208:209], 0, s[2:3]
	s_add_i32 m0, s58, 0x2000
	s_add_i32 s58, s50, s38
	global_load_lds_dwordx4 v[216:217], off
	v_lshl_add_u64 v[216:217], v[208:209], 0, s[4:5]
	s_mov_b32 m0, s58
	s_nop 0
	global_load_lds_dwordx4 v[216:217], off
	v_lshl_add_u64 v[216:217], v[208:209], 0, s[6:7]
	s_add_i32 m0, s58, 0x2000
	s_nop 0
	global_load_lds_dwordx4 v[216:217], off
	v_lshl_add_u64 v[216:217], s[56:57], 0, v[128:129]
	s_mov_b32 m0, s39
	v_lshl_add_u64 v[218:219], v[216:217], 0, s[2:3]
	global_load_lds_dwordx4 v[216:217], off
	s_mov_b32 m0, s40
	s_nop 0
	global_load_lds_dwordx4 v[218:219], off
	s_waitcnt vmcnt(8)
	s_waitcnt lgkmcnt(0)
	s_barrier
	s_waitcnt lgkmcnt(0)
	v_mfma_f32_16x16x32_bf16 v[60:63], v[144:147], v[180:183], v[60:63]
	v_mfma_f32_16x16x32_bf16 v[56:59], v[152:155], v[180:183], v[56:59]
	v_mfma_f32_16x16x32_bf16 v[52:55], v[144:147], v[188:191], v[52:55]
	v_mfma_f32_16x16x32_bf16 v[48:51], v[152:155], v[188:191], v[48:51]
	v_mfma_f32_16x16x32_bf16 v[36:39], v[144:147], v[196:199], v[36:39]
	v_mfma_f32_16x16x32_bf16 v[32:35], v[152:155], v[196:199], v[32:35]
	v_mfma_f32_16x16x32_bf16 v[20:23], v[144:147], v[204:207], v[20:23]
	v_mfma_f32_16x16x32_bf16 v[16:19], v[152:155], v[204:207], v[16:19]
	v_mfma_f32_16x16x32_bf16 v[60:63], v[148:151], v[184:187], v[60:63]
	v_mfma_f32_16x16x32_bf16 v[56:59], v[156:159], v[184:187], v[56:59]
	v_mfma_f32_16x16x32_bf16 v[52:55], v[148:151], v[192:195], v[52:55]
	v_mfma_f32_16x16x32_bf16 v[48:51], v[156:159], v[192:195], v[48:51]
	v_mfma_f32_16x16x32_bf16 v[36:39], v[148:151], v[200:203], v[36:39]
	v_mfma_f32_16x16x32_bf16 v[32:35], v[156:159], v[200:203], v[32:35]
	v_mfma_f32_16x16x32_bf16 v[20:23], v[148:151], v[212:215], v[20:23]
	v_mfma_f32_16x16x32_bf16 v[16:19], v[156:159], v[212:215], v[16:19]
	v_mfma_f32_16x16x32_bf16 v[44:47], v[160:163], v[180:183], v[44:47]
	v_mfma_f32_16x16x32_bf16 v[40:43], v[172:175], v[180:183], v[40:43]
	v_mfma_f32_16x16x32_bf16 v[28:31], v[160:163], v[188:191], v[28:31]
	v_mfma_f32_16x16x32_bf16 v[24:27], v[172:175], v[188:191], v[24:27]
	v_mfma_f32_16x16x32_bf16 v[12:15], v[160:163], v[196:199], v[12:15]
	v_mfma_f32_16x16x32_bf16 v[8:11], v[172:175], v[196:199], v[8:11]
	v_mfma_f32_16x16x32_bf16 v[4:7], v[160:163], v[204:207], v[4:7]
	v_mfma_f32_16x16x32_bf16 v[0:3], v[172:175], v[204:207], v[0:3]
	v_mfma_f32_16x16x32_bf16 v[44:47], v[164:167], v[184:187], v[44:47]
	v_mfma_f32_16x16x32_bf16 v[40:43], v[176:179], v[184:187], v[40:43]
	v_mfma_f32_16x16x32_bf16 v[28:31], v[164:167], v[192:195], v[28:31]
	v_mfma_f32_16x16x32_bf16 v[24:27], v[176:179], v[192:195], v[24:27]
	v_mfma_f32_16x16x32_bf16 v[12:15], v[164:167], v[200:203], v[12:15]
	v_mfma_f32_16x16x32_bf16 v[8:11], v[176:179], v[200:203], v[8:11]
	v_mfma_f32_16x16x32_bf16 v[4:7], v[164:167], v[212:215], v[4:7]
	v_mfma_f32_16x16x32_bf16 v[0:3], v[176:179], v[212:215], v[0:3]
	s_barrier
	s_add_i32 s56, 0, 0x18000
	v_add_u32_e32 v143, s56, v139
	s_add_i32 s57, 0, 0x1c000
	ds_read_b128 v[144:147], v143
	ds_read_b128 v[148:151], v143 offset:1024
	ds_read_b128 v[152:155], v143 offset:2048
	ds_read_b128 v[156:159], v143 offset:3072
	v_add_u32_e32 v143, s57, v139
	ds_read_b128 v[160:163], v143
	ds_read_b128 v[164:167], v143 offset:1024
	ds_read_b128 v[172:175], v143 offset:2048
	ds_read_b128 v[176:179], v143 offset:3072
	s_mov_b32 m0, s41
	v_lshl_add_u64 v[218:219], v[216:217], 0, s[4:5]
	ds_read_b128 v[180:183], v142 offset:32768
	ds_read_b128 v[184:187], v142 offset:33792
	ds_read_b128 v[188:191], v142 offset:34816
	ds_read_b128 v[192:195], v142 offset:35840
	ds_read_b128 v[196:199], v142 offset:36864
	ds_read_b128 v[200:203], v142 offset:37888
	ds_read_b128 v[204:207], v142 offset:38912
	ds_read_b128 v[212:215], v142 offset:39936
	global_load_lds_dwordx4 v[218:219], off
	v_lshl_add_u64 v[218:219], v[216:217], 0, s[6:7]
	s_mov_b32 m0, s42
	s_nop 0
	global_load_lds_dwordx4 v[218:219], off
	s_waitcnt vmcnt(8)
	s_waitcnt lgkmcnt(0)
	s_barrier
	s_waitcnt lgkmcnt(0)
	v_mfma_f32_16x16x32_bf16 v[124:127], v[144:147], v[180:183], v[124:127]
	v_mfma_f32_16x16x32_bf16 v[120:123], v[152:155], v[180:183], v[120:123]
	v_mfma_f32_16x16x32_bf16 v[116:119], v[144:147], v[188:191], v[116:119]
	v_mfma_f32_16x16x32_bf16 v[112:115], v[152:155], v[188:191], v[112:115]
	v_mfma_f32_16x16x32_bf16 v[100:103], v[144:147], v[196:199], v[100:103]
	v_mfma_f32_16x16x32_bf16 v[96:99], v[152:155], v[196:199], v[96:99]
	v_mfma_f32_16x16x32_bf16 v[84:87], v[144:147], v[204:207], v[84:87]
	v_mfma_f32_16x16x32_bf16 v[80:83], v[152:155], v[204:207], v[80:83]
	v_mfma_f32_16x16x32_bf16 v[124:127], v[148:151], v[184:187], v[124:127]
	v_mfma_f32_16x16x32_bf16 v[120:123], v[156:159], v[184:187], v[120:123]
	v_mfma_f32_16x16x32_bf16 v[116:119], v[148:151], v[192:195], v[116:119]
	v_mfma_f32_16x16x32_bf16 v[112:115], v[156:159], v[192:195], v[112:115]
	v_mfma_f32_16x16x32_bf16 v[100:103], v[148:151], v[200:203], v[100:103]
	v_mfma_f32_16x16x32_bf16 v[96:99], v[156:159], v[200:203], v[96:99]
	v_mfma_f32_16x16x32_bf16 v[84:87], v[148:151], v[212:215], v[84:87]
	v_mfma_f32_16x16x32_bf16 v[80:83], v[156:159], v[212:215], v[80:83]
	v_mfma_f32_16x16x32_bf16 v[108:111], v[160:163], v[180:183], v[108:111]
	v_mfma_f32_16x16x32_bf16 v[104:107], v[172:175], v[180:183], v[104:107]
	v_mfma_f32_16x16x32_bf16 v[92:95], v[160:163], v[188:191], v[92:95]
	v_mfma_f32_16x16x32_bf16 v[88:91], v[172:175], v[188:191], v[88:91]
	v_mfma_f32_16x16x32_bf16 v[76:79], v[160:163], v[196:199], v[76:79]
	v_mfma_f32_16x16x32_bf16 v[72:75], v[172:175], v[196:199], v[72:75]
	v_mfma_f32_16x16x32_bf16 v[68:71], v[160:163], v[204:207], v[68:71]
	v_mfma_f32_16x16x32_bf16 v[64:67], v[172:175], v[204:207], v[64:67]
	v_mfma_f32_16x16x32_bf16 v[108:111], v[164:167], v[184:187], v[108:111]
	v_mfma_f32_16x16x32_bf16 v[104:107], v[176:179], v[184:187], v[104:107]
	v_mfma_f32_16x16x32_bf16 v[92:95], v[164:167], v[192:195], v[92:95]
	v_mfma_f32_16x16x32_bf16 v[88:91], v[176:179], v[192:195], v[88:91]
	v_mfma_f32_16x16x32_bf16 v[76:79], v[164:167], v[200:203], v[76:79]
	v_mfma_f32_16x16x32_bf16 v[72:75], v[176:179], v[200:203], v[72:75]
	v_mfma_f32_16x16x32_bf16 v[68:71], v[164:167], v[212:215], v[68:71]
	v_mfma_f32_16x16x32_bf16 v[64:67], v[176:179], v[212:215], v[64:67]
	s_barrier
	s_add_i32 s56, s56, s38
	v_lshl_add_u64 v[218:219], v[208:209], 0, s[12:13]
	s_mov_b32 m0, s56
	ds_read_b128 v[180:183], v142 offset:49152
	ds_read_b128 v[184:187], v142 offset:50176
	ds_read_b128 v[188:191], v142 offset:51200
	ds_read_b128 v[192:195], v142 offset:52224
	ds_read_b128 v[196:199], v142 offset:53248
	ds_read_b128 v[200:203], v142 offset:54272
	ds_read_b128 v[204:207], v142 offset:55296
	ds_read_b128 v[212:215], v142 offset:56320
	global_load_lds_dwordx4 v[218:219], off
	v_lshl_add_u64 v[218:219], v[208:209], 0, s[14:15]
	s_add_i32 m0, s56, 0x2000
	s_add_i32 s56, s57, s38
	global_load_lds_dwordx4 v[218:219], off
	v_lshl_add_u64 v[218:219], v[208:209], 0, s[16:17]
	s_mov_b32 m0, s56
	v_lshl_add_u64 v[208:209], v[208:209], 0, s[18:19]
	global_load_lds_dwordx4 v[218:219], off
	s_add_i32 m0, s56, 0x2000
	s_nop 0
	global_load_lds_dwordx4 v[208:209], off
	v_lshl_add_u64 v[208:209], v[216:217], 0, s[12:13]
	s_mov_b32 m0, s44
	s_nop 0
	global_load_lds_dwordx4 v[208:209], off
	v_lshl_add_u64 v[208:209], v[216:217], 0, s[14:15]
	s_mov_b32 m0, s45
	s_nop 0
	global_load_lds_dwordx4 v[208:209], off
	s_waitcnt vmcnt(8)
	s_waitcnt lgkmcnt(0)
	s_barrier
	s_waitcnt lgkmcnt(0)
	v_mfma_f32_16x16x32_bf16 v[60:63], v[144:147], v[180:183], v[60:63]
	v_mfma_f32_16x16x32_bf16 v[56:59], v[152:155], v[180:183], v[56:59]
	v_mfma_f32_16x16x32_bf16 v[52:55], v[144:147], v[188:191], v[52:55]
	v_mfma_f32_16x16x32_bf16 v[48:51], v[152:155], v[188:191], v[48:51]
	v_mfma_f32_16x16x32_bf16 v[36:39], v[144:147], v[196:199], v[36:39]
	v_mfma_f32_16x16x32_bf16 v[32:35], v[152:155], v[196:199], v[32:35]
	v_mfma_f32_16x16x32_bf16 v[20:23], v[144:147], v[204:207], v[20:23]
	v_mfma_f32_16x16x32_bf16 v[16:19], v[152:155], v[204:207], v[16:19]
	v_mfma_f32_16x16x32_bf16 v[60:63], v[148:151], v[184:187], v[60:63]
	v_mfma_f32_16x16x32_bf16 v[56:59], v[156:159], v[184:187], v[56:59]
	v_mfma_f32_16x16x32_bf16 v[52:55], v[148:151], v[192:195], v[52:55]
	v_mfma_f32_16x16x32_bf16 v[48:51], v[156:159], v[192:195], v[48:51]
	v_mfma_f32_16x16x32_bf16 v[36:39], v[148:151], v[200:203], v[36:39]
	v_mfma_f32_16x16x32_bf16 v[32:35], v[156:159], v[200:203], v[32:35]
	v_mfma_f32_16x16x32_bf16 v[20:23], v[148:151], v[212:215], v[20:23]
	v_mfma_f32_16x16x32_bf16 v[16:19], v[156:159], v[212:215], v[16:19]
	v_mfma_f32_16x16x32_bf16 v[44:47], v[160:163], v[180:183], v[44:47]
	v_mfma_f32_16x16x32_bf16 v[40:43], v[172:175], v[180:183], v[40:43]
	v_mfma_f32_16x16x32_bf16 v[28:31], v[160:163], v[188:191], v[28:31]
	v_mfma_f32_16x16x32_bf16 v[24:27], v[172:175], v[188:191], v[24:27]
	v_mfma_f32_16x16x32_bf16 v[12:15], v[160:163], v[196:199], v[12:15]
	v_mfma_f32_16x16x32_bf16 v[8:11], v[172:175], v[196:199], v[8:11]
	v_mfma_f32_16x16x32_bf16 v[4:7], v[160:163], v[204:207], v[4:7]
	v_mfma_f32_16x16x32_bf16 v[0:3], v[172:175], v[204:207], v[0:3]
	v_mfma_f32_16x16x32_bf16 v[44:47], v[164:167], v[184:187], v[44:47]
	v_mfma_f32_16x16x32_bf16 v[40:43], v[176:179], v[184:187], v[40:43]
	v_mfma_f32_16x16x32_bf16 v[28:31], v[164:167], v[192:195], v[28:31]
	v_mfma_f32_16x16x32_bf16 v[24:27], v[176:179], v[192:195], v[24:27]
	v_mfma_f32_16x16x32_bf16 v[12:15], v[164:167], v[200:203], v[12:15]
	v_mfma_f32_16x16x32_bf16 v[8:11], v[176:179], v[200:203], v[8:11]
	v_mfma_f32_16x16x32_bf16 v[4:7], v[164:167], v[212:215], v[4:7]
	v_mfma_f32_16x16x32_bf16 v[0:3], v[176:179], v[212:215], v[0:3]
	s_barrier
	s_cmp_gt_u32 s55, 41
	s_cbranch_scc0 .LBB0_1046
	s_and_b64 vcc, exec, s[20:21]
	s_cbranch_vccz .LBB0_1049
	s_barrier
